# v16
# speedup vs baseline: 1.0061x; 1.0061x over previous
; #define PG8_STAGE(bufoff, gbase) PG8_STAGEV(bufoff, gbase, voff)
; #define PG8_STAGEB(bufoff, gbase) PG8_STAGEV(bufoff, gbase, voffB)
; #define PG8_LDA(dst, b, h) do { _Pragma("unroll") for (int m = 0; m < 4; ++m) _Pragma("unroll") for (int k = 0; k < 2; ++k) dst[m][k] = *(const LAS bf16x8*)(lds + PG8_SA(b, h) + aoff + m * 2048 + k * 1024); } while (0)
; #define PG8_LDB(dst, b, h) do { _Pragma("unroll") for (int n = 0; n < 2; ++n) _Pragma("unroll") for (int k = 0; k < 2; ++k) dst[n][k] = *(const LAS bf16x8*)(lds + PG8_SB(b, h) + boff + n * 2048 + k * 1024); } while (0)
; #define PG8_MMA(ai, bj, At, Bt) do { __builtin_amdgcn_s_setprio(1); _Pragma("unroll") for (int m = 0; m < 4; ++m) _Pragma("unroll") for (int n = 0; n < 2; ++n) _Pragma("unroll") for (int k = 0; k < 2; ++k) \
;         acc[ai][bj][m][n] = __builtin_amdgcn_mfma_f32_16x16x32_bf16(Bt[n][k], At[m][k], acc[ai][bj][m][n], 0, 0, 0); __builtin_amdgcn_s_setprio(0); } while (0)
; #define PG8_WAIT_V(n) asm volatile("s_waitcnt vmcnt(" #n ")" ::: "memory")
; #define PG8_WAIT_L(n) asm volatile("s_waitcnt lgkmcnt(" #n ")" ::: "memory")
; #define PG8_BAR __builtin_amdgcn_s_barrier()
; #define PG8_SCHED __builtin_amdgcn_sched_barrier(0)
; template <bool PERM, class Epi, class Sched>
; __device__ __forceinline__ void gemm_phase(LAS unsigned char* lds, const int K, const Sched& S, const Epi& E, const int wid0) {
;     ...
;             PG8_LDB(B0, 0, 0); PG8_LDB(B1, 0, 1); PG8_SCHED; PG8_LDA(At, 0, 0); PG8_STAGE(PG8_SA(1, 1), a1 + hstep);
;             PG8_WAIT_V(8); PG8_WAIT_L(0); PG8_BAR; PG8_MMA(0, 0, At, B0); PG8_MMA(0, 1, At, B1); PG8_BAR; PG8_SCHED;
;             PG8_LDA(At, 0, 1); PG8_STAGEB(PG8_SB(0, 0), b2); PG8_STAGEB(PG8_SB(0, 1), b2 + hstep); PG8_STAGE(PG8_SA(0, 0), a2);
;             PG8_WAIT_V(8); PG8_WAIT_L(0); PG8_BAR; PG8_MMA(1, 0, At, B0); PG8_MMA(1, 1, At, B1); PG8_BAR; PG8_SCHED;
.LBB0_247:
	s_add_u32 s16, s8, 0xfff80080
	s_addc_u32 s17, s9, -1
	s_add_i32 s58, 0, 0x10000
	s_cmp_eq_u32 vcc_lo, 28
	s_cselect_b32 s81, s79, s17
	s_cselect_b32 s80, s78, s16
	v_add_u32_e32 v136, s58, v168
	s_cselect_b32 s69, s18, s77
	s_cselect_b32 s68, s46, s48
	s_add_i32 s59, 0, 0x14000
	ds_read_b128 v[128:131], v136
	ds_read_b128 v[132:135], v136 offset:1024
	ds_read_b128 v[154:157], v136 offset:2048
	ds_read_b128 v[158:161], v136 offset:3072
	v_add_u32_e32 v136, s59, v168
	ds_read_b128 v[162:165], v136
	ds_read_b128 v[174:177], v136 offset:1024
	ds_read_b128 v[178:181], v136 offset:2048
	ds_read_b128 v[186:189], v136 offset:3072
	v_lshl_add_u64 v[136:137], s[8:9], 0, v[150:151]
	s_add_i32 m0, s56, 0xc000
	ds_read_b128 v[190:193], v173
	ds_read_b128 v[194:197], v173 offset:1024
	ds_read_b128 v[222:225], v173 offset:2048
	ds_read_b128 v[226:229], v173 offset:3072
	ds_read_b128 v[230:233], v173 offset:4096
	ds_read_b128 v[234:237], v173 offset:5120
	ds_read_b128 v[238:241], v173 offset:6144
	ds_read_b128 v[242:245], v173 offset:7168
	global_load_lds_dwordx4 v[136:137], off
	v_lshl_add_u64 v[136:137], s[8:9], 0, v[152:153]
	s_add_i32 m0, s56, 0xe000
	s_nop 0
	global_load_lds_dwordx4 v[136:137], off
	s_waitcnt vmcnt(8)
	s_waitcnt lgkmcnt(0)
	s_barrier
	s_waitcnt lgkmcnt(0)
	v_mfma_f32_16x16x32_bf16 v[124:127], v[128:131], v[190:193], v[124:127]
	v_mfma_f32_16x16x32_bf16 v[120:123], v[154:157], v[190:193], v[120:123]
	v_mfma_f32_16x16x32_bf16 v[108:111], v[128:131], v[222:225], v[108:111]
	v_mfma_f32_16x16x32_bf16 v[104:107], v[154:157], v[222:225], v[104:107]
	v_mfma_f32_16x16x32_bf16 v[92:95], v[128:131], v[230:233], v[92:95]
	v_mfma_f32_16x16x32_bf16 v[88:91], v[154:157], v[230:233], v[88:91]
	v_mfma_f32_16x16x32_bf16 v[76:79], v[128:131], v[238:241], v[76:79]
	v_mfma_f32_16x16x32_bf16 v[72:75], v[154:157], v[238:241], v[72:75]
	v_mfma_f32_16x16x32_bf16 v[124:127], v[132:135], v[194:197], v[124:127]
	v_mfma_f32_16x16x32_bf16 v[120:123], v[158:161], v[194:197], v[120:123]
	v_mfma_f32_16x16x32_bf16 v[108:111], v[132:135], v[226:229], v[108:111]
	v_mfma_f32_16x16x32_bf16 v[104:107], v[158:161], v[226:229], v[104:107]
	v_mfma_f32_16x16x32_bf16 v[92:95], v[132:135], v[234:237], v[92:95]
	v_mfma_f32_16x16x32_bf16 v[88:91], v[158:161], v[234:237], v[88:91]
	v_mfma_f32_16x16x32_bf16 v[76:79], v[132:135], v[242:245], v[76:79]
	v_mfma_f32_16x16x32_bf16 v[72:75], v[158:161], v[242:245], v[72:75]
	v_mfma_f32_16x16x32_bf16 v[116:119], v[162:165], v[190:193], v[116:119]
	v_mfma_f32_16x16x32_bf16 v[112:115], v[178:181], v[190:193], v[112:115]
	v_mfma_f32_16x16x32_bf16 v[100:103], v[162:165], v[222:225], v[100:103]
	v_mfma_f32_16x16x32_bf16 v[96:99], v[178:181], v[222:225], v[96:99]
	v_mfma_f32_16x16x32_bf16 v[84:87], v[162:165], v[230:233], v[84:87]
	v_mfma_f32_16x16x32_bf16 v[80:83], v[178:181], v[230:233], v[80:83]
	v_mfma_f32_16x16x32_bf16 v[68:71], v[162:165], v[238:241], v[68:71]
	v_mfma_f32_16x16x32_bf16 v[64:67], v[178:181], v[238:241], v[64:67]
	v_mfma_f32_16x16x32_bf16 v[116:119], v[174:177], v[194:197], v[116:119]
	v_mfma_f32_16x16x32_bf16 v[112:115], v[186:189], v[194:197], v[112:115]
	v_mfma_f32_16x16x32_bf16 v[100:103], v[174:177], v[226:229], v[100:103]
	v_mfma_f32_16x16x32_bf16 v[96:99], v[186:189], v[226:229], v[96:99]
	v_mfma_f32_16x16x32_bf16 v[84:87], v[174:177], v[234:237], v[84:87]
	v_mfma_f32_16x16x32_bf16 v[80:83], v[186:189], v[234:237], v[80:83]
	v_mfma_f32_16x16x32_bf16 v[68:71], v[174:177], v[242:245], v[68:71]
	v_mfma_f32_16x16x32_bf16 v[64:67], v[186:189], v[242:245], v[64:67]
	s_barrier
	s_add_i32 s16, s58, s83
	v_lshl_add_u64 v[136:137], s[68:69], 0, v[140:141]
	s_mov_b32 m0, s16
	ds_read_b128 v[190:193], v173 offset:16384
	ds_read_b128 v[194:197], v173 offset:17408
	ds_read_b128 v[222:225], v173 offset:18432
	ds_read_b128 v[226:229], v173 offset:19456
	ds_read_b128 v[230:233], v173 offset:20480
	ds_read_b128 v[234:237], v173 offset:21504
	ds_read_b128 v[238:241], v173 offset:22528
	ds_read_b128 v[242:245], v173 offset:23552
	global_load_lds_dwordx4 v[136:137], off
	s_add_i32 m0, s16, 0x2000
	s_add_u32 s16, s68, 0x80000
	v_lshl_add_u64 v[166:167], s[68:69], 0, v[144:145]
	s_addc_u32 s17, s69, 0
	s_add_i32 s58, s59, s83
	global_load_lds_dwordx4 v[166:167], off
	v_lshl_add_u64 v[182:183], s[16:17], 0, v[140:141]
	s_mov_b32 m0, s58
	v_lshl_add_u64 v[246:247], s[80:81], 0, v[142:143]
	global_load_lds_dwordx4 v[182:183], off
	v_lshl_add_u64 v[182:183], s[16:17], 0, v[144:145]
	s_add_i32 m0, s58, 0x2000
	s_nop 0
	global_load_lds_dwordx4 v[182:183], off
	v_lshl_add_u64 v[182:183], s[80:81], 0, v[138:139]
	s_mov_b32 m0, s56
	s_nop 0
	global_load_lds_dwordx4 v[182:183], off
	s_mov_b32 m0, s54
	s_nop 0
	global_load_lds_dwordx4 v[246:247], off
	s_waitcnt vmcnt(8)
	s_waitcnt lgkmcnt(0)
	s_barrier
; #define PG8_STAGE(bufoff, gbase) PG8_STAGEV(bufoff, gbase, voff)
; #define PG8_STAGEB(bufoff, gbase) PG8_STAGEV(bufoff, gbase, voffB)
; #define PG8_LDA(dst, b, h) do { _Pragma("unroll") for (int m = 0; m < 4; ++m) _Pragma("unroll") for (int k = 0; k < 2; ++k) dst[m][k] = *(const LAS bf16x8*)(lds + PG8_SA(b, h) + aoff + m * 2048 + k * 1024); } while (0)
; #define PG8_LDB(dst, b, h) do { _Pragma("unroll") for (int n = 0; n < 2; ++n) _Pragma("unroll") for (int k = 0; k < 2; ++k) dst[n][k] = *(const LAS bf16x8*)(lds + PG8_SB(b, h) + boff + n * 2048 + k * 1024); } while (0)
; #define PG8_MMA(ai, bj, At, Bt) do { __builtin_amdgcn_s_setprio(1); _Pragma("unroll") for (int m = 0; m < 4; ++m) _Pragma("unroll") for (int n = 0; n < 2; ++n) _Pragma("unroll") for (int k = 0; k < 2; ++k) \
;         acc[ai][bj][m][n] = __builtin_amdgcn_mfma_f32_16x16x32_bf16(Bt[n][k], At[m][k], acc[ai][bj][m][n], 0, 0, 0); __builtin_amdgcn_s_setprio(0); } while (0)
; #define PG8_WAIT_V(n) asm volatile("s_waitcnt vmcnt(" #n ")" ::: "memory")
; #define PG8_WAIT_L(n) asm volatile("s_waitcnt lgkmcnt(" #n ")" ::: "memory")
; #define PG8_BAR __builtin_amdgcn_s_barrier()
; #define PG8_SCHED __builtin_amdgcn_sched_barrier(0)
; template <bool PERM, class Epi, class Sched>
; __device__ __forceinline__ void gemm_phase(LAS unsigned char* lds, const int K, const Sched& S, const Epi& E, const int wid0) {
;     ...
;             PG8_LDA(At, 0, 1); PG8_STAGEB(PG8_SB(0, 0), b2); PG8_STAGEB(PG8_SB(0, 1), b2 + hstep); PG8_STAGE(PG8_SA(0, 0), a2);
;             PG8_WAIT_V(8); PG8_WAIT_L(0); PG8_BAR; PG8_MMA(1, 0, At, B0); PG8_MMA(1, 1, At, B1); PG8_BAR; PG8_SCHED;
;             PG8_LDB(B0, 1, 0); PG8_LDB(B1, 1, 1); PG8_SCHED; PG8_LDA(At, 1, 0); PG8_STAGE(PG8_SA(0, 1), a2 + hstep);
;             PG8_WAIT_V(8); PG8_WAIT_L(0); PG8_BAR; PG8_MMA(0, 0, At, B0); PG8_MMA(0, 1, At, B1); PG8_BAR; PG8_SCHED;
	s_waitcnt lgkmcnt(0)
	v_mfma_f32_16x16x32_bf16 v[60:63], v[128:131], v[190:193], v[60:63]
	v_mfma_f32_16x16x32_bf16 v[56:59], v[154:157], v[190:193], v[56:59]
	v_mfma_f32_16x16x32_bf16 v[44:47], v[128:131], v[222:225], v[44:47]
	v_mfma_f32_16x16x32_bf16 v[40:43], v[154:157], v[222:225], v[40:43]
	v_mfma_f32_16x16x32_bf16 v[28:31], v[128:131], v[230:233], v[28:31]
	v_mfma_f32_16x16x32_bf16 v[24:27], v[154:157], v[230:233], v[24:27]
	v_mfma_f32_16x16x32_bf16 v[12:15], v[128:131], v[238:241], v[12:15]
	v_mfma_f32_16x16x32_bf16 v[8:11], v[154:157], v[238:241], v[8:11]
	v_mfma_f32_16x16x32_bf16 v[60:63], v[132:135], v[194:197], v[60:63]
	v_mfma_f32_16x16x32_bf16 v[56:59], v[158:161], v[194:197], v[56:59]
	v_mfma_f32_16x16x32_bf16 v[44:47], v[132:135], v[226:229], v[44:47]
	v_mfma_f32_16x16x32_bf16 v[40:43], v[158:161], v[226:229], v[40:43]
	v_mfma_f32_16x16x32_bf16 v[28:31], v[132:135], v[234:237], v[28:31]
	v_mfma_f32_16x16x32_bf16 v[24:27], v[158:161], v[234:237], v[24:27]
	v_mfma_f32_16x16x32_bf16 v[12:15], v[132:135], v[242:245], v[12:15]
	v_mfma_f32_16x16x32_bf16 v[8:11], v[158:161], v[242:245], v[8:11]
	v_mfma_f32_16x16x32_bf16 v[52:55], v[162:165], v[190:193], v[52:55]
	v_mfma_f32_16x16x32_bf16 v[48:51], v[178:181], v[190:193], v[48:51]
	v_mfma_f32_16x16x32_bf16 v[36:39], v[162:165], v[222:225], v[36:39]
	v_mfma_f32_16x16x32_bf16 v[32:35], v[178:181], v[222:225], v[32:35]
	v_mfma_f32_16x16x32_bf16 v[20:23], v[162:165], v[230:233], v[20:23]
	v_mfma_f32_16x16x32_bf16 v[16:19], v[178:181], v[230:233], v[16:19]
	v_mfma_f32_16x16x32_bf16 v[4:7], v[162:165], v[238:241], v[4:7]
	v_mfma_f32_16x16x32_bf16 v[0:3], v[178:181], v[238:241], v[0:3]
	v_mfma_f32_16x16x32_bf16 v[52:55], v[174:177], v[194:197], v[52:55]
	v_mfma_f32_16x16x32_bf16 v[48:51], v[186:189], v[194:197], v[48:51]
	v_mfma_f32_16x16x32_bf16 v[36:39], v[174:177], v[226:229], v[36:39]
	v_mfma_f32_16x16x32_bf16 v[32:35], v[186:189], v[226:229], v[32:35]
	v_mfma_f32_16x16x32_bf16 v[20:23], v[174:177], v[234:237], v[20:23]
	v_mfma_f32_16x16x32_bf16 v[16:19], v[186:189], v[234:237], v[16:19]
	v_mfma_f32_16x16x32_bf16 v[4:7], v[174:177], v[242:245], v[4:7]
	v_mfma_f32_16x16x32_bf16 v[0:3], v[186:189], v[242:245], v[0:3]
	s_barrier
	s_add_i32 s58, 0, 0x18000
	s_add_i32 s59, 0, 0x1c000
	v_add_u32_e32 v158, s58, v168
	v_add_u32_e32 v184, s59, v168
	ds_read_b128 v[128:131], v158
	ds_read_b128 v[132:135], v158 offset:1024
	ds_read_b128 v[154:157], v158 offset:2048
	ds_read_b128 v[158:161], v158 offset:3072
	ds_read_b128 v[162:165], v184
	ds_read_b128 v[174:177], v184 offset:1024
	ds_read_b128 v[178:181], v184 offset:2048
	ds_read_b128 v[186:189], v184 offset:3072
	s_add_u32 s16, s80, 0x80000
	s_addc_u32 s17, s81, 0
	s_mov_b32 m0, s55
	v_lshl_add_u64 v[248:249], s[16:17], 0, v[138:139]
	ds_read_b128 v[190:193], v173 offset:32768
	ds_read_b128 v[194:197], v173 offset:33792
	ds_read_b128 v[222:225], v173 offset:34816
	ds_read_b128 v[226:229], v173 offset:35840
	ds_read_b128 v[230:233], v173 offset:36864
	ds_read_b128 v[234:237], v173 offset:37888
	ds_read_b128 v[238:241], v173 offset:38912
	ds_read_b128 v[242:245], v173 offset:39936
	global_load_lds_dwordx4 v[248:249], off
	v_lshl_add_u64 v[248:249], s[16:17], 0, v[142:143]
	s_mov_b32 m0, s66
	s_nop 0
	global_load_lds_dwordx4 v[248:249], off
	s_waitcnt vmcnt(8)
	s_waitcnt lgkmcnt(0)
	s_barrier
	s_waitcnt lgkmcnt(0)
	v_mfma_f32_16x16x32_bf16 v[124:127], v[128:131], v[190:193], v[124:127]
	v_mfma_f32_16x16x32_bf16 v[120:123], v[154:157], v[190:193], v[120:123]
	v_mfma_f32_16x16x32_bf16 v[108:111], v[128:131], v[222:225], v[108:111]
	v_mfma_f32_16x16x32_bf16 v[104:107], v[154:157], v[222:225], v[104:107]
	v_mfma_f32_16x16x32_bf16 v[92:95], v[128:131], v[230:233], v[92:95]
	v_mfma_f32_16x16x32_bf16 v[88:91], v[154:157], v[230:233], v[88:91]
	v_mfma_f32_16x16x32_bf16 v[76:79], v[128:131], v[238:241], v[76:79]
	v_mfma_f32_16x16x32_bf16 v[72:75], v[154:157], v[238:241], v[72:75]
	v_mfma_f32_16x16x32_bf16 v[124:127], v[132:135], v[194:197], v[124:127]
	v_mfma_f32_16x16x32_bf16 v[120:123], v[158:161], v[194:197], v[120:123]
	v_mfma_f32_16x16x32_bf16 v[108:111], v[132:135], v[226:229], v[108:111]
	v_mfma_f32_16x16x32_bf16 v[104:107], v[158:161], v[226:229], v[104:107]
	v_mfma_f32_16x16x32_bf16 v[92:95], v[132:135], v[234:237], v[92:95]
	v_mfma_f32_16x16x32_bf16 v[88:91], v[158:161], v[234:237], v[88:91]
	v_mfma_f32_16x16x32_bf16 v[76:79], v[132:135], v[242:245], v[76:79]
	v_mfma_f32_16x16x32_bf16 v[72:75], v[158:161], v[242:245], v[72:75]
	v_mfma_f32_16x16x32_bf16 v[116:119], v[162:165], v[190:193], v[116:119]
	v_mfma_f32_16x16x32_bf16 v[112:115], v[178:181], v[190:193], v[112:115]
	v_mfma_f32_16x16x32_bf16 v[100:103], v[162:165], v[222:225], v[100:103]
	v_mfma_f32_16x16x32_bf16 v[96:99], v[178:181], v[222:225], v[96:99]
	v_mfma_f32_16x16x32_bf16 v[84:87], v[162:165], v[230:233], v[84:87]
	v_mfma_f32_16x16x32_bf16 v[80:83], v[178:181], v[230:233], v[80:83]
	v_mfma_f32_16x16x32_bf16 v[68:71], v[162:165], v[238:241], v[68:71]
	v_mfma_f32_16x16x32_bf16 v[64:67], v[178:181], v[238:241], v[64:67]
	v_mfma_f32_16x16x32_bf16 v[116:119], v[174:177], v[194:197], v[116:119]
	v_mfma_f32_16x16x32_bf16 v[112:115], v[186:189], v[194:197], v[112:115]
	v_mfma_f32_16x16x32_bf16 v[100:103], v[174:177], v[226:229], v[100:103]
	v_mfma_f32_16x16x32_bf16 v[96:99], v[186:189], v[226:229], v[96:99]
	v_mfma_f32_16x16x32_bf16 v[84:87], v[174:177], v[234:237], v[84:87]
	v_mfma_f32_16x16x32_bf16 v[80:83], v[186:189], v[234:237], v[80:83]
	v_mfma_f32_16x16x32_bf16 v[68:71], v[174:177], v[242:245], v[68:71]
	v_mfma_f32_16x16x32_bf16 v[64:67], v[186:189], v[242:245], v[64:67]
	s_barrier
; #define PG8_STAGE(bufoff, gbase) PG8_STAGEV(bufoff, gbase, voff)
; #define PG8_STAGEB(bufoff, gbase) PG8_STAGEV(bufoff, gbase, voffB)
; #define PG8_LDA(dst, b, h) do { _Pragma("unroll") for (int m = 0; m < 4; ++m) _Pragma("unroll") for (int k = 0; k < 2; ++k) dst[m][k] = *(const LAS bf16x8*)(lds + PG8_SA(b, h) + aoff + m * 2048 + k * 1024); } while (0)
; #define PG8_MMA(ai, bj, At, Bt) do { __builtin_amdgcn_s_setprio(1); _Pragma("unroll") for (int m = 0; m < 4; ++m) _Pragma("unroll") for (int n = 0; n < 2; ++n) _Pragma("unroll") for (int k = 0; k < 2; ++k) \
;         acc[ai][bj][m][n] = __builtin_amdgcn_mfma_f32_16x16x32_bf16(Bt[n][k], At[m][k], acc[ai][bj][m][n], 0, 0, 0); __builtin_amdgcn_s_setprio(0); } while (0)
; #define PG8_WAIT_V(n) asm volatile("s_waitcnt vmcnt(" #n ")" ::: "memory")
; #define PG8_WAIT_L(n) asm volatile("s_waitcnt lgkmcnt(" #n ")" ::: "memory")
; #define PG8_BAR __builtin_amdgcn_s_barrier()
; #define PG8_SCHED __builtin_amdgcn_sched_barrier(0)
; template <bool PERM, class Epi, class Sched>
; __device__ __forceinline__ void gemm_phase(LAS unsigned char* lds, const int K, const Sched& S, const Epi& E, const int wid0) {
;     ...
;         for (int t = 0; t < nt; t += 2) {
;     ...
;             PG8_LDA(At, 1, 1); PG8_STAGEB(PG8_SB(1, 0), b3); PG8_STAGEB(PG8_SB(1, 1), b3 + hstep); PG8_STAGE(PG8_SA(1, 0), a3);
;             PG8_WAIT_V(8); PG8_WAIT_L(0); PG8_BAR; PG8_MMA(1, 0, At, B0); PG8_MMA(1, 1, At, B1); PG8_BAR; PG8_SCHED;
	s_add_i32 s16, s58, s83
	v_lshl_add_u64 v[136:137], v[136:137], 0, s[42:43]
	s_mov_b32 m0, s16
	ds_read_b128 v[190:193], v173 offset:49152
	ds_read_b128 v[194:197], v173 offset:50176
	ds_read_b128 v[222:225], v173 offset:51200
	ds_read_b128 v[226:229], v173 offset:52224
	ds_read_b128 v[230:233], v173 offset:53248
	ds_read_b128 v[234:237], v173 offset:54272
	ds_read_b128 v[238:241], v173 offset:55296
	ds_read_b128 v[242:245], v173 offset:56320
	global_load_lds_dwordx4 v[136:137], off
	s_add_i32 m0, s16, 0x2000
	s_add_u32 s16, s68, 0x80080
	v_lshl_add_u64 v[136:137], v[166:167], 0, s[42:43]
	s_addc_u32 s17, s69, 0
	s_add_i32 s58, s59, s83
	global_load_lds_dwordx4 v[136:137], off
	v_lshl_add_u64 v[136:137], s[16:17], 0, v[140:141]
	s_mov_b32 m0, s58
	s_nop 0
	global_load_lds_dwordx4 v[136:137], off
	v_lshl_add_u64 v[136:137], s[16:17], 0, v[144:145]
	s_add_i32 m0, s58, 0x2000
	s_nop 0
	global_load_lds_dwordx4 v[136:137], off
	v_lshl_add_u64 v[136:137], v[182:183], 0, s[42:43]
	s_mov_b32 m0, s53
	s_nop 0
	global_load_lds_dwordx4 v[136:137], off
	v_lshl_add_u64 v[136:137], v[246:247], 0, s[42:43]
	s_mov_b32 m0, s92
	s_nop 0
	global_load_lds_dwordx4 v[136:137], off
	s_waitcnt vmcnt(8)
	s_waitcnt lgkmcnt(0)
	s_barrier
	s_waitcnt lgkmcnt(0)
	v_mfma_f32_16x16x32_bf16 v[60:63], v[128:131], v[190:193], v[60:63]
	v_mfma_f32_16x16x32_bf16 v[56:59], v[154:157], v[190:193], v[56:59]
	v_mfma_f32_16x16x32_bf16 v[44:47], v[128:131], v[222:225], v[44:47]
	v_mfma_f32_16x16x32_bf16 v[40:43], v[154:157], v[222:225], v[40:43]
	v_mfma_f32_16x16x32_bf16 v[28:31], v[128:131], v[230:233], v[28:31]
	v_mfma_f32_16x16x32_bf16 v[24:27], v[154:157], v[230:233], v[24:27]
	v_mfma_f32_16x16x32_bf16 v[12:15], v[128:131], v[238:241], v[12:15]
	v_mfma_f32_16x16x32_bf16 v[8:11], v[154:157], v[238:241], v[8:11]
	v_mfma_f32_16x16x32_bf16 v[60:63], v[132:135], v[194:197], v[60:63]
	v_mfma_f32_16x16x32_bf16 v[56:59], v[158:161], v[194:197], v[56:59]
	v_mfma_f32_16x16x32_bf16 v[44:47], v[132:135], v[226:229], v[44:47]
	v_mfma_f32_16x16x32_bf16 v[40:43], v[158:161], v[226:229], v[40:43]
	v_mfma_f32_16x16x32_bf16 v[28:31], v[132:135], v[234:237], v[28:31]
	v_mfma_f32_16x16x32_bf16 v[24:27], v[158:161], v[234:237], v[24:27]
	v_mfma_f32_16x16x32_bf16 v[12:15], v[132:135], v[242:245], v[12:15]
	v_mfma_f32_16x16x32_bf16 v[8:11], v[158:161], v[242:245], v[8:11]
	v_mfma_f32_16x16x32_bf16 v[52:55], v[162:165], v[190:193], v[52:55]
	v_mfma_f32_16x16x32_bf16 v[48:51], v[178:181], v[190:193], v[48:51]
	v_mfma_f32_16x16x32_bf16 v[36:39], v[162:165], v[222:225], v[36:39]
	v_mfma_f32_16x16x32_bf16 v[32:35], v[178:181], v[222:225], v[32:35]
	v_mfma_f32_16x16x32_bf16 v[20:23], v[162:165], v[230:233], v[20:23]
	v_mfma_f32_16x16x32_bf16 v[16:19], v[178:181], v[230:233], v[16:19]
	v_mfma_f32_16x16x32_bf16 v[4:7], v[162:165], v[238:241], v[4:7]
	v_mfma_f32_16x16x32_bf16 v[0:3], v[178:181], v[238:241], v[0:3]
	v_mfma_f32_16x16x32_bf16 v[52:55], v[174:177], v[194:197], v[52:55]
	v_mfma_f32_16x16x32_bf16 v[48:51], v[186:189], v[194:197], v[48:51]
	v_mfma_f32_16x16x32_bf16 v[36:39], v[174:177], v[226:229], v[36:39]
	v_mfma_f32_16x16x32_bf16 v[32:35], v[186:189], v[226:229], v[32:35]
	v_mfma_f32_16x16x32_bf16 v[20:23], v[174:177], v[234:237], v[20:23]
	v_mfma_f32_16x16x32_bf16 v[16:19], v[186:189], v[234:237], v[16:19]
	v_mfma_f32_16x16x32_bf16 v[4:7], v[174:177], v[242:245], v[4:7]
	v_mfma_f32_16x16x32_bf16 v[0:3], v[186:189], v[242:245], v[0:3]
	s_barrier
	s_add_i32 vcc_lo, vcc_lo, 2
	s_add_u32 s8, s8, 0x100
	s_addc_u32 s9, s9, 0
	s_add_u32 s48, s48, 0x100
	s_addc_u32 s77, s77, 0
	s_cmp_gt_u32 vcc_lo, 29
	s_cbranch_scc0 .LBB0_247
	s_and_b64 vcc, exec, s[74:75]
	s_cbranch_vccnz .LBB0_252
	s_cmp_gt_i32 s0, 7
	s_mov_b64 s[8:9], -1
	s_cbranch_scc1 .LBB0_253

; #define PG8_STAGE(bufoff, gbase) PG8_STAGEV(bufoff, gbase, voff)
; #define PG8_STAGEB(bufoff, gbase) PG8_STAGEV(bufoff, gbase, voffB)
; #define PG8_LDA(dst, b, h) do { _Pragma("unroll") for (int m = 0; m < 4; ++m) _Pragma("unroll") for (int k = 0; k < 2; ++k) dst[m][k] = *(const LAS bf16x8*)(lds + PG8_SA(b, h) + aoff + m * 2048 + k * 1024); } while (0)
; #define PG8_LDB(dst, b, h) do { _Pragma("unroll") for (int n = 0; n < 2; ++n) _Pragma("unroll") for (int k = 0; k < 2; ++k) dst[n][k] = *(const LAS bf16x8*)(lds + PG8_SB(b, h) + boff + n * 2048 + k * 1024); } while (0)
; #define PG8_MMA(ai, bj, At, Bt) do { __builtin_amdgcn_s_setprio(1); _Pragma("unroll") for (int m = 0; m < 4; ++m) _Pragma("unroll") for (int n = 0; n < 2; ++n) _Pragma("unroll") for (int k = 0; k < 2; ++k) \
;         acc[ai][bj][m][n] = __builtin_amdgcn_mfma_f32_16x16x32_bf16(Bt[n][k], At[m][k], acc[ai][bj][m][n], 0, 0, 0); __builtin_amdgcn_s_setprio(0); } while (0)
; #define PG8_WAIT_V(n) asm volatile("s_waitcnt vmcnt(" #n ")" ::: "memory")
; #define PG8_WAIT_L(n) asm volatile("s_waitcnt lgkmcnt(" #n ")" ::: "memory")
; #define PG8_BAR __builtin_amdgcn_s_barrier()
; #define PG8_SCHED __builtin_amdgcn_sched_barrier(0)
; template <bool PERM, class Epi, class Sched>
; __device__ __forceinline__ void gemm_phase(LAS unsigned char* lds, const int K, const Sched& S, const Epi& E, const int wid0) {
;     ...
;             PG8_LDB(B0, 0, 0); PG8_LDB(B1, 0, 1); PG8_SCHED; PG8_LDA(At, 0, 0); PG8_STAGE(PG8_SA(1, 1), a1 + hstep);
;             PG8_WAIT_V(8); PG8_WAIT_L(0); PG8_BAR; PG8_MMA(0, 0, At, B0); PG8_MMA(0, 1, At, B1); PG8_BAR; PG8_SCHED;
;             PG8_LDA(At, 0, 1); PG8_STAGEB(PG8_SB(0, 0), b2); PG8_STAGEB(PG8_SB(0, 1), b2 + hstep); PG8_STAGE(PG8_SA(0, 0), a2);
;             PG8_WAIT_V(8); PG8_WAIT_L(0); PG8_BAR; PG8_MMA(1, 0, At, B0); PG8_MMA(1, 1, At, B1); PG8_BAR; PG8_SCHED;
.LBB0_635:
	s_add_u32 s6, s82, 0xfffc0080
	s_addc_u32 s7, s83, -1
	s_add_i32 s16, 0, 0x10000
	s_cmp_eq_u32 s92, 12
	s_cselect_b32 s23, s46, s7
	s_cselect_b32 s22, s48, s6
	v_add_u32_e32 v142, s16, v145
	s_cselect_b32 s7, s71, s81
	s_cselect_b32 s6, s73, s79
	s_add_i32 s58, 0, 0x14000
	ds_read_b128 v[138:141], v142
	ds_read_b128 v[148:151], v142 offset:1024
	ds_read_b128 v[152:155], v142 offset:2048
	ds_read_b128 v[156:159], v142 offset:3072
	v_add_u32_e32 v142, s58, v145
	ds_read_b128 v[160:163], v142
	ds_read_b128 v[164:167], v142 offset:1024
	ds_read_b128 v[168:171], v142 offset:2048
	ds_read_b128 v[172:175], v142 offset:3072
	v_lshl_add_u64 v[142:143], s[82:83], 0, v[134:135]
	s_add_i32 m0, s50, 0xc000
	ds_read_b128 v[176:179], v147
	ds_read_b128 v[180:183], v147 offset:1024
	ds_read_b128 v[186:189], v147 offset:2048
	ds_read_b128 v[190:193], v147 offset:3072
	ds_read_b128 v[194:197], v147 offset:4096
	ds_read_b128 v[222:225], v147 offset:5120
	ds_read_b128 v[226:229], v147 offset:6144
	ds_read_b128 v[230:233], v147 offset:7168
	global_load_lds_dwordx4 v[142:143], off
	v_lshl_add_u64 v[142:143], s[82:83], 0, v[136:137]
	s_add_i32 m0, s50, 0xe000
	s_nop 0
	global_load_lds_dwordx4 v[142:143], off
	s_waitcnt vmcnt(8)
	s_waitcnt lgkmcnt(0)
	s_barrier
	s_waitcnt lgkmcnt(0)
	v_mfma_f32_16x16x32_bf16 v[124:127], v[138:141], v[176:179], v[124:127]
	v_mfma_f32_16x16x32_bf16 v[120:123], v[152:155], v[176:179], v[120:123]
	v_mfma_f32_16x16x32_bf16 v[108:111], v[138:141], v[186:189], v[108:111]
	v_mfma_f32_16x16x32_bf16 v[104:107], v[152:155], v[186:189], v[104:107]
	v_mfma_f32_16x16x32_bf16 v[92:95], v[138:141], v[194:197], v[92:95]
	v_mfma_f32_16x16x32_bf16 v[88:91], v[152:155], v[194:197], v[88:91]
	v_mfma_f32_16x16x32_bf16 v[76:79], v[138:141], v[226:229], v[76:79]
	v_mfma_f32_16x16x32_bf16 v[72:75], v[152:155], v[226:229], v[72:75]
	v_mfma_f32_16x16x32_bf16 v[124:127], v[148:151], v[180:183], v[124:127]
	v_mfma_f32_16x16x32_bf16 v[120:123], v[156:159], v[180:183], v[120:123]
	v_mfma_f32_16x16x32_bf16 v[108:111], v[148:151], v[190:193], v[108:111]
	v_mfma_f32_16x16x32_bf16 v[104:107], v[156:159], v[190:193], v[104:107]
	v_mfma_f32_16x16x32_bf16 v[92:95], v[148:151], v[222:225], v[92:95]
	v_mfma_f32_16x16x32_bf16 v[88:91], v[156:159], v[222:225], v[88:91]
	v_mfma_f32_16x16x32_bf16 v[76:79], v[148:151], v[230:233], v[76:79]
	v_mfma_f32_16x16x32_bf16 v[72:75], v[156:159], v[230:233], v[72:75]
	v_mfma_f32_16x16x32_bf16 v[116:119], v[160:163], v[176:179], v[116:119]
	v_mfma_f32_16x16x32_bf16 v[112:115], v[168:171], v[176:179], v[112:115]
	v_mfma_f32_16x16x32_bf16 v[100:103], v[160:163], v[186:189], v[100:103]
	v_mfma_f32_16x16x32_bf16 v[96:99], v[168:171], v[186:189], v[96:99]
	v_mfma_f32_16x16x32_bf16 v[84:87], v[160:163], v[194:197], v[84:87]
	v_mfma_f32_16x16x32_bf16 v[80:83], v[168:171], v[194:197], v[80:83]
	v_mfma_f32_16x16x32_bf16 v[68:71], v[160:163], v[226:229], v[68:71]
	v_mfma_f32_16x16x32_bf16 v[64:67], v[168:171], v[226:229], v[64:67]
	v_mfma_f32_16x16x32_bf16 v[116:119], v[164:167], v[180:183], v[116:119]
	v_mfma_f32_16x16x32_bf16 v[112:115], v[172:175], v[180:183], v[112:115]
	v_mfma_f32_16x16x32_bf16 v[100:103], v[164:167], v[190:193], v[100:103]
	v_mfma_f32_16x16x32_bf16 v[96:99], v[172:175], v[190:193], v[96:99]
	v_mfma_f32_16x16x32_bf16 v[84:87], v[164:167], v[222:225], v[84:87]
	v_mfma_f32_16x16x32_bf16 v[80:83], v[172:175], v[222:225], v[80:83]
	v_mfma_f32_16x16x32_bf16 v[68:71], v[164:167], v[230:233], v[68:71]
	v_mfma_f32_16x16x32_bf16 v[64:67], v[172:175], v[230:233], v[64:67]
	s_barrier
	s_add_i32 s16, s16, s0
	v_lshl_add_u64 v[142:143], s[6:7], 0, v[184:185]
	s_mov_b32 m0, s16
	ds_read_b128 v[176:179], v147 offset:16384
	ds_read_b128 v[180:183], v147 offset:17408
	ds_read_b128 v[186:189], v147 offset:18432
	ds_read_b128 v[190:193], v147 offset:19456
	ds_read_b128 v[194:197], v147 offset:20480
	ds_read_b128 v[222:225], v147 offset:21504
	ds_read_b128 v[226:229], v147 offset:22528
	ds_read_b128 v[230:233], v147 offset:23552
	global_load_lds_dwordx4 v[142:143], off
	s_add_i32 m0, s16, 0x2000
	s_add_u32 s16, s6, 0x40000
	v_lshl_add_u64 v[234:235], s[6:7], 0, v[128:129]
	s_addc_u32 s17, s7, 0
	s_add_i32 s58, s58, s0
	global_load_lds_dwordx4 v[234:235], off
	v_lshl_add_u64 v[236:237], s[16:17], 0, v[184:185]
	s_mov_b32 m0, s58
	v_lshl_add_u64 v[238:239], s[22:23], 0, v[130:131]
	global_load_lds_dwordx4 v[236:237], off
	v_lshl_add_u64 v[236:237], s[16:17], 0, v[128:129]
	s_add_i32 m0, s58, 0x2000
	s_nop 0
	global_load_lds_dwordx4 v[236:237], off
	v_lshl_add_u64 v[236:237], s[22:23], 0, v[132:133]
	s_mov_b32 m0, s50
	s_nop 0
	global_load_lds_dwordx4 v[236:237], off
	s_mov_b32 m0, s52
	s_nop 0
	global_load_lds_dwordx4 v[238:239], off
	s_waitcnt vmcnt(8)
	s_waitcnt lgkmcnt(0)
	s_barrier
; #define PG8_STAGE(bufoff, gbase) PG8_STAGEV(bufoff, gbase, voff)
; #define PG8_LDA(dst, b, h) do { _Pragma("unroll") for (int m = 0; m < 4; ++m) _Pragma("unroll") for (int k = 0; k < 2; ++k) dst[m][k] = *(const LAS bf16x8*)(lds + PG8_SA(b, h) + aoff + m * 2048 + k * 1024); } while (0)
; #define PG8_LDB(dst, b, h) do { _Pragma("unroll") for (int n = 0; n < 2; ++n) _Pragma("unroll") for (int k = 0; k < 2; ++k) dst[n][k] = *(const LAS bf16x8*)(lds + PG8_SB(b, h) + boff + n * 2048 + k * 1024); } while (0)
; #define PG8_MMA(ai, bj, At, Bt) do { __builtin_amdgcn_s_setprio(1); _Pragma("unroll") for (int m = 0; m < 4; ++m) _Pragma("unroll") for (int n = 0; n < 2; ++n) _Pragma("unroll") for (int k = 0; k < 2; ++k) \
;         acc[ai][bj][m][n] = __builtin_amdgcn_mfma_f32_16x16x32_bf16(Bt[n][k], At[m][k], acc[ai][bj][m][n], 0, 0, 0); __builtin_amdgcn_s_setprio(0); } while (0)
; #define PG8_WAIT_V(n) asm volatile("s_waitcnt vmcnt(" #n ")" ::: "memory")
; #define PG8_WAIT_L(n) asm volatile("s_waitcnt lgkmcnt(" #n ")" ::: "memory")
; #define PG8_BAR __builtin_amdgcn_s_barrier()
; #define PG8_SCHED __builtin_amdgcn_sched_barrier(0)
; template <bool PERM, class Epi, class Sched>
; __device__ __forceinline__ void gemm_phase(LAS unsigned char* lds, const int K, const Sched& S, const Epi& E, const int wid0) {
;     ...
;             PG8_WAIT_V(8); PG8_WAIT_L(0); PG8_BAR; PG8_MMA(1, 0, At, B0); PG8_MMA(1, 1, At, B1); PG8_BAR; PG8_SCHED;
;             PG8_LDB(B0, 1, 0); PG8_LDB(B1, 1, 1); PG8_SCHED; PG8_LDA(At, 1, 0); PG8_STAGE(PG8_SA(0, 1), a2 + hstep);
;             PG8_WAIT_V(8); PG8_WAIT_L(0); PG8_BAR; PG8_MMA(0, 0, At, B0); PG8_MMA(0, 1, At, B1); PG8_BAR; PG8_SCHED;
	s_waitcnt lgkmcnt(0)
	v_mfma_f32_16x16x32_bf16 v[60:63], v[138:141], v[176:179], v[60:63]
	v_mfma_f32_16x16x32_bf16 v[56:59], v[152:155], v[176:179], v[56:59]
	v_mfma_f32_16x16x32_bf16 v[44:47], v[138:141], v[186:189], v[44:47]
	v_mfma_f32_16x16x32_bf16 v[40:43], v[152:155], v[186:189], v[40:43]
	v_mfma_f32_16x16x32_bf16 v[28:31], v[138:141], v[194:197], v[28:31]
	v_mfma_f32_16x16x32_bf16 v[24:27], v[152:155], v[194:197], v[24:27]
	v_mfma_f32_16x16x32_bf16 v[12:15], v[138:141], v[226:229], v[12:15]
	v_mfma_f32_16x16x32_bf16 v[8:11], v[152:155], v[226:229], v[8:11]
	v_mfma_f32_16x16x32_bf16 v[60:63], v[148:151], v[180:183], v[60:63]
	v_mfma_f32_16x16x32_bf16 v[56:59], v[156:159], v[180:183], v[56:59]
	v_mfma_f32_16x16x32_bf16 v[44:47], v[148:151], v[190:193], v[44:47]
	v_mfma_f32_16x16x32_bf16 v[40:43], v[156:159], v[190:193], v[40:43]
	v_mfma_f32_16x16x32_bf16 v[28:31], v[148:151], v[222:225], v[28:31]
	v_mfma_f32_16x16x32_bf16 v[24:27], v[156:159], v[222:225], v[24:27]
	v_mfma_f32_16x16x32_bf16 v[12:15], v[148:151], v[230:233], v[12:15]
	v_mfma_f32_16x16x32_bf16 v[8:11], v[156:159], v[230:233], v[8:11]
	v_mfma_f32_16x16x32_bf16 v[52:55], v[160:163], v[176:179], v[52:55]
	v_mfma_f32_16x16x32_bf16 v[48:51], v[168:171], v[176:179], v[48:51]
	v_mfma_f32_16x16x32_bf16 v[36:39], v[160:163], v[186:189], v[36:39]
	v_mfma_f32_16x16x32_bf16 v[32:35], v[168:171], v[186:189], v[32:35]
	v_mfma_f32_16x16x32_bf16 v[20:23], v[160:163], v[194:197], v[20:23]
	v_mfma_f32_16x16x32_bf16 v[16:19], v[168:171], v[194:197], v[16:19]
	v_mfma_f32_16x16x32_bf16 v[4:7], v[160:163], v[226:229], v[4:7]
	v_mfma_f32_16x16x32_bf16 v[0:3], v[168:171], v[226:229], v[0:3]
	v_mfma_f32_16x16x32_bf16 v[52:55], v[164:167], v[180:183], v[52:55]
	v_mfma_f32_16x16x32_bf16 v[48:51], v[172:175], v[180:183], v[48:51]
	v_mfma_f32_16x16x32_bf16 v[36:39], v[164:167], v[190:193], v[36:39]
	v_mfma_f32_16x16x32_bf16 v[32:35], v[172:175], v[190:193], v[32:35]
	v_mfma_f32_16x16x32_bf16 v[20:23], v[164:167], v[222:225], v[20:23]
	v_mfma_f32_16x16x32_bf16 v[16:19], v[172:175], v[222:225], v[16:19]
	v_mfma_f32_16x16x32_bf16 v[4:7], v[164:167], v[230:233], v[4:7]
	v_mfma_f32_16x16x32_bf16 v[0:3], v[172:175], v[230:233], v[0:3]
	s_barrier
	s_add_i32 s58, 0, 0x18000
	s_add_i32 s59, 0, 0x1c000
	v_add_u32_e32 v156, s58, v145
	v_add_u32_e32 v172, s59, v145
	ds_read_b128 v[138:141], v156
	ds_read_b128 v[148:151], v156 offset:1024
	ds_read_b128 v[152:155], v156 offset:2048
	ds_read_b128 v[156:159], v156 offset:3072
	ds_read_b128 v[160:163], v172
	ds_read_b128 v[164:167], v172 offset:1024
	ds_read_b128 v[168:171], v172 offset:2048
	ds_read_b128 v[172:175], v172 offset:3072
	s_add_u32 s16, s22, 0x40000
	s_addc_u32 s17, s23, 0
	s_mov_b32 m0, s53
	v_lshl_add_u64 v[240:241], s[16:17], 0, v[132:133]
	ds_read_b128 v[176:179], v147 offset:32768
	ds_read_b128 v[180:183], v147 offset:33792
	ds_read_b128 v[186:189], v147 offset:34816
	ds_read_b128 v[190:193], v147 offset:35840
	ds_read_b128 v[194:197], v147 offset:36864
	ds_read_b128 v[222:225], v147 offset:37888
	ds_read_b128 v[226:229], v147 offset:38912
	ds_read_b128 v[230:233], v147 offset:39936
	global_load_lds_dwordx4 v[240:241], off
	v_lshl_add_u64 v[240:241], s[16:17], 0, v[130:131]
	s_mov_b32 m0, s54
	s_nop 0
	global_load_lds_dwordx4 v[240:241], off
	s_waitcnt vmcnt(8)
	s_waitcnt lgkmcnt(0)
	s_barrier
	s_waitcnt lgkmcnt(0)
	v_mfma_f32_16x16x32_bf16 v[124:127], v[138:141], v[176:179], v[124:127]
	v_mfma_f32_16x16x32_bf16 v[120:123], v[152:155], v[176:179], v[120:123]
	v_mfma_f32_16x16x32_bf16 v[108:111], v[138:141], v[186:189], v[108:111]
	v_mfma_f32_16x16x32_bf16 v[104:107], v[152:155], v[186:189], v[104:107]
	v_mfma_f32_16x16x32_bf16 v[92:95], v[138:141], v[194:197], v[92:95]
	v_mfma_f32_16x16x32_bf16 v[88:91], v[152:155], v[194:197], v[88:91]
	v_mfma_f32_16x16x32_bf16 v[76:79], v[138:141], v[226:229], v[76:79]
	v_mfma_f32_16x16x32_bf16 v[72:75], v[152:155], v[226:229], v[72:75]
	v_mfma_f32_16x16x32_bf16 v[124:127], v[148:151], v[180:183], v[124:127]
	v_mfma_f32_16x16x32_bf16 v[120:123], v[156:159], v[180:183], v[120:123]
	v_mfma_f32_16x16x32_bf16 v[108:111], v[148:151], v[190:193], v[108:111]
	v_mfma_f32_16x16x32_bf16 v[104:107], v[156:159], v[190:193], v[104:107]
	v_mfma_f32_16x16x32_bf16 v[92:95], v[148:151], v[222:225], v[92:95]
	v_mfma_f32_16x16x32_bf16 v[88:91], v[156:159], v[222:225], v[88:91]
	v_mfma_f32_16x16x32_bf16 v[76:79], v[148:151], v[230:233], v[76:79]
	v_mfma_f32_16x16x32_bf16 v[72:75], v[156:159], v[230:233], v[72:75]
	v_mfma_f32_16x16x32_bf16 v[116:119], v[160:163], v[176:179], v[116:119]
	v_mfma_f32_16x16x32_bf16 v[112:115], v[168:171], v[176:179], v[112:115]
	v_mfma_f32_16x16x32_bf16 v[100:103], v[160:163], v[186:189], v[100:103]
	v_mfma_f32_16x16x32_bf16 v[96:99], v[168:171], v[186:189], v[96:99]
	v_mfma_f32_16x16x32_bf16 v[84:87], v[160:163], v[194:197], v[84:87]
	v_mfma_f32_16x16x32_bf16 v[80:83], v[168:171], v[194:197], v[80:83]
	v_mfma_f32_16x16x32_bf16 v[68:71], v[160:163], v[226:229], v[68:71]
	v_mfma_f32_16x16x32_bf16 v[64:67], v[168:171], v[226:229], v[64:67]
	v_mfma_f32_16x16x32_bf16 v[116:119], v[164:167], v[180:183], v[116:119]
	v_mfma_f32_16x16x32_bf16 v[112:115], v[172:175], v[180:183], v[112:115]
	v_mfma_f32_16x16x32_bf16 v[100:103], v[164:167], v[190:193], v[100:103]
	v_mfma_f32_16x16x32_bf16 v[96:99], v[172:175], v[190:193], v[96:99]
	v_mfma_f32_16x16x32_bf16 v[84:87], v[164:167], v[222:225], v[84:87]
	v_mfma_f32_16x16x32_bf16 v[80:83], v[172:175], v[222:225], v[80:83]
	v_mfma_f32_16x16x32_bf16 v[68:71], v[164:167], v[230:233], v[68:71]
	v_mfma_f32_16x16x32_bf16 v[64:67], v[172:175], v[230:233], v[64:67]
	s_barrier
; #define PG8_STAGE(bufoff, gbase) PG8_STAGEV(bufoff, gbase, voff)
; #define PG8_STAGEB(bufoff, gbase) PG8_STAGEV(bufoff, gbase, voffB)
; #define PG8_LDA(dst, b, h) do { _Pragma("unroll") for (int m = 0; m < 4; ++m) _Pragma("unroll") for (int k = 0; k < 2; ++k) dst[m][k] = *(const LAS bf16x8*)(lds + PG8_SA(b, h) + aoff + m * 2048 + k * 1024); } while (0)
; #define PG8_MMA(ai, bj, At, Bt) do { __builtin_amdgcn_s_setprio(1); _Pragma("unroll") for (int m = 0; m < 4; ++m) _Pragma("unroll") for (int n = 0; n < 2; ++n) _Pragma("unroll") for (int k = 0; k < 2; ++k) \
;         acc[ai][bj][m][n] = __builtin_amdgcn_mfma_f32_16x16x32_bf16(Bt[n][k], At[m][k], acc[ai][bj][m][n], 0, 0, 0); __builtin_amdgcn_s_setprio(0); } while (0)
; #define PG8_WAIT_V(n) asm volatile("s_waitcnt vmcnt(" #n ")" ::: "memory")
; #define PG8_WAIT_L(n) asm volatile("s_waitcnt lgkmcnt(" #n ")" ::: "memory")
; #define PG8_BAR __builtin_amdgcn_s_barrier()
; #define PG8_SCHED __builtin_amdgcn_sched_barrier(0)
; template <bool PERM, class Epi, class Sched>
; __device__ __forceinline__ void gemm_phase(LAS unsigned char* lds, const int K, const Sched& S, const Epi& E, const int wid0) {
;     ...
;         for (int t = 0; t < nt; t += 2) {
;     ...
;             PG8_LDA(At, 1, 1); PG8_STAGEB(PG8_SB(1, 0), b3); PG8_STAGEB(PG8_SB(1, 1), b3 + hstep); PG8_STAGE(PG8_SA(1, 0), a3);
;             PG8_WAIT_V(8); PG8_WAIT_L(0); PG8_BAR; PG8_MMA(1, 0, At, B0); PG8_MMA(1, 1, At, B1); PG8_BAR; PG8_SCHED;
	s_add_i32 s16, s58, s0
	v_lshl_add_u64 v[142:143], v[142:143], 0, s[42:43]
	s_mov_b32 m0, s16
	ds_read_b128 v[176:179], v147 offset:49152
	ds_read_b128 v[180:183], v147 offset:50176
	ds_read_b128 v[186:189], v147 offset:51200
	ds_read_b128 v[190:193], v147 offset:52224
	ds_read_b128 v[194:197], v147 offset:53248
	ds_read_b128 v[222:225], v147 offset:54272
	ds_read_b128 v[226:229], v147 offset:55296
	ds_read_b128 v[230:233], v147 offset:56320
	global_load_lds_dwordx4 v[142:143], off
	s_add_i32 m0, s16, 0x2000
	s_add_u32 s6, s6, 0x40080
	v_lshl_add_u64 v[142:143], v[234:235], 0, s[42:43]
	s_addc_u32 s7, s7, 0
	s_add_i32 s16, s59, s0
	global_load_lds_dwordx4 v[142:143], off
	v_lshl_add_u64 v[142:143], s[6:7], 0, v[184:185]
	s_mov_b32 m0, s16
	s_nop 0
	global_load_lds_dwordx4 v[142:143], off
	v_lshl_add_u64 v[142:143], s[6:7], 0, v[128:129]
	s_add_i32 m0, s16, 0x2000
	s_nop 0
	global_load_lds_dwordx4 v[142:143], off
	v_lshl_add_u64 v[142:143], v[236:237], 0, s[42:43]
	s_mov_b32 m0, s55
	s_nop 0
	global_load_lds_dwordx4 v[142:143], off
	v_lshl_add_u64 v[142:143], v[238:239], 0, s[42:43]
	s_mov_b32 m0, s66
	s_nop 0
	global_load_lds_dwordx4 v[142:143], off
	s_waitcnt vmcnt(8)
	s_waitcnt lgkmcnt(0)
	s_barrier
	s_waitcnt lgkmcnt(0)
	v_mfma_f32_16x16x32_bf16 v[60:63], v[138:141], v[176:179], v[60:63]
	v_mfma_f32_16x16x32_bf16 v[56:59], v[152:155], v[176:179], v[56:59]
	v_mfma_f32_16x16x32_bf16 v[44:47], v[138:141], v[186:189], v[44:47]
	v_mfma_f32_16x16x32_bf16 v[40:43], v[152:155], v[186:189], v[40:43]
	v_mfma_f32_16x16x32_bf16 v[28:31], v[138:141], v[194:197], v[28:31]
	v_mfma_f32_16x16x32_bf16 v[24:27], v[152:155], v[194:197], v[24:27]
	v_mfma_f32_16x16x32_bf16 v[12:15], v[138:141], v[226:229], v[12:15]
	v_mfma_f32_16x16x32_bf16 v[8:11], v[152:155], v[226:229], v[8:11]
	v_mfma_f32_16x16x32_bf16 v[60:63], v[148:151], v[180:183], v[60:63]
	v_mfma_f32_16x16x32_bf16 v[56:59], v[156:159], v[180:183], v[56:59]
	v_mfma_f32_16x16x32_bf16 v[44:47], v[148:151], v[190:193], v[44:47]
	v_mfma_f32_16x16x32_bf16 v[40:43], v[156:159], v[190:193], v[40:43]
	v_mfma_f32_16x16x32_bf16 v[28:31], v[148:151], v[222:225], v[28:31]
	v_mfma_f32_16x16x32_bf16 v[24:27], v[156:159], v[222:225], v[24:27]
	v_mfma_f32_16x16x32_bf16 v[12:15], v[148:151], v[230:233], v[12:15]
	v_mfma_f32_16x16x32_bf16 v[8:11], v[156:159], v[230:233], v[8:11]
	v_mfma_f32_16x16x32_bf16 v[52:55], v[160:163], v[176:179], v[52:55]
	v_mfma_f32_16x16x32_bf16 v[48:51], v[168:171], v[176:179], v[48:51]
	v_mfma_f32_16x16x32_bf16 v[36:39], v[160:163], v[186:189], v[36:39]
	v_mfma_f32_16x16x32_bf16 v[32:35], v[168:171], v[186:189], v[32:35]
	v_mfma_f32_16x16x32_bf16 v[20:23], v[160:163], v[194:197], v[20:23]
	v_mfma_f32_16x16x32_bf16 v[16:19], v[168:171], v[194:197], v[16:19]
	v_mfma_f32_16x16x32_bf16 v[4:7], v[160:163], v[226:229], v[4:7]
	v_mfma_f32_16x16x32_bf16 v[0:3], v[168:171], v[226:229], v[0:3]
	v_mfma_f32_16x16x32_bf16 v[52:55], v[164:167], v[180:183], v[52:55]
	v_mfma_f32_16x16x32_bf16 v[48:51], v[172:175], v[180:183], v[48:51]
	v_mfma_f32_16x16x32_bf16 v[36:39], v[164:167], v[190:193], v[36:39]
	v_mfma_f32_16x16x32_bf16 v[32:35], v[172:175], v[190:193], v[32:35]
	v_mfma_f32_16x16x32_bf16 v[20:23], v[164:167], v[222:225], v[20:23]
	v_mfma_f32_16x16x32_bf16 v[16:19], v[172:175], v[222:225], v[16:19]
	v_mfma_f32_16x16x32_bf16 v[4:7], v[164:167], v[230:233], v[4:7]
	v_mfma_f32_16x16x32_bf16 v[0:3], v[172:175], v[230:233], v[0:3]
	s_barrier
	s_add_i32 s92, s92, 2
	s_add_u32 s82, s82, 0x100
	s_addc_u32 s83, s83, 0
	s_add_u32 s79, s79, 0x100
	s_addc_u32 s81, s81, 0
	s_cmp_gt_u32 s92, 13
	s_cbranch_scc0 .LBB0_635
	s_and_b64 vcc, exec, s[68:69]
	s_cbranch_vccz .LBB0_638
	s_barrier

; #define PG8_STAGE(bufoff, gbase) PG8_STAGEV(bufoff, gbase, voff)
; #define PG8_STAGEB(bufoff, gbase) PG8_STAGEV(bufoff, gbase, voffB)
; #define PG8_LDA(dst, b, h) do { _Pragma("unroll") for (int m = 0; m < 4; ++m) _Pragma("unroll") for (int k = 0; k < 2; ++k) dst[m][k] = *(const LAS bf16x8*)(lds + PG8_SA(b, h) + aoff + m * 2048 + k * 1024); } while (0)
; #define PG8_LDB(dst, b, h) do { _Pragma("unroll") for (int n = 0; n < 2; ++n) _Pragma("unroll") for (int k = 0; k < 2; ++k) dst[n][k] = *(const LAS bf16x8*)(lds + PG8_SB(b, h) + boff + n * 2048 + k * 1024); } while (0)
; #define PG8_MMA(ai, bj, At, Bt) do { __builtin_amdgcn_s_setprio(1); _Pragma("unroll") for (int m = 0; m < 4; ++m) _Pragma("unroll") for (int n = 0; n < 2; ++n) _Pragma("unroll") for (int k = 0; k < 2; ++k) \
;         acc[ai][bj][m][n] = __builtin_amdgcn_mfma_f32_16x16x32_bf16(Bt[n][k], At[m][k], acc[ai][bj][m][n], 0, 0, 0); __builtin_amdgcn_s_setprio(0); } while (0)
; #define PG8_WAIT_V(n) asm volatile("s_waitcnt vmcnt(" #n ")" ::: "memory")
; #define PG8_WAIT_L(n) asm volatile("s_waitcnt lgkmcnt(" #n ")" ::: "memory")
; #define PG8_BAR __builtin_amdgcn_s_barrier()
; #define PG8_SCHED __builtin_amdgcn_sched_barrier(0)
; template <bool PERM, class Epi, class Sched>
; __device__ __forceinline__ void gemm_phase(LAS unsigned char* lds, const int K, const Sched& S, const Epi& E, const int wid0) {
;     ...
;             PG8_LDB(B0, 0, 0); PG8_LDB(B1, 0, 1); PG8_SCHED; PG8_LDA(At, 0, 0); PG8_STAGE(PG8_SA(1, 1), a1 + hstep);
;             PG8_WAIT_V(8); PG8_WAIT_L(0); PG8_BAR; PG8_MMA(0, 0, At, B0); PG8_MMA(0, 1, At, B1); PG8_BAR; PG8_SCHED;
;             PG8_LDA(At, 0, 1); PG8_STAGEB(PG8_SB(0, 0), b2); PG8_STAGEB(PG8_SB(0, 1), b2 + hstep); PG8_STAGE(PG8_SA(0, 0), a2);
;             PG8_WAIT_V(8); PG8_WAIT_L(0); PG8_BAR; PG8_MMA(1, 0, At, B0); PG8_MMA(1, 1, At, B1); PG8_BAR; PG8_SCHED;
.LBB0_651:
	s_add_u32 s6, s82, 0xfffc0080
	s_addc_u32 s7, s83, -1
	s_add_i32 s16, 0, 0x10000
	s_cmp_eq_u32 s92, 12
	s_cselect_b32 s23, s46, s7
	s_cselect_b32 s22, s48, s6
	s_cselect_b32 s7, s71, s81
	s_cselect_b32 s6, s73, s79
	s_add_i32 s58, 0, 0x14000
	v_add_u32_e32 v154, s16, v147
	v_add_u32_e32 v170, s58, v147
	ds_read_b128 v[138:141], v154
	ds_read_b128 v[142:145], v154 offset:1024
	ds_read_b128 v[150:153], v154 offset:2048
	ds_read_b128 v[154:157], v154 offset:3072
	ds_read_b128 v[158:161], v170
	ds_read_b128 v[162:165], v170 offset:1024
	ds_read_b128 v[166:169], v170 offset:2048
	ds_read_b128 v[170:173], v170 offset:3072
	v_lshl_add_u64 v[182:183], s[82:83], 0, v[134:135]
	s_add_i32 m0, s50, 0xc000
	ds_read_b128 v[174:177], v149
	ds_read_b128 v[178:181], v149 offset:1024
	ds_read_b128 v[186:189], v149 offset:2048
	ds_read_b128 v[190:193], v149 offset:3072
	ds_read_b128 v[194:197], v149 offset:4096
	ds_read_b128 v[222:225], v149 offset:5120
	ds_read_b128 v[226:229], v149 offset:6144
	ds_read_b128 v[230:233], v149 offset:7168
	global_load_lds_dwordx4 v[182:183], off
	v_lshl_add_u64 v[182:183], s[82:83], 0, v[136:137]
	s_add_i32 m0, s50, 0xe000
	s_nop 0
	global_load_lds_dwordx4 v[182:183], off
	s_waitcnt vmcnt(8)
	s_waitcnt lgkmcnt(0)
	s_barrier
	s_waitcnt lgkmcnt(0)
	v_mfma_f32_16x16x32_bf16 v[124:127], v[138:141], v[174:177], v[124:127]
	v_mfma_f32_16x16x32_bf16 v[120:123], v[150:153], v[174:177], v[120:123]
	v_mfma_f32_16x16x32_bf16 v[108:111], v[138:141], v[186:189], v[108:111]
	v_mfma_f32_16x16x32_bf16 v[104:107], v[150:153], v[186:189], v[104:107]
	v_mfma_f32_16x16x32_bf16 v[92:95], v[138:141], v[194:197], v[92:95]
	v_mfma_f32_16x16x32_bf16 v[88:91], v[150:153], v[194:197], v[88:91]
	v_mfma_f32_16x16x32_bf16 v[76:79], v[138:141], v[226:229], v[76:79]
	v_mfma_f32_16x16x32_bf16 v[72:75], v[150:153], v[226:229], v[72:75]
	v_mfma_f32_16x16x32_bf16 v[124:127], v[142:145], v[178:181], v[124:127]
	v_mfma_f32_16x16x32_bf16 v[120:123], v[154:157], v[178:181], v[120:123]
	v_mfma_f32_16x16x32_bf16 v[108:111], v[142:145], v[190:193], v[108:111]
	v_mfma_f32_16x16x32_bf16 v[104:107], v[154:157], v[190:193], v[104:107]
	v_mfma_f32_16x16x32_bf16 v[92:95], v[142:145], v[222:225], v[92:95]
	v_mfma_f32_16x16x32_bf16 v[88:91], v[154:157], v[222:225], v[88:91]
	v_mfma_f32_16x16x32_bf16 v[76:79], v[142:145], v[230:233], v[76:79]
	v_mfma_f32_16x16x32_bf16 v[72:75], v[154:157], v[230:233], v[72:75]
	v_mfma_f32_16x16x32_bf16 v[116:119], v[158:161], v[174:177], v[116:119]
	v_mfma_f32_16x16x32_bf16 v[112:115], v[166:169], v[174:177], v[112:115]
	v_mfma_f32_16x16x32_bf16 v[100:103], v[158:161], v[186:189], v[100:103]
	v_mfma_f32_16x16x32_bf16 v[96:99], v[166:169], v[186:189], v[96:99]
	v_mfma_f32_16x16x32_bf16 v[84:87], v[158:161], v[194:197], v[84:87]
	v_mfma_f32_16x16x32_bf16 v[80:83], v[166:169], v[194:197], v[80:83]
	v_mfma_f32_16x16x32_bf16 v[68:71], v[158:161], v[226:229], v[68:71]
	v_mfma_f32_16x16x32_bf16 v[64:67], v[166:169], v[226:229], v[64:67]
	v_mfma_f32_16x16x32_bf16 v[116:119], v[162:165], v[178:181], v[116:119]
	v_mfma_f32_16x16x32_bf16 v[112:115], v[170:173], v[178:181], v[112:115]
	v_mfma_f32_16x16x32_bf16 v[100:103], v[162:165], v[190:193], v[100:103]
	v_mfma_f32_16x16x32_bf16 v[96:99], v[170:173], v[190:193], v[96:99]
	v_mfma_f32_16x16x32_bf16 v[84:87], v[162:165], v[222:225], v[84:87]
	v_mfma_f32_16x16x32_bf16 v[80:83], v[170:173], v[222:225], v[80:83]
	v_mfma_f32_16x16x32_bf16 v[68:71], v[162:165], v[230:233], v[68:71]
	v_mfma_f32_16x16x32_bf16 v[64:67], v[170:173], v[230:233], v[64:67]
	s_barrier
	s_add_i32 s16, s16, s0
	v_lshl_add_u64 v[182:183], s[6:7], 0, v[184:185]
	s_mov_b32 m0, s16
	ds_read_b128 v[174:177], v149 offset:16384
	ds_read_b128 v[178:181], v149 offset:17408
	ds_read_b128 v[186:189], v149 offset:18432
	ds_read_b128 v[190:193], v149 offset:19456
	ds_read_b128 v[194:197], v149 offset:20480
	ds_read_b128 v[222:225], v149 offset:21504
	ds_read_b128 v[226:229], v149 offset:22528
	ds_read_b128 v[230:233], v149 offset:23552
	global_load_lds_dwordx4 v[182:183], off
	s_add_i32 m0, s16, 0x2000
	s_add_u32 s16, s6, 0x40000
	v_lshl_add_u64 v[234:235], s[6:7], 0, v[128:129]
	s_addc_u32 s17, s7, 0
	s_add_i32 s58, s58, s0
	global_load_lds_dwordx4 v[234:235], off
	v_lshl_add_u64 v[236:237], s[16:17], 0, v[184:185]
	s_mov_b32 m0, s58
	v_lshl_add_u64 v[238:239], s[22:23], 0, v[130:131]
	global_load_lds_dwordx4 v[236:237], off
	v_lshl_add_u64 v[236:237], s[16:17], 0, v[128:129]
	s_add_i32 m0, s58, 0x2000
	s_nop 0
	global_load_lds_dwordx4 v[236:237], off
	v_lshl_add_u64 v[236:237], s[22:23], 0, v[132:133]
	s_mov_b32 m0, s50
	s_nop 0
	global_load_lds_dwordx4 v[236:237], off
	s_mov_b32 m0, s52
	s_nop 0
	global_load_lds_dwordx4 v[238:239], off
	s_waitcnt vmcnt(8)
	s_waitcnt lgkmcnt(0)
	s_barrier
; #define PG8_STAGE(bufoff, gbase) PG8_STAGEV(bufoff, gbase, voff)
; #define PG8_LDA(dst, b, h) do { _Pragma("unroll") for (int m = 0; m < 4; ++m) _Pragma("unroll") for (int k = 0; k < 2; ++k) dst[m][k] = *(const LAS bf16x8*)(lds + PG8_SA(b, h) + aoff + m * 2048 + k * 1024); } while (0)
; #define PG8_LDB(dst, b, h) do { _Pragma("unroll") for (int n = 0; n < 2; ++n) _Pragma("unroll") for (int k = 0; k < 2; ++k) dst[n][k] = *(const LAS bf16x8*)(lds + PG8_SB(b, h) + boff + n * 2048 + k * 1024); } while (0)
; #define PG8_MMA(ai, bj, At, Bt) do { __builtin_amdgcn_s_setprio(1); _Pragma("unroll") for (int m = 0; m < 4; ++m) _Pragma("unroll") for (int n = 0; n < 2; ++n) _Pragma("unroll") for (int k = 0; k < 2; ++k) \
;         acc[ai][bj][m][n] = __builtin_amdgcn_mfma_f32_16x16x32_bf16(Bt[n][k], At[m][k], acc[ai][bj][m][n], 0, 0, 0); __builtin_amdgcn_s_setprio(0); } while (0)
; #define PG8_WAIT_V(n) asm volatile("s_waitcnt vmcnt(" #n ")" ::: "memory")
; #define PG8_WAIT_L(n) asm volatile("s_waitcnt lgkmcnt(" #n ")" ::: "memory")
; #define PG8_BAR __builtin_amdgcn_s_barrier()
; #define PG8_SCHED __builtin_amdgcn_sched_barrier(0)
; template <bool PERM, class Epi, class Sched>
; __device__ __forceinline__ void gemm_phase(LAS unsigned char* lds, const int K, const Sched& S, const Epi& E, const int wid0) {
;     ...
;             PG8_WAIT_V(8); PG8_WAIT_L(0); PG8_BAR; PG8_MMA(1, 0, At, B0); PG8_MMA(1, 1, At, B1); PG8_BAR; PG8_SCHED;
;             PG8_LDB(B0, 1, 0); PG8_LDB(B1, 1, 1); PG8_SCHED; PG8_LDA(At, 1, 0); PG8_STAGE(PG8_SA(0, 1), a2 + hstep);
;             PG8_WAIT_V(8); PG8_WAIT_L(0); PG8_BAR; PG8_MMA(0, 0, At, B0); PG8_MMA(0, 1, At, B1); PG8_BAR; PG8_SCHED;
	s_waitcnt lgkmcnt(0)
	v_mfma_f32_16x16x32_bf16 v[60:63], v[138:141], v[174:177], v[60:63]
	v_mfma_f32_16x16x32_bf16 v[56:59], v[150:153], v[174:177], v[56:59]
	v_mfma_f32_16x16x32_bf16 v[44:47], v[138:141], v[186:189], v[44:47]
	v_mfma_f32_16x16x32_bf16 v[40:43], v[150:153], v[186:189], v[40:43]
	v_mfma_f32_16x16x32_bf16 v[28:31], v[138:141], v[194:197], v[28:31]
	v_mfma_f32_16x16x32_bf16 v[24:27], v[150:153], v[194:197], v[24:27]
	v_mfma_f32_16x16x32_bf16 v[12:15], v[138:141], v[226:229], v[12:15]
	v_mfma_f32_16x16x32_bf16 v[8:11], v[150:153], v[226:229], v[8:11]
	v_mfma_f32_16x16x32_bf16 v[60:63], v[142:145], v[178:181], v[60:63]
	v_mfma_f32_16x16x32_bf16 v[56:59], v[154:157], v[178:181], v[56:59]
	v_mfma_f32_16x16x32_bf16 v[44:47], v[142:145], v[190:193], v[44:47]
	v_mfma_f32_16x16x32_bf16 v[40:43], v[154:157], v[190:193], v[40:43]
	v_mfma_f32_16x16x32_bf16 v[28:31], v[142:145], v[222:225], v[28:31]
	v_mfma_f32_16x16x32_bf16 v[24:27], v[154:157], v[222:225], v[24:27]
	v_mfma_f32_16x16x32_bf16 v[12:15], v[142:145], v[230:233], v[12:15]
	v_mfma_f32_16x16x32_bf16 v[8:11], v[154:157], v[230:233], v[8:11]
	v_mfma_f32_16x16x32_bf16 v[52:55], v[158:161], v[174:177], v[52:55]
	v_mfma_f32_16x16x32_bf16 v[48:51], v[166:169], v[174:177], v[48:51]
	v_mfma_f32_16x16x32_bf16 v[36:39], v[158:161], v[186:189], v[36:39]
	v_mfma_f32_16x16x32_bf16 v[32:35], v[166:169], v[186:189], v[32:35]
	v_mfma_f32_16x16x32_bf16 v[20:23], v[158:161], v[194:197], v[20:23]
	v_mfma_f32_16x16x32_bf16 v[16:19], v[166:169], v[194:197], v[16:19]
	v_mfma_f32_16x16x32_bf16 v[4:7], v[158:161], v[226:229], v[4:7]
	v_mfma_f32_16x16x32_bf16 v[0:3], v[166:169], v[226:229], v[0:3]
	v_mfma_f32_16x16x32_bf16 v[52:55], v[162:165], v[178:181], v[52:55]
	v_mfma_f32_16x16x32_bf16 v[48:51], v[170:173], v[178:181], v[48:51]
	v_mfma_f32_16x16x32_bf16 v[36:39], v[162:165], v[190:193], v[36:39]
	v_mfma_f32_16x16x32_bf16 v[32:35], v[170:173], v[190:193], v[32:35]
	v_mfma_f32_16x16x32_bf16 v[20:23], v[162:165], v[222:225], v[20:23]
	v_mfma_f32_16x16x32_bf16 v[16:19], v[170:173], v[222:225], v[16:19]
	v_mfma_f32_16x16x32_bf16 v[4:7], v[162:165], v[230:233], v[4:7]
	v_mfma_f32_16x16x32_bf16 v[0:3], v[170:173], v[230:233], v[0:3]
	s_barrier
	s_add_i32 s58, 0, 0x18000
	s_add_i32 s59, 0, 0x1c000
	v_add_u32_e32 v154, s58, v147
	v_add_u32_e32 v170, s59, v147
	ds_read_b128 v[138:141], v154
	ds_read_b128 v[142:145], v154 offset:1024
	ds_read_b128 v[150:153], v154 offset:2048
	ds_read_b128 v[154:157], v154 offset:3072
	ds_read_b128 v[158:161], v170
	ds_read_b128 v[162:165], v170 offset:1024
	ds_read_b128 v[166:169], v170 offset:2048
	ds_read_b128 v[170:173], v170 offset:3072
	s_add_u32 s16, s22, 0x40000
	s_addc_u32 s17, s23, 0
	s_mov_b32 m0, s53
	v_lshl_add_u64 v[240:241], s[16:17], 0, v[132:133]
	ds_read_b128 v[174:177], v149 offset:32768
	ds_read_b128 v[178:181], v149 offset:33792
	ds_read_b128 v[186:189], v149 offset:34816
	ds_read_b128 v[190:193], v149 offset:35840
	ds_read_b128 v[194:197], v149 offset:36864
	ds_read_b128 v[222:225], v149 offset:37888
	ds_read_b128 v[226:229], v149 offset:38912
	ds_read_b128 v[230:233], v149 offset:39936
	global_load_lds_dwordx4 v[240:241], off
	v_lshl_add_u64 v[240:241], s[16:17], 0, v[130:131]
	s_mov_b32 m0, s54
	s_nop 0
	global_load_lds_dwordx4 v[240:241], off
	s_waitcnt vmcnt(8)
	s_waitcnt lgkmcnt(0)
	s_barrier
	s_waitcnt lgkmcnt(0)
	v_mfma_f32_16x16x32_bf16 v[124:127], v[138:141], v[174:177], v[124:127]
	v_mfma_f32_16x16x32_bf16 v[120:123], v[150:153], v[174:177], v[120:123]
	v_mfma_f32_16x16x32_bf16 v[108:111], v[138:141], v[186:189], v[108:111]
	v_mfma_f32_16x16x32_bf16 v[104:107], v[150:153], v[186:189], v[104:107]
	v_mfma_f32_16x16x32_bf16 v[92:95], v[138:141], v[194:197], v[92:95]
	v_mfma_f32_16x16x32_bf16 v[88:91], v[150:153], v[194:197], v[88:91]
	v_mfma_f32_16x16x32_bf16 v[76:79], v[138:141], v[226:229], v[76:79]
	v_mfma_f32_16x16x32_bf16 v[72:75], v[150:153], v[226:229], v[72:75]
	v_mfma_f32_16x16x32_bf16 v[124:127], v[142:145], v[178:181], v[124:127]
	v_mfma_f32_16x16x32_bf16 v[120:123], v[154:157], v[178:181], v[120:123]
	v_mfma_f32_16x16x32_bf16 v[108:111], v[142:145], v[190:193], v[108:111]
	v_mfma_f32_16x16x32_bf16 v[104:107], v[154:157], v[190:193], v[104:107]
	v_mfma_f32_16x16x32_bf16 v[92:95], v[142:145], v[222:225], v[92:95]
	v_mfma_f32_16x16x32_bf16 v[88:91], v[154:157], v[222:225], v[88:91]
	v_mfma_f32_16x16x32_bf16 v[76:79], v[142:145], v[230:233], v[76:79]
	v_mfma_f32_16x16x32_bf16 v[72:75], v[154:157], v[230:233], v[72:75]
	v_mfma_f32_16x16x32_bf16 v[116:119], v[158:161], v[174:177], v[116:119]
	v_mfma_f32_16x16x32_bf16 v[112:115], v[166:169], v[174:177], v[112:115]
	v_mfma_f32_16x16x32_bf16 v[100:103], v[158:161], v[186:189], v[100:103]
	v_mfma_f32_16x16x32_bf16 v[96:99], v[166:169], v[186:189], v[96:99]
	v_mfma_f32_16x16x32_bf16 v[84:87], v[158:161], v[194:197], v[84:87]
	v_mfma_f32_16x16x32_bf16 v[80:83], v[166:169], v[194:197], v[80:83]
	v_mfma_f32_16x16x32_bf16 v[68:71], v[158:161], v[226:229], v[68:71]
	v_mfma_f32_16x16x32_bf16 v[64:67], v[166:169], v[226:229], v[64:67]
	v_mfma_f32_16x16x32_bf16 v[116:119], v[162:165], v[178:181], v[116:119]
	v_mfma_f32_16x16x32_bf16 v[112:115], v[170:173], v[178:181], v[112:115]
	v_mfma_f32_16x16x32_bf16 v[100:103], v[162:165], v[190:193], v[100:103]
	v_mfma_f32_16x16x32_bf16 v[96:99], v[170:173], v[190:193], v[96:99]
	v_mfma_f32_16x16x32_bf16 v[84:87], v[162:165], v[222:225], v[84:87]
	v_mfma_f32_16x16x32_bf16 v[80:83], v[170:173], v[222:225], v[80:83]
	v_mfma_f32_16x16x32_bf16 v[68:71], v[162:165], v[230:233], v[68:71]
	v_mfma_f32_16x16x32_bf16 v[64:67], v[170:173], v[230:233], v[64:67]
	s_barrier
; #define PG8_STAGE(bufoff, gbase) PG8_STAGEV(bufoff, gbase, voff)
; #define PG8_STAGEB(bufoff, gbase) PG8_STAGEV(bufoff, gbase, voffB)
; #define PG8_LDA(dst, b, h) do { _Pragma("unroll") for (int m = 0; m < 4; ++m) _Pragma("unroll") for (int k = 0; k < 2; ++k) dst[m][k] = *(const LAS bf16x8*)(lds + PG8_SA(b, h) + aoff + m * 2048 + k * 1024); } while (0)
; #define PG8_MMA(ai, bj, At, Bt) do { __builtin_amdgcn_s_setprio(1); _Pragma("unroll") for (int m = 0; m < 4; ++m) _Pragma("unroll") for (int n = 0; n < 2; ++n) _Pragma("unroll") for (int k = 0; k < 2; ++k) \
;         acc[ai][bj][m][n] = __builtin_amdgcn_mfma_f32_16x16x32_bf16(Bt[n][k], At[m][k], acc[ai][bj][m][n], 0, 0, 0); __builtin_amdgcn_s_setprio(0); } while (0)
; #define PG8_WAIT_V(n) asm volatile("s_waitcnt vmcnt(" #n ")" ::: "memory")
; #define PG8_WAIT_L(n) asm volatile("s_waitcnt lgkmcnt(" #n ")" ::: "memory")
; #define PG8_BAR __builtin_amdgcn_s_barrier()
; #define PG8_SCHED __builtin_amdgcn_sched_barrier(0)
; template <bool PERM, class Epi, class Sched>
; __device__ __forceinline__ void gemm_phase(LAS unsigned char* lds, const int K, const Sched& S, const Epi& E, const int wid0) {
;     ...
;             PG8_LDA(At, 1, 1); PG8_STAGEB(PG8_SB(1, 0), b3); PG8_STAGEB(PG8_SB(1, 1), b3 + hstep); PG8_STAGE(PG8_SA(1, 0), a3);
;             PG8_WAIT_V(8); PG8_WAIT_L(0); PG8_BAR; PG8_MMA(1, 0, At, B0); PG8_MMA(1, 1, At, B1); PG8_BAR; PG8_SCHED;
;         }
	s_add_i32 s16, s58, s0
	v_lshl_add_u64 v[182:183], v[182:183], 0, s[42:43]
	s_mov_b32 m0, s16
	ds_read_b128 v[174:177], v149 offset:49152
	ds_read_b128 v[178:181], v149 offset:50176
	ds_read_b128 v[186:189], v149 offset:51200
	ds_read_b128 v[190:193], v149 offset:52224
	ds_read_b128 v[194:197], v149 offset:53248
	ds_read_b128 v[222:225], v149 offset:54272
	ds_read_b128 v[226:229], v149 offset:55296
	ds_read_b128 v[230:233], v149 offset:56320
	global_load_lds_dwordx4 v[182:183], off
	s_add_i32 m0, s16, 0x2000
	s_add_u32 s6, s6, 0x40080
	v_lshl_add_u64 v[182:183], v[234:235], 0, s[42:43]
	s_addc_u32 s7, s7, 0
	s_add_i32 s16, s59, s0
	global_load_lds_dwordx4 v[182:183], off
	v_lshl_add_u64 v[182:183], s[6:7], 0, v[184:185]
	s_mov_b32 m0, s16
	s_nop 0
	global_load_lds_dwordx4 v[182:183], off
	v_lshl_add_u64 v[182:183], s[6:7], 0, v[128:129]
	s_add_i32 m0, s16, 0x2000
	s_nop 0
	global_load_lds_dwordx4 v[182:183], off
	v_lshl_add_u64 v[182:183], v[236:237], 0, s[42:43]
	s_mov_b32 m0, s55
	s_nop 0
	global_load_lds_dwordx4 v[182:183], off
	v_lshl_add_u64 v[182:183], v[238:239], 0, s[42:43]
	s_mov_b32 m0, s66
	s_nop 0
	global_load_lds_dwordx4 v[182:183], off
	s_waitcnt vmcnt(8)
	s_waitcnt lgkmcnt(0)
	s_barrier
	s_waitcnt lgkmcnt(0)
	v_mfma_f32_16x16x32_bf16 v[60:63], v[138:141], v[174:177], v[60:63]
	v_mfma_f32_16x16x32_bf16 v[56:59], v[150:153], v[174:177], v[56:59]
	v_mfma_f32_16x16x32_bf16 v[44:47], v[138:141], v[186:189], v[44:47]
	v_mfma_f32_16x16x32_bf16 v[40:43], v[150:153], v[186:189], v[40:43]
	v_mfma_f32_16x16x32_bf16 v[28:31], v[138:141], v[194:197], v[28:31]
	v_mfma_f32_16x16x32_bf16 v[24:27], v[150:153], v[194:197], v[24:27]
	v_mfma_f32_16x16x32_bf16 v[12:15], v[138:141], v[226:229], v[12:15]
	v_mfma_f32_16x16x32_bf16 v[8:11], v[150:153], v[226:229], v[8:11]
	v_mfma_f32_16x16x32_bf16 v[60:63], v[142:145], v[178:181], v[60:63]
	v_mfma_f32_16x16x32_bf16 v[56:59], v[154:157], v[178:181], v[56:59]
	v_mfma_f32_16x16x32_bf16 v[44:47], v[142:145], v[190:193], v[44:47]
	v_mfma_f32_16x16x32_bf16 v[40:43], v[154:157], v[190:193], v[40:43]
	v_mfma_f32_16x16x32_bf16 v[28:31], v[142:145], v[222:225], v[28:31]
	v_mfma_f32_16x16x32_bf16 v[24:27], v[154:157], v[222:225], v[24:27]
	v_mfma_f32_16x16x32_bf16 v[12:15], v[142:145], v[230:233], v[12:15]
	v_mfma_f32_16x16x32_bf16 v[8:11], v[154:157], v[230:233], v[8:11]
	v_mfma_f32_16x16x32_bf16 v[52:55], v[158:161], v[174:177], v[52:55]
	v_mfma_f32_16x16x32_bf16 v[48:51], v[166:169], v[174:177], v[48:51]
	v_mfma_f32_16x16x32_bf16 v[36:39], v[158:161], v[186:189], v[36:39]
	v_mfma_f32_16x16x32_bf16 v[32:35], v[166:169], v[186:189], v[32:35]
	v_mfma_f32_16x16x32_bf16 v[20:23], v[158:161], v[194:197], v[20:23]
	v_mfma_f32_16x16x32_bf16 v[16:19], v[166:169], v[194:197], v[16:19]
	v_mfma_f32_16x16x32_bf16 v[4:7], v[158:161], v[226:229], v[4:7]
	v_mfma_f32_16x16x32_bf16 v[0:3], v[166:169], v[226:229], v[0:3]
	v_mfma_f32_16x16x32_bf16 v[52:55], v[162:165], v[178:181], v[52:55]
	v_mfma_f32_16x16x32_bf16 v[48:51], v[170:173], v[178:181], v[48:51]
	v_mfma_f32_16x16x32_bf16 v[36:39], v[162:165], v[190:193], v[36:39]
	v_mfma_f32_16x16x32_bf16 v[32:35], v[170:173], v[190:193], v[32:35]
	v_mfma_f32_16x16x32_bf16 v[20:23], v[162:165], v[222:225], v[20:23]
	v_mfma_f32_16x16x32_bf16 v[16:19], v[170:173], v[222:225], v[16:19]
	v_mfma_f32_16x16x32_bf16 v[4:7], v[162:165], v[230:233], v[4:7]
	v_mfma_f32_16x16x32_bf16 v[0:3], v[170:173], v[230:233], v[0:3]
	s_barrier
	s_add_i32 s92, s92, 2
	s_add_u32 s82, s82, 0x100
	s_addc_u32 s83, s83, 0
	s_add_u32 s79, s79, 0x100
	s_addc_u32 s81, s81, 0
	s_cmp_gt_u32 s92, 13
	s_cbranch_scc0 .LBB0_651
	s_and_b64 vcc, exec, s[68:69]
	s_cbranch_vccz .LBB0_654
	s_barrier

; #define PG8_STAGE(bufoff, gbase) PG8_STAGEV(bufoff, gbase, voff)
; #define PG8_STAGEB(bufoff, gbase) PG8_STAGEV(bufoff, gbase, voffB)
; #define PG8_LDA(dst, b, h) do { _Pragma("unroll") for (int m = 0; m < 4; ++m) _Pragma("unroll") for (int k = 0; k < 2; ++k) dst[m][k] = *(const LAS bf16x8*)(lds + PG8_SA(b, h) + aoff + m * 2048 + k * 1024); } while (0)
; #define PG8_LDB(dst, b, h) do { _Pragma("unroll") for (int n = 0; n < 2; ++n) _Pragma("unroll") for (int k = 0; k < 2; ++k) dst[n][k] = *(const LAS bf16x8*)(lds + PG8_SB(b, h) + boff + n * 2048 + k * 1024); } while (0)
; #define PG8_MMA(ai, bj, At, Bt) do { __builtin_amdgcn_s_setprio(1); _Pragma("unroll") for (int m = 0; m < 4; ++m) _Pragma("unroll") for (int n = 0; n < 2; ++n) _Pragma("unroll") for (int k = 0; k < 2; ++k) \
;         acc[ai][bj][m][n] = __builtin_amdgcn_mfma_f32_16x16x32_bf16(Bt[n][k], At[m][k], acc[ai][bj][m][n], 0, 0, 0); __builtin_amdgcn_s_setprio(0); } while (0)
; #define PG8_WAIT_V(n) asm volatile("s_waitcnt vmcnt(" #n ")" ::: "memory")
; #define PG8_WAIT_L(n) asm volatile("s_waitcnt lgkmcnt(" #n ")" ::: "memory")
; #define PG8_BAR __builtin_amdgcn_s_barrier()
; #define PG8_SCHED __builtin_amdgcn_sched_barrier(0)
; template <bool PERM, class Epi, class Sched>
; __device__ __forceinline__ void gemm_phase(LAS unsigned char* lds, const int K, const Sched& S, const Epi& E, const int wid0) {
;     ...
;             const bool last = (t == nt - 2);
;             const char* a1 = cA + (size_t)(t + 1) * kstep;
;             const char* a2 = last ? nA : cA + (size_t)(t + 2) * kstep; const char* b2 = last ? nB : cB + (size_t)(t + 2) * kstep;
;             const char* a3 = a2 + kstep; const char* b3 = b2 + kstep;
;             PG8_LDB(B0, 0, 0); PG8_LDB(B1, 0, 1); PG8_SCHED; PG8_LDA(At, 0, 0); PG8_STAGE(PG8_SA(1, 1), a1 + hstep);
;             PG8_WAIT_V(8); PG8_WAIT_L(0); PG8_BAR; PG8_MMA(0, 0, At, B0); PG8_MMA(0, 1, At, B1); PG8_BAR; PG8_SCHED;
;             PG8_LDA(At, 0, 1); PG8_STAGEB(PG8_SB(0, 0), b2); PG8_STAGEB(PG8_SB(0, 1), b2 + hstep); PG8_STAGE(PG8_SA(0, 0), a2);
.LBB0_667:
	s_add_u32 s6, s82, 0xfff80080
	s_addc_u32 s7, s83, -1
	s_add_i32 s16, 0, 0x10000
	s_cmp_eq_u32 s92, 28
	s_cselect_b32 s23, s46, s7
	s_cselect_b32 s22, s48, s6
	s_cselect_b32 s7, s71, s81
	s_cselect_b32 s6, s73, s79
	s_add_i32 s58, 0, 0x14000
	v_add_u32_e32 v154, s16, v147
	v_add_u32_e32 v170, s58, v147
	ds_read_b128 v[138:141], v154
	ds_read_b128 v[142:145], v154 offset:1024
	ds_read_b128 v[150:153], v154 offset:2048
	ds_read_b128 v[154:157], v154 offset:3072
	ds_read_b128 v[158:161], v170
	ds_read_b128 v[162:165], v170 offset:1024
	ds_read_b128 v[166:169], v170 offset:2048
	ds_read_b128 v[170:173], v170 offset:3072
	v_lshl_add_u64 v[182:183], s[82:83], 0, v[134:135]
	s_add_i32 m0, s50, 0xc000
	ds_read_b128 v[174:177], v149
	ds_read_b128 v[178:181], v149 offset:1024
	ds_read_b128 v[186:189], v149 offset:2048
	ds_read_b128 v[190:193], v149 offset:3072
	ds_read_b128 v[194:197], v149 offset:4096
	ds_read_b128 v[222:225], v149 offset:5120
	ds_read_b128 v[226:229], v149 offset:6144
	ds_read_b128 v[230:233], v149 offset:7168
	global_load_lds_dwordx4 v[182:183], off
	v_lshl_add_u64 v[182:183], s[82:83], 0, v[136:137]
	s_add_i32 m0, s50, 0xe000
	s_nop 0
	global_load_lds_dwordx4 v[182:183], off
	s_waitcnt vmcnt(8)
	s_waitcnt lgkmcnt(0)
	s_barrier
	s_waitcnt lgkmcnt(0)
	v_mfma_f32_16x16x32_bf16 v[124:127], v[138:141], v[174:177], v[124:127]
	v_mfma_f32_16x16x32_bf16 v[120:123], v[150:153], v[174:177], v[120:123]
	v_mfma_f32_16x16x32_bf16 v[108:111], v[138:141], v[186:189], v[108:111]
	v_mfma_f32_16x16x32_bf16 v[104:107], v[150:153], v[186:189], v[104:107]
	v_mfma_f32_16x16x32_bf16 v[92:95], v[138:141], v[194:197], v[92:95]
	v_mfma_f32_16x16x32_bf16 v[88:91], v[150:153], v[194:197], v[88:91]
	v_mfma_f32_16x16x32_bf16 v[76:79], v[138:141], v[226:229], v[76:79]
	v_mfma_f32_16x16x32_bf16 v[72:75], v[150:153], v[226:229], v[72:75]
	v_mfma_f32_16x16x32_bf16 v[124:127], v[142:145], v[178:181], v[124:127]
	v_mfma_f32_16x16x32_bf16 v[120:123], v[154:157], v[178:181], v[120:123]
	v_mfma_f32_16x16x32_bf16 v[108:111], v[142:145], v[190:193], v[108:111]
	v_mfma_f32_16x16x32_bf16 v[104:107], v[154:157], v[190:193], v[104:107]
	v_mfma_f32_16x16x32_bf16 v[92:95], v[142:145], v[222:225], v[92:95]
	v_mfma_f32_16x16x32_bf16 v[88:91], v[154:157], v[222:225], v[88:91]
	v_mfma_f32_16x16x32_bf16 v[76:79], v[142:145], v[230:233], v[76:79]
	v_mfma_f32_16x16x32_bf16 v[72:75], v[154:157], v[230:233], v[72:75]
	v_mfma_f32_16x16x32_bf16 v[116:119], v[158:161], v[174:177], v[116:119]
	v_mfma_f32_16x16x32_bf16 v[112:115], v[166:169], v[174:177], v[112:115]
	v_mfma_f32_16x16x32_bf16 v[100:103], v[158:161], v[186:189], v[100:103]
	v_mfma_f32_16x16x32_bf16 v[96:99], v[166:169], v[186:189], v[96:99]
	v_mfma_f32_16x16x32_bf16 v[84:87], v[158:161], v[194:197], v[84:87]
	v_mfma_f32_16x16x32_bf16 v[80:83], v[166:169], v[194:197], v[80:83]
	v_mfma_f32_16x16x32_bf16 v[68:71], v[158:161], v[226:229], v[68:71]
	v_mfma_f32_16x16x32_bf16 v[64:67], v[166:169], v[226:229], v[64:67]
	v_mfma_f32_16x16x32_bf16 v[116:119], v[162:165], v[178:181], v[116:119]
	v_mfma_f32_16x16x32_bf16 v[112:115], v[170:173], v[178:181], v[112:115]
	v_mfma_f32_16x16x32_bf16 v[100:103], v[162:165], v[190:193], v[100:103]
	v_mfma_f32_16x16x32_bf16 v[96:99], v[170:173], v[190:193], v[96:99]
	v_mfma_f32_16x16x32_bf16 v[84:87], v[162:165], v[222:225], v[84:87]
	v_mfma_f32_16x16x32_bf16 v[80:83], v[170:173], v[222:225], v[80:83]
	v_mfma_f32_16x16x32_bf16 v[68:71], v[162:165], v[230:233], v[68:71]
	v_mfma_f32_16x16x32_bf16 v[64:67], v[170:173], v[230:233], v[64:67]
	s_barrier
	s_add_i32 s16, s16, s0
	v_lshl_add_u64 v[182:183], s[6:7], 0, v[184:185]
	s_mov_b32 m0, s16
	ds_read_b128 v[174:177], v149 offset:16384
	ds_read_b128 v[178:181], v149 offset:17408
	ds_read_b128 v[186:189], v149 offset:18432
	ds_read_b128 v[190:193], v149 offset:19456
	ds_read_b128 v[194:197], v149 offset:20480
	ds_read_b128 v[222:225], v149 offset:21504
	ds_read_b128 v[226:229], v149 offset:22528
	ds_read_b128 v[230:233], v149 offset:23552
	global_load_lds_dwordx4 v[182:183], off
	s_add_i32 m0, s16, 0x2000
	s_add_u32 s16, s6, 0x80000
	v_lshl_add_u64 v[234:235], s[6:7], 0, v[128:129]
	s_addc_u32 s17, s7, 0
	s_add_i32 s58, s58, s0
	global_load_lds_dwordx4 v[234:235], off
	v_lshl_add_u64 v[236:237], s[16:17], 0, v[184:185]
	s_mov_b32 m0, s58
	v_lshl_add_u64 v[238:239], s[22:23], 0, v[130:131]
	global_load_lds_dwordx4 v[236:237], off
	v_lshl_add_u64 v[236:237], s[16:17], 0, v[128:129]
	s_add_i32 m0, s58, 0x2000
	s_nop 0
	global_load_lds_dwordx4 v[236:237], off
	v_lshl_add_u64 v[236:237], s[22:23], 0, v[132:133]
	s_mov_b32 m0, s50
	s_nop 0
	global_load_lds_dwordx4 v[236:237], off
	s_mov_b32 m0, s52
	s_nop 0
	global_load_lds_dwordx4 v[238:239], off
	s_waitcnt vmcnt(8)
	s_waitcnt lgkmcnt(0)
	s_barrier
; #define PG8_STAGE(bufoff, gbase) PG8_STAGEV(bufoff, gbase, voff)
; #define PG8_LDA(dst, b, h) do { _Pragma("unroll") for (int m = 0; m < 4; ++m) _Pragma("unroll") for (int k = 0; k < 2; ++k) dst[m][k] = *(const LAS bf16x8*)(lds + PG8_SA(b, h) + aoff + m * 2048 + k * 1024); } while (0)
; #define PG8_LDB(dst, b, h) do { _Pragma("unroll") for (int n = 0; n < 2; ++n) _Pragma("unroll") for (int k = 0; k < 2; ++k) dst[n][k] = *(const LAS bf16x8*)(lds + PG8_SB(b, h) + boff + n * 2048 + k * 1024); } while (0)
; #define PG8_MMA(ai, bj, At, Bt) do { __builtin_amdgcn_s_setprio(1); _Pragma("unroll") for (int m = 0; m < 4; ++m) _Pragma("unroll") for (int n = 0; n < 2; ++n) _Pragma("unroll") for (int k = 0; k < 2; ++k) \
;         acc[ai][bj][m][n] = __builtin_amdgcn_mfma_f32_16x16x32_bf16(Bt[n][k], At[m][k], acc[ai][bj][m][n], 0, 0, 0); __builtin_amdgcn_s_setprio(0); } while (0)
; #define PG8_WAIT_V(n) asm volatile("s_waitcnt vmcnt(" #n ")" ::: "memory")
; #define PG8_WAIT_L(n) asm volatile("s_waitcnt lgkmcnt(" #n ")" ::: "memory")
; #define PG8_BAR __builtin_amdgcn_s_barrier()
; #define PG8_SCHED __builtin_amdgcn_sched_barrier(0)
; template <bool PERM, class Epi, class Sched>
; __device__ __forceinline__ void gemm_phase(LAS unsigned char* lds, const int K, const Sched& S, const Epi& E, const int wid0) {
;     ...
;             PG8_WAIT_V(8); PG8_WAIT_L(0); PG8_BAR; PG8_MMA(1, 0, At, B0); PG8_MMA(1, 1, At, B1); PG8_BAR; PG8_SCHED;
;             PG8_LDB(B0, 1, 0); PG8_LDB(B1, 1, 1); PG8_SCHED; PG8_LDA(At, 1, 0); PG8_STAGE(PG8_SA(0, 1), a2 + hstep);
;             PG8_WAIT_V(8); PG8_WAIT_L(0); PG8_BAR; PG8_MMA(0, 0, At, B0); PG8_MMA(0, 1, At, B1); PG8_BAR; PG8_SCHED;
	s_waitcnt lgkmcnt(0)
	v_mfma_f32_16x16x32_bf16 v[60:63], v[138:141], v[174:177], v[60:63]
	v_mfma_f32_16x16x32_bf16 v[56:59], v[150:153], v[174:177], v[56:59]
	v_mfma_f32_16x16x32_bf16 v[44:47], v[138:141], v[186:189], v[44:47]
	v_mfma_f32_16x16x32_bf16 v[40:43], v[150:153], v[186:189], v[40:43]
	v_mfma_f32_16x16x32_bf16 v[28:31], v[138:141], v[194:197], v[28:31]
	v_mfma_f32_16x16x32_bf16 v[24:27], v[150:153], v[194:197], v[24:27]
	v_mfma_f32_16x16x32_bf16 v[12:15], v[138:141], v[226:229], v[12:15]
	v_mfma_f32_16x16x32_bf16 v[8:11], v[150:153], v[226:229], v[8:11]
	v_mfma_f32_16x16x32_bf16 v[60:63], v[142:145], v[178:181], v[60:63]
	v_mfma_f32_16x16x32_bf16 v[56:59], v[154:157], v[178:181], v[56:59]
	v_mfma_f32_16x16x32_bf16 v[44:47], v[142:145], v[190:193], v[44:47]
	v_mfma_f32_16x16x32_bf16 v[40:43], v[154:157], v[190:193], v[40:43]
	v_mfma_f32_16x16x32_bf16 v[28:31], v[142:145], v[222:225], v[28:31]
	v_mfma_f32_16x16x32_bf16 v[24:27], v[154:157], v[222:225], v[24:27]
	v_mfma_f32_16x16x32_bf16 v[12:15], v[142:145], v[230:233], v[12:15]
	v_mfma_f32_16x16x32_bf16 v[8:11], v[154:157], v[230:233], v[8:11]
	v_mfma_f32_16x16x32_bf16 v[52:55], v[158:161], v[174:177], v[52:55]
	v_mfma_f32_16x16x32_bf16 v[48:51], v[166:169], v[174:177], v[48:51]
	v_mfma_f32_16x16x32_bf16 v[36:39], v[158:161], v[186:189], v[36:39]
	v_mfma_f32_16x16x32_bf16 v[32:35], v[166:169], v[186:189], v[32:35]
	v_mfma_f32_16x16x32_bf16 v[20:23], v[158:161], v[194:197], v[20:23]
	v_mfma_f32_16x16x32_bf16 v[16:19], v[166:169], v[194:197], v[16:19]
	v_mfma_f32_16x16x32_bf16 v[4:7], v[158:161], v[226:229], v[4:7]
	v_mfma_f32_16x16x32_bf16 v[0:3], v[166:169], v[226:229], v[0:3]
	v_mfma_f32_16x16x32_bf16 v[52:55], v[162:165], v[178:181], v[52:55]
	v_mfma_f32_16x16x32_bf16 v[48:51], v[170:173], v[178:181], v[48:51]
	v_mfma_f32_16x16x32_bf16 v[36:39], v[162:165], v[190:193], v[36:39]
	v_mfma_f32_16x16x32_bf16 v[32:35], v[170:173], v[190:193], v[32:35]
	v_mfma_f32_16x16x32_bf16 v[20:23], v[162:165], v[222:225], v[20:23]
	v_mfma_f32_16x16x32_bf16 v[16:19], v[170:173], v[222:225], v[16:19]
	v_mfma_f32_16x16x32_bf16 v[4:7], v[162:165], v[230:233], v[4:7]
	v_mfma_f32_16x16x32_bf16 v[0:3], v[170:173], v[230:233], v[0:3]
	s_barrier
	s_add_i32 s58, 0, 0x18000
	s_add_i32 s59, 0, 0x1c000
	v_add_u32_e32 v154, s58, v147
	v_add_u32_e32 v170, s59, v147
	ds_read_b128 v[138:141], v154
	ds_read_b128 v[142:145], v154 offset:1024
	ds_read_b128 v[150:153], v154 offset:2048
	ds_read_b128 v[154:157], v154 offset:3072
	ds_read_b128 v[158:161], v170
	ds_read_b128 v[162:165], v170 offset:1024
	ds_read_b128 v[166:169], v170 offset:2048
	ds_read_b128 v[170:173], v170 offset:3072
	s_add_u32 s16, s22, 0x80000
	s_addc_u32 s17, s23, 0
	s_mov_b32 m0, s53
	v_lshl_add_u64 v[240:241], s[16:17], 0, v[132:133]
	ds_read_b128 v[174:177], v149 offset:32768
	ds_read_b128 v[178:181], v149 offset:33792
	ds_read_b128 v[186:189], v149 offset:34816
	ds_read_b128 v[190:193], v149 offset:35840
	ds_read_b128 v[194:197], v149 offset:36864
	ds_read_b128 v[222:225], v149 offset:37888
	ds_read_b128 v[226:229], v149 offset:38912
	ds_read_b128 v[230:233], v149 offset:39936
	global_load_lds_dwordx4 v[240:241], off
	v_lshl_add_u64 v[240:241], s[16:17], 0, v[130:131]
	s_mov_b32 m0, s54
	s_nop 0
	global_load_lds_dwordx4 v[240:241], off
	s_waitcnt vmcnt(8)
	s_waitcnt lgkmcnt(0)
	s_barrier
	s_waitcnt lgkmcnt(0)
	v_mfma_f32_16x16x32_bf16 v[124:127], v[138:141], v[174:177], v[124:127]
	v_mfma_f32_16x16x32_bf16 v[120:123], v[150:153], v[174:177], v[120:123]
	v_mfma_f32_16x16x32_bf16 v[108:111], v[138:141], v[186:189], v[108:111]
	v_mfma_f32_16x16x32_bf16 v[104:107], v[150:153], v[186:189], v[104:107]
	v_mfma_f32_16x16x32_bf16 v[92:95], v[138:141], v[194:197], v[92:95]
	v_mfma_f32_16x16x32_bf16 v[88:91], v[150:153], v[194:197], v[88:91]
	v_mfma_f32_16x16x32_bf16 v[76:79], v[138:141], v[226:229], v[76:79]
	v_mfma_f32_16x16x32_bf16 v[72:75], v[150:153], v[226:229], v[72:75]
	v_mfma_f32_16x16x32_bf16 v[124:127], v[142:145], v[178:181], v[124:127]
	v_mfma_f32_16x16x32_bf16 v[120:123], v[154:157], v[178:181], v[120:123]
	v_mfma_f32_16x16x32_bf16 v[108:111], v[142:145], v[190:193], v[108:111]
	v_mfma_f32_16x16x32_bf16 v[104:107], v[154:157], v[190:193], v[104:107]
	v_mfma_f32_16x16x32_bf16 v[92:95], v[142:145], v[222:225], v[92:95]
	v_mfma_f32_16x16x32_bf16 v[88:91], v[154:157], v[222:225], v[88:91]
	v_mfma_f32_16x16x32_bf16 v[76:79], v[142:145], v[230:233], v[76:79]
	v_mfma_f32_16x16x32_bf16 v[72:75], v[154:157], v[230:233], v[72:75]
	v_mfma_f32_16x16x32_bf16 v[116:119], v[158:161], v[174:177], v[116:119]
	v_mfma_f32_16x16x32_bf16 v[112:115], v[166:169], v[174:177], v[112:115]
	v_mfma_f32_16x16x32_bf16 v[100:103], v[158:161], v[186:189], v[100:103]
	v_mfma_f32_16x16x32_bf16 v[96:99], v[166:169], v[186:189], v[96:99]
	v_mfma_f32_16x16x32_bf16 v[84:87], v[158:161], v[194:197], v[84:87]
	v_mfma_f32_16x16x32_bf16 v[80:83], v[166:169], v[194:197], v[80:83]
	v_mfma_f32_16x16x32_bf16 v[68:71], v[158:161], v[226:229], v[68:71]
	v_mfma_f32_16x16x32_bf16 v[64:67], v[166:169], v[226:229], v[64:67]
	v_mfma_f32_16x16x32_bf16 v[116:119], v[162:165], v[178:181], v[116:119]
	v_mfma_f32_16x16x32_bf16 v[112:115], v[170:173], v[178:181], v[112:115]
	v_mfma_f32_16x16x32_bf16 v[100:103], v[162:165], v[190:193], v[100:103]
	v_mfma_f32_16x16x32_bf16 v[96:99], v[170:173], v[190:193], v[96:99]
	v_mfma_f32_16x16x32_bf16 v[84:87], v[162:165], v[222:225], v[84:87]
	v_mfma_f32_16x16x32_bf16 v[80:83], v[170:173], v[222:225], v[80:83]
	v_mfma_f32_16x16x32_bf16 v[68:71], v[162:165], v[230:233], v[68:71]
	v_mfma_f32_16x16x32_bf16 v[64:67], v[170:173], v[230:233], v[64:67]
	s_barrier
; #define PG8_STAGE(bufoff, gbase) PG8_STAGEV(bufoff, gbase, voff)
; #define PG8_STAGEB(bufoff, gbase) PG8_STAGEV(bufoff, gbase, voffB)
; #define PG8_LDA(dst, b, h) do { _Pragma("unroll") for (int m = 0; m < 4; ++m) _Pragma("unroll") for (int k = 0; k < 2; ++k) dst[m][k] = *(const LAS bf16x8*)(lds + PG8_SA(b, h) + aoff + m * 2048 + k * 1024); } while (0)
; #define PG8_MMA(ai, bj, At, Bt) do { __builtin_amdgcn_s_setprio(1); _Pragma("unroll") for (int m = 0; m < 4; ++m) _Pragma("unroll") for (int n = 0; n < 2; ++n) _Pragma("unroll") for (int k = 0; k < 2; ++k) \
;         acc[ai][bj][m][n] = __builtin_amdgcn_mfma_f32_16x16x32_bf16(Bt[n][k], At[m][k], acc[ai][bj][m][n], 0, 0, 0); __builtin_amdgcn_s_setprio(0); } while (0)
; #define PG8_WAIT_V(n) asm volatile("s_waitcnt vmcnt(" #n ")" ::: "memory")
; #define PG8_WAIT_L(n) asm volatile("s_waitcnt lgkmcnt(" #n ")" ::: "memory")
; #define PG8_BAR __builtin_amdgcn_s_barrier()
; #define PG8_SCHED __builtin_amdgcn_sched_barrier(0)
; template <bool PERM, class Epi, class Sched>
; __device__ __forceinline__ void gemm_phase(LAS unsigned char* lds, const int K, const Sched& S, const Epi& E, const int wid0) {
;     ...
;             PG8_LDA(At, 1, 1); PG8_STAGEB(PG8_SB(1, 0), b3); PG8_STAGEB(PG8_SB(1, 1), b3 + hstep); PG8_STAGE(PG8_SA(1, 0), a3);
;             PG8_WAIT_V(8); PG8_WAIT_L(0); PG8_BAR; PG8_MMA(1, 0, At, B0); PG8_MMA(1, 1, At, B1); PG8_BAR; PG8_SCHED;
;         }
	s_add_i32 s16, s58, s0
	v_lshl_add_u64 v[182:183], v[182:183], 0, s[42:43]
	s_mov_b32 m0, s16
	ds_read_b128 v[174:177], v149 offset:49152
	ds_read_b128 v[178:181], v149 offset:50176
	ds_read_b128 v[186:189], v149 offset:51200
	ds_read_b128 v[190:193], v149 offset:52224
	ds_read_b128 v[194:197], v149 offset:53248
	ds_read_b128 v[222:225], v149 offset:54272
	ds_read_b128 v[226:229], v149 offset:55296
	ds_read_b128 v[230:233], v149 offset:56320
	global_load_lds_dwordx4 v[182:183], off
	s_add_i32 m0, s16, 0x2000
	s_add_u32 s6, s6, 0x80080
	v_lshl_add_u64 v[182:183], v[234:235], 0, s[42:43]
	s_addc_u32 s7, s7, 0
	s_add_i32 s16, s59, s0
	global_load_lds_dwordx4 v[182:183], off
	v_lshl_add_u64 v[182:183], s[6:7], 0, v[184:185]
	s_mov_b32 m0, s16
	s_nop 0
	global_load_lds_dwordx4 v[182:183], off
	v_lshl_add_u64 v[182:183], s[6:7], 0, v[128:129]
	s_add_i32 m0, s16, 0x2000
	s_nop 0
	global_load_lds_dwordx4 v[182:183], off
	v_lshl_add_u64 v[182:183], v[236:237], 0, s[42:43]
	s_mov_b32 m0, s55
	s_nop 0
	global_load_lds_dwordx4 v[182:183], off
	v_lshl_add_u64 v[182:183], v[238:239], 0, s[42:43]
	s_mov_b32 m0, s66
	s_nop 0
	global_load_lds_dwordx4 v[182:183], off
	s_waitcnt vmcnt(8)
	s_waitcnt lgkmcnt(0)
	s_barrier
	s_waitcnt lgkmcnt(0)
	v_mfma_f32_16x16x32_bf16 v[60:63], v[138:141], v[174:177], v[60:63]
	v_mfma_f32_16x16x32_bf16 v[56:59], v[150:153], v[174:177], v[56:59]
	v_mfma_f32_16x16x32_bf16 v[44:47], v[138:141], v[186:189], v[44:47]
	v_mfma_f32_16x16x32_bf16 v[40:43], v[150:153], v[186:189], v[40:43]
	v_mfma_f32_16x16x32_bf16 v[28:31], v[138:141], v[194:197], v[28:31]
	v_mfma_f32_16x16x32_bf16 v[24:27], v[150:153], v[194:197], v[24:27]
	v_mfma_f32_16x16x32_bf16 v[12:15], v[138:141], v[226:229], v[12:15]
	v_mfma_f32_16x16x32_bf16 v[8:11], v[150:153], v[226:229], v[8:11]
	v_mfma_f32_16x16x32_bf16 v[60:63], v[142:145], v[178:181], v[60:63]
	v_mfma_f32_16x16x32_bf16 v[56:59], v[154:157], v[178:181], v[56:59]
	v_mfma_f32_16x16x32_bf16 v[44:47], v[142:145], v[190:193], v[44:47]
	v_mfma_f32_16x16x32_bf16 v[40:43], v[154:157], v[190:193], v[40:43]
	v_mfma_f32_16x16x32_bf16 v[28:31], v[142:145], v[222:225], v[28:31]
	v_mfma_f32_16x16x32_bf16 v[24:27], v[154:157], v[222:225], v[24:27]
	v_mfma_f32_16x16x32_bf16 v[12:15], v[142:145], v[230:233], v[12:15]
	v_mfma_f32_16x16x32_bf16 v[8:11], v[154:157], v[230:233], v[8:11]
	v_mfma_f32_16x16x32_bf16 v[52:55], v[158:161], v[174:177], v[52:55]
	v_mfma_f32_16x16x32_bf16 v[48:51], v[166:169], v[174:177], v[48:51]
	v_mfma_f32_16x16x32_bf16 v[36:39], v[158:161], v[186:189], v[36:39]
	v_mfma_f32_16x16x32_bf16 v[32:35], v[166:169], v[186:189], v[32:35]
	v_mfma_f32_16x16x32_bf16 v[20:23], v[158:161], v[194:197], v[20:23]
	v_mfma_f32_16x16x32_bf16 v[16:19], v[166:169], v[194:197], v[16:19]
	v_mfma_f32_16x16x32_bf16 v[4:7], v[158:161], v[226:229], v[4:7]
	v_mfma_f32_16x16x32_bf16 v[0:3], v[166:169], v[226:229], v[0:3]
	v_mfma_f32_16x16x32_bf16 v[52:55], v[162:165], v[178:181], v[52:55]
	v_mfma_f32_16x16x32_bf16 v[48:51], v[170:173], v[178:181], v[48:51]
	v_mfma_f32_16x16x32_bf16 v[36:39], v[162:165], v[190:193], v[36:39]
	v_mfma_f32_16x16x32_bf16 v[32:35], v[170:173], v[190:193], v[32:35]
	v_mfma_f32_16x16x32_bf16 v[20:23], v[162:165], v[222:225], v[20:23]
	v_mfma_f32_16x16x32_bf16 v[16:19], v[170:173], v[222:225], v[16:19]
	v_mfma_f32_16x16x32_bf16 v[4:7], v[162:165], v[230:233], v[4:7]
	v_mfma_f32_16x16x32_bf16 v[0:3], v[170:173], v[230:233], v[0:3]
	s_barrier
	s_add_i32 s92, s92, 2
	s_add_u32 s82, s82, 0x100
	s_addc_u32 s83, s83, 0
	s_add_u32 s79, s79, 0x100
	s_addc_u32 s81, s81, 0
	s_cmp_gt_u32 s92, 29
	s_cbranch_scc0 .LBB0_667
	s_and_b64 vcc, exec, s[68:69]
	s_cbranch_vccz .LBB0_670
	s_barrier

; #define PG8_STAGE(bufoff, gbase) PG8_STAGEV(bufoff, gbase, voff)
; #define PG8_STAGEB(bufoff, gbase) PG8_STAGEV(bufoff, gbase, voffB)
; #define PG8_LDA(dst, b, h) do { _Pragma("unroll") for (int m = 0; m < 4; ++m) _Pragma("unroll") for (int k = 0; k < 2; ++k) dst[m][k] = *(const LAS bf16x8*)(lds + PG8_SA(b, h) + aoff + m * 2048 + k * 1024); } while (0)
; #define PG8_LDB(dst, b, h) do { _Pragma("unroll") for (int n = 0; n < 2; ++n) _Pragma("unroll") for (int k = 0; k < 2; ++k) dst[n][k] = *(const LAS bf16x8*)(lds + PG8_SB(b, h) + boff + n * 2048 + k * 1024); } while (0)
; #define PG8_MMA(ai, bj, At, Bt) do { __builtin_amdgcn_s_setprio(1); _Pragma("unroll") for (int m = 0; m < 4; ++m) _Pragma("unroll") for (int n = 0; n < 2; ++n) _Pragma("unroll") for (int k = 0; k < 2; ++k) \
;         acc[ai][bj][m][n] = __builtin_amdgcn_mfma_f32_16x16x32_bf16(Bt[n][k], At[m][k], acc[ai][bj][m][n], 0, 0, 0); __builtin_amdgcn_s_setprio(0); } while (0)
; #define PG8_WAIT_V(n) asm volatile("s_waitcnt vmcnt(" #n ")" ::: "memory")
; #define PG8_WAIT_L(n) asm volatile("s_waitcnt lgkmcnt(" #n ")" ::: "memory")
; #define PG8_BAR __builtin_amdgcn_s_barrier()
; #define PG8_SCHED __builtin_amdgcn_sched_barrier(0)
; template <bool PERM, class Epi, class Sched>
; __device__ __forceinline__ void gemm_phase(LAS unsigned char* lds, const int K, const Sched& S, const Epi& E, const int wid0) {
;     ...
;             const bool last = (t == nt - 2);
;             const char* a1 = cA + (size_t)(t + 1) * kstep;
;             const char* a2 = last ? nA : cA + (size_t)(t + 2) * kstep; const char* b2 = last ? nB : cB + (size_t)(t + 2) * kstep;
;             const char* a3 = a2 + kstep; const char* b3 = b2 + kstep;
;             PG8_LDB(B0, 0, 0); PG8_LDB(B1, 0, 1); PG8_SCHED; PG8_LDA(At, 0, 0); PG8_STAGE(PG8_SA(1, 1), a1 + hstep);
;             PG8_WAIT_V(8); PG8_WAIT_L(0); PG8_BAR; PG8_MMA(0, 0, At, B0); PG8_MMA(0, 1, At, B1); PG8_BAR; PG8_SCHED;
;             PG8_LDA(At, 0, 1); PG8_STAGEB(PG8_SB(0, 0), b2); PG8_STAGEB(PG8_SB(0, 1), b2 + hstep); PG8_STAGE(PG8_SA(0, 0), a2);
.LBB0_735:
	s_add_u32 s16, s82, 0xfff80080
	s_addc_u32 s17, s83, -1
	s_add_i32 s58, 0, 0x10000
	s_cmp_eq_u32 vcc_lo, 28
	s_cselect_b32 s77, s73, s17
	s_cselect_b32 s76, s79, s16
	s_cselect_b32 s23, s71, s93
	s_cselect_b32 s22, s81, s92
	s_add_i32 s59, 0, 0x14000
	v_add_u32_e32 v124, s58, v159
	v_add_u32_e32 v170, s59, v159
	ds_read_b128 v[112:115], v124
	ds_read_b128 v[116:119], v124 offset:1024
	ds_read_b128 v[120:123], v124 offset:2048
	ds_read_b128 v[124:127], v124 offset:3072
	ds_read_b128 v[154:157], v170
	ds_read_b128 v[162:165], v170 offset:1024
	ds_read_b128 v[166:169], v170 offset:2048
	ds_read_b128 v[170:173], v170 offset:3072
	v_lshl_add_u64 v[182:183], s[82:83], 0, v[150:151]
	s_add_i32 m0, s46, 0xc000
	ds_read_b128 v[174:177], v161
	ds_read_b128 v[178:181], v161 offset:1024
	ds_read_b128 v[186:189], v161 offset:2048
	ds_read_b128 v[190:193], v161 offset:3072
	ds_read_b128 v[194:197], v161 offset:4096
	ds_read_b128 v[222:225], v161 offset:5120
	ds_read_b128 v[226:229], v161 offset:6144
	ds_read_b128 v[230:233], v161 offset:7168
	global_load_lds_dwordx4 v[182:183], off
	v_lshl_add_u64 v[182:183], s[82:83], 0, v[152:153]
	s_add_i32 m0, s46, 0xe000
	s_nop 0
	global_load_lds_dwordx4 v[182:183], off
	s_waitcnt vmcnt(8)
	s_waitcnt lgkmcnt(0)
	s_barrier
	s_waitcnt lgkmcnt(0)
	v_mfma_f32_16x16x32_bf16 v[140:143], v[112:115], v[174:177], v[140:143]
	v_mfma_f32_16x16x32_bf16 v[136:139], v[120:123], v[174:177], v[136:139]
	v_mfma_f32_16x16x32_bf16 v[108:111], v[112:115], v[186:189], v[108:111]
	v_mfma_f32_16x16x32_bf16 v[104:107], v[120:123], v[186:189], v[104:107]
	v_mfma_f32_16x16x32_bf16 v[92:95], v[112:115], v[194:197], v[92:95]
	v_mfma_f32_16x16x32_bf16 v[88:91], v[120:123], v[194:197], v[88:91]
	v_mfma_f32_16x16x32_bf16 v[76:79], v[112:115], v[226:229], v[76:79]
	v_mfma_f32_16x16x32_bf16 v[72:75], v[120:123], v[226:229], v[72:75]
	v_mfma_f32_16x16x32_bf16 v[140:143], v[116:119], v[178:181], v[140:143]
	v_mfma_f32_16x16x32_bf16 v[136:139], v[124:127], v[178:181], v[136:139]
	v_mfma_f32_16x16x32_bf16 v[108:111], v[116:119], v[190:193], v[108:111]
	v_mfma_f32_16x16x32_bf16 v[104:107], v[124:127], v[190:193], v[104:107]
	v_mfma_f32_16x16x32_bf16 v[92:95], v[116:119], v[222:225], v[92:95]
	v_mfma_f32_16x16x32_bf16 v[88:91], v[124:127], v[222:225], v[88:91]
	v_mfma_f32_16x16x32_bf16 v[76:79], v[116:119], v[230:233], v[76:79]
	v_mfma_f32_16x16x32_bf16 v[72:75], v[124:127], v[230:233], v[72:75]
	v_mfma_f32_16x16x32_bf16 v[132:135], v[154:157], v[174:177], v[132:135]
	v_mfma_f32_16x16x32_bf16 v[128:131], v[166:169], v[174:177], v[128:131]
	v_mfma_f32_16x16x32_bf16 v[100:103], v[154:157], v[186:189], v[100:103]
	v_mfma_f32_16x16x32_bf16 v[96:99], v[166:169], v[186:189], v[96:99]
	v_mfma_f32_16x16x32_bf16 v[84:87], v[154:157], v[194:197], v[84:87]
	v_mfma_f32_16x16x32_bf16 v[80:83], v[166:169], v[194:197], v[80:83]
	v_mfma_f32_16x16x32_bf16 v[68:71], v[154:157], v[226:229], v[68:71]
	v_mfma_f32_16x16x32_bf16 v[64:67], v[166:169], v[226:229], v[64:67]
	v_mfma_f32_16x16x32_bf16 v[132:135], v[162:165], v[178:181], v[132:135]
	v_mfma_f32_16x16x32_bf16 v[128:131], v[170:173], v[178:181], v[128:131]
	v_mfma_f32_16x16x32_bf16 v[100:103], v[162:165], v[190:193], v[100:103]
	v_mfma_f32_16x16x32_bf16 v[96:99], v[170:173], v[190:193], v[96:99]
	v_mfma_f32_16x16x32_bf16 v[84:87], v[162:165], v[222:225], v[84:87]
	v_mfma_f32_16x16x32_bf16 v[80:83], v[170:173], v[222:225], v[80:83]
	v_mfma_f32_16x16x32_bf16 v[68:71], v[162:165], v[230:233], v[68:71]
	v_mfma_f32_16x16x32_bf16 v[64:67], v[170:173], v[230:233], v[64:67]
	s_barrier
	s_add_i32 s16, s58, s0
	v_lshl_add_u64 v[182:183], s[22:23], 0, v[184:185]
	s_mov_b32 m0, s16
	ds_read_b128 v[174:177], v161 offset:16384
	ds_read_b128 v[178:181], v161 offset:17408
	ds_read_b128 v[186:189], v161 offset:18432
	ds_read_b128 v[190:193], v161 offset:19456
	ds_read_b128 v[194:197], v161 offset:20480
	ds_read_b128 v[222:225], v161 offset:21504
	ds_read_b128 v[226:229], v161 offset:22528
	ds_read_b128 v[230:233], v161 offset:23552
	global_load_lds_dwordx4 v[182:183], off
	s_add_i32 m0, s16, 0x2000
	s_add_u32 s16, s22, 0x80000
	v_lshl_add_u64 v[234:235], s[22:23], 0, v[144:145]
	s_addc_u32 s17, s23, 0
	s_add_i32 s58, s59, s0
	global_load_lds_dwordx4 v[234:235], off
	v_lshl_add_u64 v[236:237], s[16:17], 0, v[184:185]
	s_mov_b32 m0, s58
	v_lshl_add_u64 v[238:239], s[76:77], 0, v[146:147]
	global_load_lds_dwordx4 v[236:237], off
	v_lshl_add_u64 v[236:237], s[16:17], 0, v[144:145]
	s_add_i32 m0, s58, 0x2000
	s_nop 0
	global_load_lds_dwordx4 v[236:237], off
	v_lshl_add_u64 v[236:237], s[76:77], 0, v[148:149]
	s_mov_b32 m0, s46
	s_nop 0
	global_load_lds_dwordx4 v[236:237], off
	s_mov_b32 m0, s48
	s_nop 0
	global_load_lds_dwordx4 v[238:239], off
	s_waitcnt vmcnt(8)
	s_waitcnt lgkmcnt(0)
	s_barrier
; #define PG8_STAGE(bufoff, gbase) PG8_STAGEV(bufoff, gbase, voff)
; #define PG8_LDA(dst, b, h) do { _Pragma("unroll") for (int m = 0; m < 4; ++m) _Pragma("unroll") for (int k = 0; k < 2; ++k) dst[m][k] = *(const LAS bf16x8*)(lds + PG8_SA(b, h) + aoff + m * 2048 + k * 1024); } while (0)
; #define PG8_LDB(dst, b, h) do { _Pragma("unroll") for (int n = 0; n < 2; ++n) _Pragma("unroll") for (int k = 0; k < 2; ++k) dst[n][k] = *(const LAS bf16x8*)(lds + PG8_SB(b, h) + boff + n * 2048 + k * 1024); } while (0)
; #define PG8_MMA(ai, bj, At, Bt) do { __builtin_amdgcn_s_setprio(1); _Pragma("unroll") for (int m = 0; m < 4; ++m) _Pragma("unroll") for (int n = 0; n < 2; ++n) _Pragma("unroll") for (int k = 0; k < 2; ++k) \
;         acc[ai][bj][m][n] = __builtin_amdgcn_mfma_f32_16x16x32_bf16(Bt[n][k], At[m][k], acc[ai][bj][m][n], 0, 0, 0); __builtin_amdgcn_s_setprio(0); } while (0)
; #define PG8_WAIT_V(n) asm volatile("s_waitcnt vmcnt(" #n ")" ::: "memory")
; #define PG8_WAIT_L(n) asm volatile("s_waitcnt lgkmcnt(" #n ")" ::: "memory")
; #define PG8_BAR __builtin_amdgcn_s_barrier()
; #define PG8_SCHED __builtin_amdgcn_sched_barrier(0)
; template <bool PERM, class Epi, class Sched>
; __device__ __forceinline__ void gemm_phase(LAS unsigned char* lds, const int K, const Sched& S, const Epi& E, const int wid0) {
;     ...
;             PG8_WAIT_V(8); PG8_WAIT_L(0); PG8_BAR; PG8_MMA(1, 0, At, B0); PG8_MMA(1, 1, At, B1); PG8_BAR; PG8_SCHED;
;             PG8_LDB(B0, 1, 0); PG8_LDB(B1, 1, 1); PG8_SCHED; PG8_LDA(At, 1, 0); PG8_STAGE(PG8_SA(0, 1), a2 + hstep);
;             PG8_WAIT_V(8); PG8_WAIT_L(0); PG8_BAR; PG8_MMA(0, 0, At, B0); PG8_MMA(0, 1, At, B1); PG8_BAR; PG8_SCHED;
	s_waitcnt lgkmcnt(0)
	v_mfma_f32_16x16x32_bf16 v[60:63], v[112:115], v[174:177], v[60:63]
	v_mfma_f32_16x16x32_bf16 v[56:59], v[120:123], v[174:177], v[56:59]
	v_mfma_f32_16x16x32_bf16 v[52:55], v[112:115], v[186:189], v[52:55]
	v_mfma_f32_16x16x32_bf16 v[44:47], v[120:123], v[186:189], v[44:47]
	v_mfma_f32_16x16x32_bf16 v[36:39], v[112:115], v[194:197], v[36:39]
	v_mfma_f32_16x16x32_bf16 v[28:31], v[120:123], v[194:197], v[28:31]
	v_mfma_f32_16x16x32_bf16 v[20:23], v[112:115], v[226:229], v[20:23]
	v_mfma_f32_16x16x32_bf16 v[12:15], v[120:123], v[226:229], v[12:15]
	v_mfma_f32_16x16x32_bf16 v[60:63], v[116:119], v[178:181], v[60:63]
	v_mfma_f32_16x16x32_bf16 v[56:59], v[124:127], v[178:181], v[56:59]
	v_mfma_f32_16x16x32_bf16 v[52:55], v[116:119], v[190:193], v[52:55]
	v_mfma_f32_16x16x32_bf16 v[44:47], v[124:127], v[190:193], v[44:47]
	v_mfma_f32_16x16x32_bf16 v[36:39], v[116:119], v[222:225], v[36:39]
	v_mfma_f32_16x16x32_bf16 v[28:31], v[124:127], v[222:225], v[28:31]
	v_mfma_f32_16x16x32_bf16 v[20:23], v[116:119], v[230:233], v[20:23]
	v_mfma_f32_16x16x32_bf16 v[12:15], v[124:127], v[230:233], v[12:15]
	v_mfma_f32_16x16x32_bf16 v[48:51], v[154:157], v[174:177], v[48:51]
	v_mfma_f32_16x16x32_bf16 v[40:43], v[166:169], v[174:177], v[40:43]
	v_mfma_f32_16x16x32_bf16 v[32:35], v[154:157], v[186:189], v[32:35]
	v_mfma_f32_16x16x32_bf16 v[24:27], v[166:169], v[186:189], v[24:27]
	v_mfma_f32_16x16x32_bf16 v[16:19], v[154:157], v[194:197], v[16:19]
	v_mfma_f32_16x16x32_bf16 v[8:11], v[166:169], v[194:197], v[8:11]
	v_mfma_f32_16x16x32_bf16 v[4:7], v[154:157], v[226:229], v[4:7]
	v_mfma_f32_16x16x32_bf16 v[0:3], v[166:169], v[226:229], v[0:3]
	v_mfma_f32_16x16x32_bf16 v[48:51], v[162:165], v[178:181], v[48:51]
	v_mfma_f32_16x16x32_bf16 v[40:43], v[170:173], v[178:181], v[40:43]
	v_mfma_f32_16x16x32_bf16 v[32:35], v[162:165], v[190:193], v[32:35]
	v_mfma_f32_16x16x32_bf16 v[24:27], v[170:173], v[190:193], v[24:27]
	v_mfma_f32_16x16x32_bf16 v[16:19], v[162:165], v[222:225], v[16:19]
	v_mfma_f32_16x16x32_bf16 v[8:11], v[170:173], v[222:225], v[8:11]
	v_mfma_f32_16x16x32_bf16 v[4:7], v[162:165], v[230:233], v[4:7]
	v_mfma_f32_16x16x32_bf16 v[0:3], v[170:173], v[230:233], v[0:3]
	s_barrier
	s_add_i32 s58, 0, 0x18000
	s_add_i32 s59, 0, 0x1c000
	v_add_u32_e32 v124, s58, v159
	v_add_u32_e32 v170, s59, v159
	ds_read_b128 v[112:115], v124
	ds_read_b128 v[116:119], v124 offset:1024
	ds_read_b128 v[120:123], v124 offset:2048
	ds_read_b128 v[124:127], v124 offset:3072
	ds_read_b128 v[154:157], v170
	ds_read_b128 v[162:165], v170 offset:1024
	ds_read_b128 v[166:169], v170 offset:2048
	ds_read_b128 v[170:173], v170 offset:3072
	s_add_u32 s16, s76, 0x80000
	s_addc_u32 s17, s77, 0
	s_mov_b32 m0, s50
	v_lshl_add_u64 v[240:241], s[16:17], 0, v[148:149]
	ds_read_b128 v[174:177], v161 offset:32768
	ds_read_b128 v[178:181], v161 offset:33792
	ds_read_b128 v[186:189], v161 offset:34816
	ds_read_b128 v[190:193], v161 offset:35840
	ds_read_b128 v[194:197], v161 offset:36864
	ds_read_b128 v[222:225], v161 offset:37888
	ds_read_b128 v[226:229], v161 offset:38912
	ds_read_b128 v[230:233], v161 offset:39936
	global_load_lds_dwordx4 v[240:241], off
	v_lshl_add_u64 v[240:241], s[16:17], 0, v[146:147]
	s_mov_b32 m0, s52
	s_nop 0
	global_load_lds_dwordx4 v[240:241], off
	s_waitcnt vmcnt(8)
	s_waitcnt lgkmcnt(0)
	s_barrier
	s_waitcnt lgkmcnt(0)
	v_mfma_f32_16x16x32_bf16 v[140:143], v[112:115], v[174:177], v[140:143]
	v_mfma_f32_16x16x32_bf16 v[136:139], v[120:123], v[174:177], v[136:139]
	v_mfma_f32_16x16x32_bf16 v[108:111], v[112:115], v[186:189], v[108:111]
	v_mfma_f32_16x16x32_bf16 v[104:107], v[120:123], v[186:189], v[104:107]
	v_mfma_f32_16x16x32_bf16 v[92:95], v[112:115], v[194:197], v[92:95]
	v_mfma_f32_16x16x32_bf16 v[88:91], v[120:123], v[194:197], v[88:91]
	v_mfma_f32_16x16x32_bf16 v[76:79], v[112:115], v[226:229], v[76:79]
	v_mfma_f32_16x16x32_bf16 v[72:75], v[120:123], v[226:229], v[72:75]
	v_mfma_f32_16x16x32_bf16 v[140:143], v[116:119], v[178:181], v[140:143]
	v_mfma_f32_16x16x32_bf16 v[136:139], v[124:127], v[178:181], v[136:139]
	v_mfma_f32_16x16x32_bf16 v[108:111], v[116:119], v[190:193], v[108:111]
	v_mfma_f32_16x16x32_bf16 v[104:107], v[124:127], v[190:193], v[104:107]
	v_mfma_f32_16x16x32_bf16 v[92:95], v[116:119], v[222:225], v[92:95]
	v_mfma_f32_16x16x32_bf16 v[88:91], v[124:127], v[222:225], v[88:91]
	v_mfma_f32_16x16x32_bf16 v[76:79], v[116:119], v[230:233], v[76:79]
	v_mfma_f32_16x16x32_bf16 v[72:75], v[124:127], v[230:233], v[72:75]
	v_mfma_f32_16x16x32_bf16 v[132:135], v[154:157], v[174:177], v[132:135]
	v_mfma_f32_16x16x32_bf16 v[128:131], v[166:169], v[174:177], v[128:131]
	v_mfma_f32_16x16x32_bf16 v[100:103], v[154:157], v[186:189], v[100:103]
	v_mfma_f32_16x16x32_bf16 v[96:99], v[166:169], v[186:189], v[96:99]
	v_mfma_f32_16x16x32_bf16 v[84:87], v[154:157], v[194:197], v[84:87]
	v_mfma_f32_16x16x32_bf16 v[80:83], v[166:169], v[194:197], v[80:83]
	v_mfma_f32_16x16x32_bf16 v[68:71], v[154:157], v[226:229], v[68:71]
	v_mfma_f32_16x16x32_bf16 v[64:67], v[166:169], v[226:229], v[64:67]
	v_mfma_f32_16x16x32_bf16 v[132:135], v[162:165], v[178:181], v[132:135]
	v_mfma_f32_16x16x32_bf16 v[128:131], v[170:173], v[178:181], v[128:131]
	v_mfma_f32_16x16x32_bf16 v[100:103], v[162:165], v[190:193], v[100:103]
	v_mfma_f32_16x16x32_bf16 v[96:99], v[170:173], v[190:193], v[96:99]
	v_mfma_f32_16x16x32_bf16 v[84:87], v[162:165], v[222:225], v[84:87]
	v_mfma_f32_16x16x32_bf16 v[80:83], v[170:173], v[222:225], v[80:83]
	v_mfma_f32_16x16x32_bf16 v[68:71], v[162:165], v[230:233], v[68:71]
	v_mfma_f32_16x16x32_bf16 v[64:67], v[170:173], v[230:233], v[64:67]
	s_barrier
; #define PG8_STAGE(bufoff, gbase) PG8_STAGEV(bufoff, gbase, voff)
; #define PG8_STAGEB(bufoff, gbase) PG8_STAGEV(bufoff, gbase, voffB)
; #define PG8_LDA(dst, b, h) do { _Pragma("unroll") for (int m = 0; m < 4; ++m) _Pragma("unroll") for (int k = 0; k < 2; ++k) dst[m][k] = *(const LAS bf16x8*)(lds + PG8_SA(b, h) + aoff + m * 2048 + k * 1024); } while (0)
; #define PG8_MMA(ai, bj, At, Bt) do { __builtin_amdgcn_s_setprio(1); _Pragma("unroll") for (int m = 0; m < 4; ++m) _Pragma("unroll") for (int n = 0; n < 2; ++n) _Pragma("unroll") for (int k = 0; k < 2; ++k) \
;         acc[ai][bj][m][n] = __builtin_amdgcn_mfma_f32_16x16x32_bf16(Bt[n][k], At[m][k], acc[ai][bj][m][n], 0, 0, 0); __builtin_amdgcn_s_setprio(0); } while (0)
; #define PG8_WAIT_V(n) asm volatile("s_waitcnt vmcnt(" #n ")" ::: "memory")
; #define PG8_WAIT_L(n) asm volatile("s_waitcnt lgkmcnt(" #n ")" ::: "memory")
; #define PG8_BAR __builtin_amdgcn_s_barrier()
; #define PG8_SCHED __builtin_amdgcn_sched_barrier(0)
; template <bool PERM, class Epi, class Sched>
; __device__ __forceinline__ void gemm_phase(LAS unsigned char* lds, const int K, const Sched& S, const Epi& E, const int wid0) {
;     ...
;             PG8_LDA(At, 1, 1); PG8_STAGEB(PG8_SB(1, 0), b3); PG8_STAGEB(PG8_SB(1, 1), b3 + hstep); PG8_STAGE(PG8_SA(1, 0), a3);
;             PG8_WAIT_V(8); PG8_WAIT_L(0); PG8_BAR; PG8_MMA(1, 0, At, B0); PG8_MMA(1, 1, At, B1); PG8_BAR; PG8_SCHED;
;         }
	s_add_i32 s16, s58, s0
	v_lshl_add_u64 v[182:183], v[182:183], 0, s[42:43]
	s_mov_b32 m0, s16
	ds_read_b128 v[174:177], v161 offset:49152
	ds_read_b128 v[178:181], v161 offset:50176
	ds_read_b128 v[186:189], v161 offset:51200
	ds_read_b128 v[190:193], v161 offset:52224
	ds_read_b128 v[194:197], v161 offset:53248
	ds_read_b128 v[222:225], v161 offset:54272
	ds_read_b128 v[226:229], v161 offset:55296
	ds_read_b128 v[230:233], v161 offset:56320
	global_load_lds_dwordx4 v[182:183], off
	s_add_i32 m0, s16, 0x2000
	s_add_u32 s16, s22, 0x80080
	v_lshl_add_u64 v[182:183], v[234:235], 0, s[42:43]
	s_addc_u32 s17, s23, 0
	s_add_i32 s22, s59, s0
	global_load_lds_dwordx4 v[182:183], off
	v_lshl_add_u64 v[182:183], s[16:17], 0, v[184:185]
	s_mov_b32 m0, s22
	s_nop 0
	global_load_lds_dwordx4 v[182:183], off
	v_lshl_add_u64 v[182:183], s[16:17], 0, v[144:145]
	s_add_i32 m0, s22, 0x2000
	s_nop 0
	global_load_lds_dwordx4 v[182:183], off
	v_lshl_add_u64 v[182:183], v[236:237], 0, s[42:43]
	s_mov_b32 m0, s55
	s_nop 0
	global_load_lds_dwordx4 v[182:183], off
	v_lshl_add_u64 v[182:183], v[238:239], 0, s[42:43]
	s_mov_b32 m0, s66
	s_nop 0
	global_load_lds_dwordx4 v[182:183], off
	s_waitcnt vmcnt(8)
	s_waitcnt lgkmcnt(0)
	s_barrier
	s_waitcnt lgkmcnt(0)
	v_mfma_f32_16x16x32_bf16 v[60:63], v[112:115], v[174:177], v[60:63]
	v_mfma_f32_16x16x32_bf16 v[56:59], v[120:123], v[174:177], v[56:59]
	v_mfma_f32_16x16x32_bf16 v[52:55], v[112:115], v[186:189], v[52:55]
	v_mfma_f32_16x16x32_bf16 v[44:47], v[120:123], v[186:189], v[44:47]
	v_mfma_f32_16x16x32_bf16 v[36:39], v[112:115], v[194:197], v[36:39]
	v_mfma_f32_16x16x32_bf16 v[28:31], v[120:123], v[194:197], v[28:31]
	v_mfma_f32_16x16x32_bf16 v[20:23], v[112:115], v[226:229], v[20:23]
	v_mfma_f32_16x16x32_bf16 v[12:15], v[120:123], v[226:229], v[12:15]
	v_mfma_f32_16x16x32_bf16 v[60:63], v[116:119], v[178:181], v[60:63]
	v_mfma_f32_16x16x32_bf16 v[56:59], v[124:127], v[178:181], v[56:59]
	v_mfma_f32_16x16x32_bf16 v[52:55], v[116:119], v[190:193], v[52:55]
	v_mfma_f32_16x16x32_bf16 v[44:47], v[124:127], v[190:193], v[44:47]
	v_mfma_f32_16x16x32_bf16 v[36:39], v[116:119], v[222:225], v[36:39]
	v_mfma_f32_16x16x32_bf16 v[28:31], v[124:127], v[222:225], v[28:31]
	v_mfma_f32_16x16x32_bf16 v[20:23], v[116:119], v[230:233], v[20:23]
	v_mfma_f32_16x16x32_bf16 v[12:15], v[124:127], v[230:233], v[12:15]
	v_mfma_f32_16x16x32_bf16 v[48:51], v[154:157], v[174:177], v[48:51]
	v_mfma_f32_16x16x32_bf16 v[40:43], v[166:169], v[174:177], v[40:43]
	v_mfma_f32_16x16x32_bf16 v[32:35], v[154:157], v[186:189], v[32:35]
	v_mfma_f32_16x16x32_bf16 v[24:27], v[166:169], v[186:189], v[24:27]
	v_mfma_f32_16x16x32_bf16 v[16:19], v[154:157], v[194:197], v[16:19]
	v_mfma_f32_16x16x32_bf16 v[8:11], v[166:169], v[194:197], v[8:11]
	v_mfma_f32_16x16x32_bf16 v[4:7], v[154:157], v[226:229], v[4:7]
	v_mfma_f32_16x16x32_bf16 v[0:3], v[166:169], v[226:229], v[0:3]
	v_mfma_f32_16x16x32_bf16 v[48:51], v[162:165], v[178:181], v[48:51]
	v_mfma_f32_16x16x32_bf16 v[40:43], v[170:173], v[178:181], v[40:43]
	v_mfma_f32_16x16x32_bf16 v[32:35], v[162:165], v[190:193], v[32:35]
	v_mfma_f32_16x16x32_bf16 v[24:27], v[170:173], v[190:193], v[24:27]
	v_mfma_f32_16x16x32_bf16 v[16:19], v[162:165], v[222:225], v[16:19]
	v_mfma_f32_16x16x32_bf16 v[8:11], v[170:173], v[222:225], v[8:11]
	v_mfma_f32_16x16x32_bf16 v[4:7], v[162:165], v[230:233], v[4:7]
	v_mfma_f32_16x16x32_bf16 v[0:3], v[170:173], v[230:233], v[0:3]
	s_barrier
	s_add_i32 vcc_lo, vcc_lo, 2
	s_add_u32 s82, s82, 0x100
	s_addc_u32 s83, s83, 0
	s_add_u32 s92, s92, 0x100
	s_addc_u32 s93, s93, 0
	s_cmp_gt_u32 vcc_lo, 29
	s_cbranch_scc0 .LBB0_735
	s_and_b64 vcc, exec, s[68:69]
	s_cbranch_vccz .LBB0_738
	s_barrier

; #define PG8_STAGE(bufoff, gbase) PG8_STAGEV(bufoff, gbase, voff)
; #define PG8_STAGEB(bufoff, gbase) PG8_STAGEV(bufoff, gbase, voffB)
; #define PG8_LDA(dst, b, h) do { _Pragma("unroll") for (int m = 0; m < 4; ++m) _Pragma("unroll") for (int k = 0; k < 2; ++k) dst[m][k] = *(const LAS bf16x8*)(lds + PG8_SA(b, h) + aoff + m * 2048 + k * 1024); } while (0)
; #define PG8_LDB(dst, b, h) do { _Pragma("unroll") for (int n = 0; n < 2; ++n) _Pragma("unroll") for (int k = 0; k < 2; ++k) dst[n][k] = *(const LAS bf16x8*)(lds + PG8_SB(b, h) + boff + n * 2048 + k * 1024); } while (0)
; #define PG8_MMA(ai, bj, At, Bt) do { __builtin_amdgcn_s_setprio(1); _Pragma("unroll") for (int m = 0; m < 4; ++m) _Pragma("unroll") for (int n = 0; n < 2; ++n) _Pragma("unroll") for (int k = 0; k < 2; ++k) \
;         acc[ai][bj][m][n] = __builtin_amdgcn_mfma_f32_16x16x32_bf16(Bt[n][k], At[m][k], acc[ai][bj][m][n], 0, 0, 0); __builtin_amdgcn_s_setprio(0); } while (0)
; #define PG8_WAIT_V(n) asm volatile("s_waitcnt vmcnt(" #n ")" ::: "memory")
; #define PG8_WAIT_L(n) asm volatile("s_waitcnt lgkmcnt(" #n ")" ::: "memory")
; #define PG8_BAR __builtin_amdgcn_s_barrier()
; #define PG8_SCHED __builtin_amdgcn_sched_barrier(0)
; template <bool PERM, class Epi, class Sched>
; __device__ __forceinline__ void gemm_phase(LAS unsigned char* lds, const int K, const Sched& S, const Epi& E, const int wid0) {
;     ...
;             const bool last = (t == nt - 2);
;             const char* a1 = cA + (size_t)(t + 1) * kstep;
;             const char* a2 = last ? nA : cA + (size_t)(t + 2) * kstep; const char* b2 = last ? nB : cB + (size_t)(t + 2) * kstep;
;             const char* a3 = a2 + kstep; const char* b3 = b2 + kstep;
;             PG8_LDB(B0, 0, 0); PG8_LDB(B1, 0, 1); PG8_SCHED; PG8_LDA(At, 0, 0); PG8_STAGE(PG8_SA(1, 1), a1 + hstep);
;             PG8_WAIT_V(8); PG8_WAIT_L(0); PG8_BAR; PG8_MMA(0, 0, At, B0); PG8_MMA(0, 1, At, B1); PG8_BAR; PG8_SCHED;
;             PG8_LDA(At, 0, 1); PG8_STAGEB(PG8_SB(0, 0), b2); PG8_STAGEB(PG8_SB(0, 1), b2 + hstep); PG8_STAGE(PG8_SA(0, 0), a2);
.LBB0_866:
	s_add_u32 s6, vcc_lo, 0xfff80080
	s_addc_u32 s7, vcc_hi, -1
	s_add_i32 s17, 0, 0x10000
	s_cmp_eq_u32 s16, 28
	s_cselect_b32 s23, s75, s7
	s_cselect_b32 s22, s81, s6
	v_add_u32_e32 v140, s17, v143
	s_cselect_b32 s7, s73, s93
	s_cselect_b32 s6, s83, s92
	s_add_i32 s60, 0, 0x14000
	ds_read_b128 v[146:149], v140
	ds_read_b128 v[150:153], v140 offset:1024
	ds_read_b128 v[154:157], v140 offset:2048
	ds_read_b128 v[158:161], v140 offset:3072
	v_add_u32_e32 v140, s60, v143
	ds_read_b128 v[162:165], v140
	ds_read_b128 v[166:169], v140 offset:1024
	ds_read_b128 v[170:173], v140 offset:2048
	ds_read_b128 v[174:177], v140 offset:3072
	v_lshl_add_u64 v[140:141], vcc, 0, v[136:137]
	s_add_i32 m0, s50, 0xc000
	ds_read_b128 v[178:181], v144
	ds_read_b128 v[186:189], v144 offset:1024
	ds_read_b128 v[190:193], v144 offset:2048
	ds_read_b128 v[194:197], v144 offset:3072
	ds_read_b128 v[222:225], v144 offset:4096
	ds_read_b128 v[226:229], v144 offset:5120
	ds_read_b128 v[230:233], v144 offset:6144
	ds_read_b128 v[234:237], v144 offset:7168
	global_load_lds_dwordx4 v[140:141], off
	v_lshl_add_u64 v[140:141], vcc, 0, v[138:139]
	s_add_i32 m0, s50, 0xe000
	s_nop 0
	global_load_lds_dwordx4 v[140:141], off
	s_waitcnt vmcnt(8)
	s_waitcnt lgkmcnt(0)
	s_barrier
	s_waitcnt lgkmcnt(0)
	v_mfma_f32_16x16x32_bf16 v[124:127], v[146:149], v[178:181], v[124:127]
	v_mfma_f32_16x16x32_bf16 v[120:123], v[154:157], v[178:181], v[120:123]
	v_mfma_f32_16x16x32_bf16 v[108:111], v[146:149], v[190:193], v[108:111]
	v_mfma_f32_16x16x32_bf16 v[104:107], v[154:157], v[190:193], v[104:107]
	v_mfma_f32_16x16x32_bf16 v[92:95], v[146:149], v[222:225], v[92:95]
	v_mfma_f32_16x16x32_bf16 v[88:91], v[154:157], v[222:225], v[88:91]
	v_mfma_f32_16x16x32_bf16 v[76:79], v[146:149], v[230:233], v[76:79]
	v_mfma_f32_16x16x32_bf16 v[72:75], v[154:157], v[230:233], v[72:75]
	v_mfma_f32_16x16x32_bf16 v[124:127], v[150:153], v[186:189], v[124:127]
	v_mfma_f32_16x16x32_bf16 v[120:123], v[158:161], v[186:189], v[120:123]
	v_mfma_f32_16x16x32_bf16 v[108:111], v[150:153], v[194:197], v[108:111]
	v_mfma_f32_16x16x32_bf16 v[104:107], v[158:161], v[194:197], v[104:107]
	v_mfma_f32_16x16x32_bf16 v[92:95], v[150:153], v[226:229], v[92:95]
	v_mfma_f32_16x16x32_bf16 v[88:91], v[158:161], v[226:229], v[88:91]
	v_mfma_f32_16x16x32_bf16 v[76:79], v[150:153], v[234:237], v[76:79]
	v_mfma_f32_16x16x32_bf16 v[72:75], v[158:161], v[234:237], v[72:75]
	v_mfma_f32_16x16x32_bf16 v[116:119], v[162:165], v[178:181], v[116:119]
	v_mfma_f32_16x16x32_bf16 v[112:115], v[170:173], v[178:181], v[112:115]
	v_mfma_f32_16x16x32_bf16 v[100:103], v[162:165], v[190:193], v[100:103]
	v_mfma_f32_16x16x32_bf16 v[96:99], v[170:173], v[190:193], v[96:99]
	v_mfma_f32_16x16x32_bf16 v[84:87], v[162:165], v[222:225], v[84:87]
	v_mfma_f32_16x16x32_bf16 v[80:83], v[170:173], v[222:225], v[80:83]
	v_mfma_f32_16x16x32_bf16 v[68:71], v[162:165], v[230:233], v[68:71]
	v_mfma_f32_16x16x32_bf16 v[64:67], v[170:173], v[230:233], v[64:67]
	v_mfma_f32_16x16x32_bf16 v[116:119], v[166:169], v[186:189], v[116:119]
	v_mfma_f32_16x16x32_bf16 v[112:115], v[174:177], v[186:189], v[112:115]
	v_mfma_f32_16x16x32_bf16 v[100:103], v[166:169], v[194:197], v[100:103]
	v_mfma_f32_16x16x32_bf16 v[96:99], v[174:177], v[194:197], v[96:99]
	v_mfma_f32_16x16x32_bf16 v[84:87], v[166:169], v[226:229], v[84:87]
	v_mfma_f32_16x16x32_bf16 v[80:83], v[174:177], v[226:229], v[80:83]
	v_mfma_f32_16x16x32_bf16 v[68:71], v[166:169], v[234:237], v[68:71]
	v_mfma_f32_16x16x32_bf16 v[64:67], v[174:177], v[234:237], v[64:67]
	s_barrier
	s_add_i32 s17, s17, s11
	v_lshl_add_u64 v[140:141], s[6:7], 0, v[132:133]
	s_mov_b32 m0, s17
	ds_read_b128 v[178:181], v144 offset:16384
	ds_read_b128 v[186:189], v144 offset:17408
	ds_read_b128 v[190:193], v144 offset:18432
	ds_read_b128 v[194:197], v144 offset:19456
	ds_read_b128 v[222:225], v144 offset:20480
	ds_read_b128 v[226:229], v144 offset:21504
	ds_read_b128 v[230:233], v144 offset:22528
	ds_read_b128 v[234:237], v144 offset:23552
	global_load_lds_dwordx4 v[140:141], off
	s_add_i32 m0, s17, 0x2000
	s_add_u32 s58, s6, 0x80000
	v_lshl_add_u64 v[182:183], s[6:7], 0, v[128:129]
	s_addc_u32 s59, s7, 0
	s_add_i32 s17, s60, s11
	global_load_lds_dwordx4 v[182:183], off
	v_lshl_add_u64 v[238:239], s[58:59], 0, v[132:133]
	s_mov_b32 m0, s17
	v_lshl_add_u64 v[240:241], s[22:23], 0, v[130:131]
	global_load_lds_dwordx4 v[238:239], off
	v_lshl_add_u64 v[238:239], s[58:59], 0, v[128:129]
	s_add_i32 m0, s17, 0x2000
	s_nop 0
	global_load_lds_dwordx4 v[238:239], off
	v_lshl_add_u64 v[238:239], s[22:23], 0, v[134:135]
	s_mov_b32 m0, s50
	s_nop 0
	global_load_lds_dwordx4 v[238:239], off
	s_mov_b32 m0, s53
	s_nop 0
	global_load_lds_dwordx4 v[240:241], off
	s_waitcnt vmcnt(8)
	s_waitcnt lgkmcnt(0)
	s_barrier
; #define PG8_STAGE(bufoff, gbase) PG8_STAGEV(bufoff, gbase, voff)
; #define PG8_LDA(dst, b, h) do { _Pragma("unroll") for (int m = 0; m < 4; ++m) _Pragma("unroll") for (int k = 0; k < 2; ++k) dst[m][k] = *(const LAS bf16x8*)(lds + PG8_SA(b, h) + aoff + m * 2048 + k * 1024); } while (0)
; #define PG8_LDB(dst, b, h) do { _Pragma("unroll") for (int n = 0; n < 2; ++n) _Pragma("unroll") for (int k = 0; k < 2; ++k) dst[n][k] = *(const LAS bf16x8*)(lds + PG8_SB(b, h) + boff + n * 2048 + k * 1024); } while (0)
; #define PG8_MMA(ai, bj, At, Bt) do { __builtin_amdgcn_s_setprio(1); _Pragma("unroll") for (int m = 0; m < 4; ++m) _Pragma("unroll") for (int n = 0; n < 2; ++n) _Pragma("unroll") for (int k = 0; k < 2; ++k) \
;         acc[ai][bj][m][n] = __builtin_amdgcn_mfma_f32_16x16x32_bf16(Bt[n][k], At[m][k], acc[ai][bj][m][n], 0, 0, 0); __builtin_amdgcn_s_setprio(0); } while (0)
; #define PG8_WAIT_V(n) asm volatile("s_waitcnt vmcnt(" #n ")" ::: "memory")
; #define PG8_WAIT_L(n) asm volatile("s_waitcnt lgkmcnt(" #n ")" ::: "memory")
; #define PG8_BAR __builtin_amdgcn_s_barrier()
; #define PG8_SCHED __builtin_amdgcn_sched_barrier(0)
; template <bool PERM, class Epi, class Sched>
; __device__ __forceinline__ void gemm_phase(LAS unsigned char* lds, const int K, const Sched& S, const Epi& E, const int wid0) {
;     ...
;             PG8_WAIT_V(8); PG8_WAIT_L(0); PG8_BAR; PG8_MMA(1, 0, At, B0); PG8_MMA(1, 1, At, B1); PG8_BAR; PG8_SCHED;
;             PG8_LDB(B0, 1, 0); PG8_LDB(B1, 1, 1); PG8_SCHED; PG8_LDA(At, 1, 0); PG8_STAGE(PG8_SA(0, 1), a2 + hstep);
;             PG8_WAIT_V(8); PG8_WAIT_L(0); PG8_BAR; PG8_MMA(0, 0, At, B0); PG8_MMA(0, 1, At, B1); PG8_BAR; PG8_SCHED;
	s_waitcnt lgkmcnt(0)
	v_mfma_f32_16x16x32_bf16 v[60:63], v[146:149], v[178:181], v[60:63]
	v_mfma_f32_16x16x32_bf16 v[56:59], v[154:157], v[178:181], v[56:59]
	v_mfma_f32_16x16x32_bf16 v[44:47], v[146:149], v[190:193], v[44:47]
	v_mfma_f32_16x16x32_bf16 v[40:43], v[154:157], v[190:193], v[40:43]
	v_mfma_f32_16x16x32_bf16 v[28:31], v[146:149], v[222:225], v[28:31]
	v_mfma_f32_16x16x32_bf16 v[24:27], v[154:157], v[222:225], v[24:27]
	v_mfma_f32_16x16x32_bf16 v[12:15], v[146:149], v[230:233], v[12:15]
	v_mfma_f32_16x16x32_bf16 v[8:11], v[154:157], v[230:233], v[8:11]
	v_mfma_f32_16x16x32_bf16 v[60:63], v[150:153], v[186:189], v[60:63]
	v_mfma_f32_16x16x32_bf16 v[56:59], v[158:161], v[186:189], v[56:59]
	v_mfma_f32_16x16x32_bf16 v[44:47], v[150:153], v[194:197], v[44:47]
	v_mfma_f32_16x16x32_bf16 v[40:43], v[158:161], v[194:197], v[40:43]
	v_mfma_f32_16x16x32_bf16 v[28:31], v[150:153], v[226:229], v[28:31]
	v_mfma_f32_16x16x32_bf16 v[24:27], v[158:161], v[226:229], v[24:27]
	v_mfma_f32_16x16x32_bf16 v[12:15], v[150:153], v[234:237], v[12:15]
	v_mfma_f32_16x16x32_bf16 v[8:11], v[158:161], v[234:237], v[8:11]
	v_mfma_f32_16x16x32_bf16 v[52:55], v[162:165], v[178:181], v[52:55]
	v_mfma_f32_16x16x32_bf16 v[48:51], v[170:173], v[178:181], v[48:51]
	v_mfma_f32_16x16x32_bf16 v[36:39], v[162:165], v[190:193], v[36:39]
	v_mfma_f32_16x16x32_bf16 v[32:35], v[170:173], v[190:193], v[32:35]
	v_mfma_f32_16x16x32_bf16 v[20:23], v[162:165], v[222:225], v[20:23]
	v_mfma_f32_16x16x32_bf16 v[16:19], v[170:173], v[222:225], v[16:19]
	v_mfma_f32_16x16x32_bf16 v[4:7], v[162:165], v[230:233], v[4:7]
	v_mfma_f32_16x16x32_bf16 v[0:3], v[170:173], v[230:233], v[0:3]
	v_mfma_f32_16x16x32_bf16 v[52:55], v[166:169], v[186:189], v[52:55]
	v_mfma_f32_16x16x32_bf16 v[48:51], v[174:177], v[186:189], v[48:51]
	v_mfma_f32_16x16x32_bf16 v[36:39], v[166:169], v[194:197], v[36:39]
	v_mfma_f32_16x16x32_bf16 v[32:35], v[174:177], v[194:197], v[32:35]
	v_mfma_f32_16x16x32_bf16 v[20:23], v[166:169], v[226:229], v[20:23]
	v_mfma_f32_16x16x32_bf16 v[16:19], v[174:177], v[226:229], v[16:19]
	v_mfma_f32_16x16x32_bf16 v[4:7], v[166:169], v[234:237], v[4:7]
	v_mfma_f32_16x16x32_bf16 v[0:3], v[174:177], v[234:237], v[0:3]
	s_barrier
	s_add_i32 s17, 0, 0x18000
	v_add_u32_e32 v145, s17, v143
	s_add_i32 s58, 0, 0x1c000
	ds_read_b128 v[146:149], v145
	ds_read_b128 v[150:153], v145 offset:1024
	ds_read_b128 v[154:157], v145 offset:2048
	ds_read_b128 v[158:161], v145 offset:3072
	v_add_u32_e32 v145, s58, v143
	ds_read_b128 v[162:165], v145
	ds_read_b128 v[166:169], v145 offset:1024
	ds_read_b128 v[170:173], v145 offset:2048
	ds_read_b128 v[174:177], v145 offset:3072
	s_add_u32 s22, s22, 0x80000
	s_addc_u32 s23, s23, 0
	s_mov_b32 m0, s54
	v_lshl_add_u64 v[242:243], s[22:23], 0, v[134:135]
	ds_read_b128 v[178:181], v144 offset:32768
	ds_read_b128 v[186:189], v144 offset:33792
	ds_read_b128 v[190:193], v144 offset:34816
	ds_read_b128 v[194:197], v144 offset:35840
	ds_read_b128 v[222:225], v144 offset:36864
	ds_read_b128 v[226:229], v144 offset:37888
	ds_read_b128 v[230:233], v144 offset:38912
	ds_read_b128 v[234:237], v144 offset:39936
	global_load_lds_dwordx4 v[242:243], off
	v_lshl_add_u64 v[242:243], s[22:23], 0, v[130:131]
	s_mov_b32 m0, s55
	s_nop 0
	global_load_lds_dwordx4 v[242:243], off
	s_waitcnt vmcnt(8)
	s_waitcnt lgkmcnt(0)
	s_barrier
	s_waitcnt lgkmcnt(0)
	v_mfma_f32_16x16x32_bf16 v[124:127], v[146:149], v[178:181], v[124:127]
	v_mfma_f32_16x16x32_bf16 v[120:123], v[154:157], v[178:181], v[120:123]
	v_mfma_f32_16x16x32_bf16 v[108:111], v[146:149], v[190:193], v[108:111]
	v_mfma_f32_16x16x32_bf16 v[104:107], v[154:157], v[190:193], v[104:107]
	v_mfma_f32_16x16x32_bf16 v[92:95], v[146:149], v[222:225], v[92:95]
	v_mfma_f32_16x16x32_bf16 v[88:91], v[154:157], v[222:225], v[88:91]
	v_mfma_f32_16x16x32_bf16 v[76:79], v[146:149], v[230:233], v[76:79]
	v_mfma_f32_16x16x32_bf16 v[72:75], v[154:157], v[230:233], v[72:75]
	v_mfma_f32_16x16x32_bf16 v[124:127], v[150:153], v[186:189], v[124:127]
	v_mfma_f32_16x16x32_bf16 v[120:123], v[158:161], v[186:189], v[120:123]
	v_mfma_f32_16x16x32_bf16 v[108:111], v[150:153], v[194:197], v[108:111]
	v_mfma_f32_16x16x32_bf16 v[104:107], v[158:161], v[194:197], v[104:107]
	v_mfma_f32_16x16x32_bf16 v[92:95], v[150:153], v[226:229], v[92:95]
	v_mfma_f32_16x16x32_bf16 v[88:91], v[158:161], v[226:229], v[88:91]
	v_mfma_f32_16x16x32_bf16 v[76:79], v[150:153], v[234:237], v[76:79]
	v_mfma_f32_16x16x32_bf16 v[72:75], v[158:161], v[234:237], v[72:75]
	v_mfma_f32_16x16x32_bf16 v[116:119], v[162:165], v[178:181], v[116:119]
	v_mfma_f32_16x16x32_bf16 v[112:115], v[170:173], v[178:181], v[112:115]
	v_mfma_f32_16x16x32_bf16 v[100:103], v[162:165], v[190:193], v[100:103]
	v_mfma_f32_16x16x32_bf16 v[96:99], v[170:173], v[190:193], v[96:99]
	v_mfma_f32_16x16x32_bf16 v[84:87], v[162:165], v[222:225], v[84:87]
	v_mfma_f32_16x16x32_bf16 v[80:83], v[170:173], v[222:225], v[80:83]
	v_mfma_f32_16x16x32_bf16 v[68:71], v[162:165], v[230:233], v[68:71]
	v_mfma_f32_16x16x32_bf16 v[64:67], v[170:173], v[230:233], v[64:67]
	v_mfma_f32_16x16x32_bf16 v[116:119], v[166:169], v[186:189], v[116:119]
	v_mfma_f32_16x16x32_bf16 v[112:115], v[174:177], v[186:189], v[112:115]
	v_mfma_f32_16x16x32_bf16 v[100:103], v[166:169], v[194:197], v[100:103]
	v_mfma_f32_16x16x32_bf16 v[96:99], v[174:177], v[194:197], v[96:99]
	v_mfma_f32_16x16x32_bf16 v[84:87], v[166:169], v[226:229], v[84:87]
	v_mfma_f32_16x16x32_bf16 v[80:83], v[174:177], v[226:229], v[80:83]
	v_mfma_f32_16x16x32_bf16 v[68:71], v[166:169], v[234:237], v[68:71]
	v_mfma_f32_16x16x32_bf16 v[64:67], v[174:177], v[234:237], v[64:67]
	s_barrier
; #define PG8_STAGE(bufoff, gbase) PG8_STAGEV(bufoff, gbase, voff)
; #define PG8_STAGEB(bufoff, gbase) PG8_STAGEV(bufoff, gbase, voffB)
; #define PG8_LDA(dst, b, h) do { _Pragma("unroll") for (int m = 0; m < 4; ++m) _Pragma("unroll") for (int k = 0; k < 2; ++k) dst[m][k] = *(const LAS bf16x8*)(lds + PG8_SA(b, h) + aoff + m * 2048 + k * 1024); } while (0)
; #define PG8_MMA(ai, bj, At, Bt) do { __builtin_amdgcn_s_setprio(1); _Pragma("unroll") for (int m = 0; m < 4; ++m) _Pragma("unroll") for (int n = 0; n < 2; ++n) _Pragma("unroll") for (int k = 0; k < 2; ++k) \
;         acc[ai][bj][m][n] = __builtin_amdgcn_mfma_f32_16x16x32_bf16(Bt[n][k], At[m][k], acc[ai][bj][m][n], 0, 0, 0); __builtin_amdgcn_s_setprio(0); } while (0)
; #define PG8_WAIT_V(n) asm volatile("s_waitcnt vmcnt(" #n ")" ::: "memory")
; #define PG8_WAIT_L(n) asm volatile("s_waitcnt lgkmcnt(" #n ")" ::: "memory")
; #define PG8_BAR __builtin_amdgcn_s_barrier()
; #define PG8_SCHED __builtin_amdgcn_sched_barrier(0)
; template <bool PERM, class Epi, class Sched>
; __device__ __forceinline__ void gemm_phase(LAS unsigned char* lds, const int K, const Sched& S, const Epi& E, const int wid0) {
;     ...
;             PG8_LDA(At, 1, 1); PG8_STAGEB(PG8_SB(1, 0), b3); PG8_STAGEB(PG8_SB(1, 1), b3 + hstep); PG8_STAGE(PG8_SA(1, 0), a3);
;             PG8_WAIT_V(8); PG8_WAIT_L(0); PG8_BAR; PG8_MMA(1, 0, At, B0); PG8_MMA(1, 1, At, B1); PG8_BAR; PG8_SCHED;
;         }
	s_add_i32 s17, s17, s11
	v_lshl_add_u64 v[140:141], v[140:141], 0, s[42:43]
	s_mov_b32 m0, s17
	ds_read_b128 v[178:181], v144 offset:49152
	ds_read_b128 v[186:189], v144 offset:50176
	ds_read_b128 v[190:193], v144 offset:51200
	ds_read_b128 v[194:197], v144 offset:52224
	ds_read_b128 v[222:225], v144 offset:53248
	ds_read_b128 v[226:229], v144 offset:54272
	ds_read_b128 v[230:233], v144 offset:55296
	ds_read_b128 v[234:237], v144 offset:56320
	global_load_lds_dwordx4 v[140:141], off
	s_add_i32 m0, s17, 0x2000
	s_add_u32 s6, s6, 0x80080
	v_lshl_add_u64 v[140:141], v[182:183], 0, s[42:43]
	s_addc_u32 s7, s7, 0
	s_add_i32 s17, s58, s11
	global_load_lds_dwordx4 v[140:141], off
	v_lshl_add_u64 v[140:141], s[6:7], 0, v[132:133]
	s_mov_b32 m0, s17
	s_nop 0
	global_load_lds_dwordx4 v[140:141], off
	v_lshl_add_u64 v[140:141], s[6:7], 0, v[128:129]
	s_add_i32 m0, s17, 0x2000
	s_nop 0
	global_load_lds_dwordx4 v[140:141], off
	v_lshl_add_u64 v[140:141], v[238:239], 0, s[42:43]
	s_mov_b32 m0, s56
	s_nop 0
	global_load_lds_dwordx4 v[140:141], off
	v_lshl_add_u64 v[140:141], v[240:241], 0, s[42:43]
	s_mov_b32 m0, s66
	s_nop 0
	global_load_lds_dwordx4 v[140:141], off
	s_waitcnt vmcnt(8)
	s_waitcnt lgkmcnt(0)
	s_barrier
	s_waitcnt lgkmcnt(0)
	v_mfma_f32_16x16x32_bf16 v[60:63], v[146:149], v[178:181], v[60:63]
	v_mfma_f32_16x16x32_bf16 v[56:59], v[154:157], v[178:181], v[56:59]
	v_mfma_f32_16x16x32_bf16 v[44:47], v[146:149], v[190:193], v[44:47]
	v_mfma_f32_16x16x32_bf16 v[40:43], v[154:157], v[190:193], v[40:43]
	v_mfma_f32_16x16x32_bf16 v[28:31], v[146:149], v[222:225], v[28:31]
	v_mfma_f32_16x16x32_bf16 v[24:27], v[154:157], v[222:225], v[24:27]
	v_mfma_f32_16x16x32_bf16 v[12:15], v[146:149], v[230:233], v[12:15]
	v_mfma_f32_16x16x32_bf16 v[8:11], v[154:157], v[230:233], v[8:11]
	v_mfma_f32_16x16x32_bf16 v[60:63], v[150:153], v[186:189], v[60:63]
	v_mfma_f32_16x16x32_bf16 v[56:59], v[158:161], v[186:189], v[56:59]
	v_mfma_f32_16x16x32_bf16 v[44:47], v[150:153], v[194:197], v[44:47]
	v_mfma_f32_16x16x32_bf16 v[40:43], v[158:161], v[194:197], v[40:43]
	v_mfma_f32_16x16x32_bf16 v[28:31], v[150:153], v[226:229], v[28:31]
	v_mfma_f32_16x16x32_bf16 v[24:27], v[158:161], v[226:229], v[24:27]
	v_mfma_f32_16x16x32_bf16 v[12:15], v[150:153], v[234:237], v[12:15]
	v_mfma_f32_16x16x32_bf16 v[8:11], v[158:161], v[234:237], v[8:11]
	v_mfma_f32_16x16x32_bf16 v[52:55], v[162:165], v[178:181], v[52:55]
	v_mfma_f32_16x16x32_bf16 v[48:51], v[170:173], v[178:181], v[48:51]
	v_mfma_f32_16x16x32_bf16 v[36:39], v[162:165], v[190:193], v[36:39]
	v_mfma_f32_16x16x32_bf16 v[32:35], v[170:173], v[190:193], v[32:35]
	v_mfma_f32_16x16x32_bf16 v[20:23], v[162:165], v[222:225], v[20:23]
	v_mfma_f32_16x16x32_bf16 v[16:19], v[170:173], v[222:225], v[16:19]
	v_mfma_f32_16x16x32_bf16 v[4:7], v[162:165], v[230:233], v[4:7]
	v_mfma_f32_16x16x32_bf16 v[0:3], v[170:173], v[230:233], v[0:3]
	v_mfma_f32_16x16x32_bf16 v[52:55], v[166:169], v[186:189], v[52:55]
	v_mfma_f32_16x16x32_bf16 v[48:51], v[174:177], v[186:189], v[48:51]
	v_mfma_f32_16x16x32_bf16 v[36:39], v[166:169], v[194:197], v[36:39]
	v_mfma_f32_16x16x32_bf16 v[32:35], v[174:177], v[194:197], v[32:35]
	v_mfma_f32_16x16x32_bf16 v[20:23], v[166:169], v[226:229], v[20:23]
	v_mfma_f32_16x16x32_bf16 v[16:19], v[174:177], v[226:229], v[16:19]
	v_mfma_f32_16x16x32_bf16 v[4:7], v[166:169], v[234:237], v[4:7]
	v_mfma_f32_16x16x32_bf16 v[0:3], v[174:177], v[234:237], v[0:3]
	s_barrier
	s_add_i32 s16, s16, 2
	s_add_u32 vcc_lo, vcc_lo, 0x100
	s_addc_u32 vcc_hi, vcc_hi, 0
	s_add_u32 s92, s92, 0x100
	s_addc_u32 s93, s93, 0
	s_cmp_gt_u32 s16, 29
	s_cbranch_scc0 .LBB0_866
	s_and_b64 vcc, exec, s[70:71]
	s_cbranch_vccz .LBB0_869
	s_barrier

; #define PG8_STAGE(bufoff, gbase) PG8_STAGEV(bufoff, gbase, voff)
; #define PG8_STAGEB(bufoff, gbase) PG8_STAGEV(bufoff, gbase, voffB)
; #define PG8_LDA(dst, b, h) do { _Pragma("unroll") for (int m = 0; m < 4; ++m) _Pragma("unroll") for (int k = 0; k < 2; ++k) dst[m][k] = *(const LAS bf16x8*)(lds + PG8_SA(b, h) + aoff + m * 2048 + k * 1024); } while (0)
; #define PG8_LDB(dst, b, h) do { _Pragma("unroll") for (int n = 0; n < 2; ++n) _Pragma("unroll") for (int k = 0; k < 2; ++k) dst[n][k] = *(const LAS bf16x8*)(lds + PG8_SB(b, h) + boff + n * 2048 + k * 1024); } while (0)
; #define PG8_MMA(ai, bj, At, Bt) do { __builtin_amdgcn_s_setprio(1); _Pragma("unroll") for (int m = 0; m < 4; ++m) _Pragma("unroll") for (int n = 0; n < 2; ++n) _Pragma("unroll") for (int k = 0; k < 2; ++k) \
;         acc[ai][bj][m][n] = __builtin_amdgcn_mfma_f32_16x16x32_bf16(Bt[n][k], At[m][k], acc[ai][bj][m][n], 0, 0, 0); __builtin_amdgcn_s_setprio(0); } while (0)
; #define PG8_WAIT_V(n) asm volatile("s_waitcnt vmcnt(" #n ")" ::: "memory")
; #define PG8_WAIT_L(n) asm volatile("s_waitcnt lgkmcnt(" #n ")" ::: "memory")
; #define PG8_BAR __builtin_amdgcn_s_barrier()
; #define PG8_SCHED __builtin_amdgcn_sched_barrier(0)
; template <bool PERM, class Epi, class Sched>
; __device__ __forceinline__ void gemm_phase(LAS unsigned char* lds, const int K, const Sched& S, const Epi& E, const int wid0) {
;     ...
;             const bool last = (t == nt - 2);
;             const char* a1 = cA + (size_t)(t + 1) * kstep;
;             const char* a2 = last ? nA : cA + (size_t)(t + 2) * kstep; const char* b2 = last ? nB : cB + (size_t)(t + 2) * kstep;
;             const char* a3 = a2 + kstep; const char* b3 = b2 + kstep;
;             PG8_LDB(B0, 0, 0); PG8_LDB(B1, 0, 1); PG8_SCHED; PG8_LDA(At, 0, 0); PG8_STAGE(PG8_SA(1, 1), a1 + hstep);
;             PG8_WAIT_V(8); PG8_WAIT_L(0); PG8_BAR; PG8_MMA(0, 0, At, B0); PG8_MMA(0, 1, At, B1); PG8_BAR; PG8_SCHED;
;             PG8_LDA(At, 0, 1); PG8_STAGEB(PG8_SB(0, 0), b2); PG8_STAGEB(PG8_SB(0, 1), b2 + hstep); PG8_STAGE(PG8_SA(0, 0), a2);
.LBB0_934:
	s_add_u32 s17, s78, 0xffe00080
	s_addc_u32 s22, s79, -1
	s_add_i32 s58, 0, 0x10000
	s_cmpk_eq_i32 s16, 0x7c
	s_cselect_b32 s81, s69, s22
	s_cselect_b32 s80, s77, s17
	s_cselect_b32 s23, s25, s92
	s_cselect_b32 s22, s82, s83
	s_add_i32 s17, 0, 0x14000
	v_add_u32_e32 v120, s58, v168
	v_add_u32_e32 v166, s17, v168
	ds_read_b128 v[56:59], v120
	ds_read_b128 v[108:111], v120 offset:1024
	ds_read_b128 v[112:115], v120 offset:2048
	ds_read_b128 v[120:123], v120 offset:3072
	ds_read_b128 v[172:175], v166
	ds_read_b128 v[176:179], v166 offset:1024
	ds_read_b128 v[180:183], v166 offset:2048
	ds_read_b128 v[186:189], v166 offset:3072
	v_lshl_add_u64 v[166:167], s[78:79], 0, v[162:163]
	s_add_i32 m0, s48, 0xc000
	ds_read_b128 v[190:193], v170
	ds_read_b128 v[194:197], v170 offset:1024
	ds_read_b128 v[222:225], v170 offset:2048
	ds_read_b128 v[226:229], v170 offset:3072
	ds_read_b128 v[230:233], v170 offset:4096
	ds_read_b128 v[234:237], v170 offset:5120
	ds_read_b128 v[238:241], v170 offset:6144
	ds_read_b128 v[242:245], v170 offset:7168
	global_load_lds_dwordx4 v[166:167], off
	v_lshl_add_u64 v[166:167], s[78:79], 0, v[164:165]
	s_add_i32 m0, s48, 0xe000
	s_nop 0
	global_load_lds_dwordx4 v[166:167], off
	s_waitcnt vmcnt(8)
	s_waitcnt lgkmcnt(0)
	s_barrier
	s_waitcnt lgkmcnt(0)
	v_mfma_f32_16x16x32_bf16 v[140:143], v[56:59], v[190:193], v[140:143]
	v_mfma_f32_16x16x32_bf16 v[136:139], v[112:115], v[190:193], v[136:139]
	v_mfma_f32_16x16x32_bf16 v[128:131], v[56:59], v[222:225], v[128:131]
	v_mfma_f32_16x16x32_bf16 v[116:119], v[112:115], v[222:225], v[116:119]
	v_mfma_f32_16x16x32_bf16 v[100:103], v[56:59], v[230:233], v[100:103]
	v_mfma_f32_16x16x32_bf16 v[92:95], v[112:115], v[230:233], v[92:95]
	v_mfma_f32_16x16x32_bf16 v[84:87], v[56:59], v[238:241], v[84:87]
	v_mfma_f32_16x16x32_bf16 v[76:79], v[112:115], v[238:241], v[76:79]
	v_mfma_f32_16x16x32_bf16 v[140:143], v[108:111], v[194:197], v[140:143]
	v_mfma_f32_16x16x32_bf16 v[136:139], v[120:123], v[194:197], v[136:139]
	v_mfma_f32_16x16x32_bf16 v[128:131], v[108:111], v[226:229], v[128:131]
	v_mfma_f32_16x16x32_bf16 v[116:119], v[120:123], v[226:229], v[116:119]
	v_mfma_f32_16x16x32_bf16 v[100:103], v[108:111], v[234:237], v[100:103]
	v_mfma_f32_16x16x32_bf16 v[92:95], v[120:123], v[234:237], v[92:95]
	v_mfma_f32_16x16x32_bf16 v[84:87], v[108:111], v[242:245], v[84:87]
	v_mfma_f32_16x16x32_bf16 v[76:79], v[120:123], v[242:245], v[76:79]
	v_mfma_f32_16x16x32_bf16 v[132:135], v[172:175], v[190:193], v[132:135]
	v_mfma_f32_16x16x32_bf16 v[124:127], v[180:183], v[190:193], v[124:127]
	v_mfma_f32_16x16x32_bf16 v[104:107], v[172:175], v[222:225], v[104:107]
	v_mfma_f32_16x16x32_bf16 v[96:99], v[180:183], v[222:225], v[96:99]
	v_mfma_f32_16x16x32_bf16 v[88:91], v[172:175], v[230:233], v[88:91]
	v_mfma_f32_16x16x32_bf16 v[80:83], v[180:183], v[230:233], v[80:83]
	v_mfma_f32_16x16x32_bf16 v[72:75], v[172:175], v[238:241], v[72:75]
	v_mfma_f32_16x16x32_bf16 v[68:71], v[180:183], v[238:241], v[68:71]
	v_mfma_f32_16x16x32_bf16 v[132:135], v[176:179], v[194:197], v[132:135]
	v_mfma_f32_16x16x32_bf16 v[124:127], v[186:189], v[194:197], v[124:127]
	v_mfma_f32_16x16x32_bf16 v[104:107], v[176:179], v[226:229], v[104:107]
	v_mfma_f32_16x16x32_bf16 v[96:99], v[186:189], v[226:229], v[96:99]
	v_mfma_f32_16x16x32_bf16 v[88:91], v[176:179], v[234:237], v[88:91]
	v_mfma_f32_16x16x32_bf16 v[80:83], v[186:189], v[234:237], v[80:83]
	v_mfma_f32_16x16x32_bf16 v[72:75], v[176:179], v[242:245], v[72:75]
	v_mfma_f32_16x16x32_bf16 v[68:71], v[186:189], v[242:245], v[68:71]
	s_barrier
	s_add_i32 s58, s58, s18
	v_lshl_add_u64 v[166:167], s[22:23], 0, v[184:185]
	s_mov_b32 m0, s58
	ds_read_b128 v[190:193], v170 offset:16384
	ds_read_b128 v[194:197], v170 offset:17408
	ds_read_b128 v[222:225], v170 offset:18432
	ds_read_b128 v[226:229], v170 offset:19456
	ds_read_b128 v[230:233], v170 offset:20480
	ds_read_b128 v[234:237], v170 offset:21504
	ds_read_b128 v[238:241], v170 offset:22528
	ds_read_b128 v[242:245], v170 offset:23552
	global_load_lds_dwordx4 v[166:167], off
	s_add_i32 m0, s58, 0x2000
	s_add_u32 s58, s22, 0x200000
	v_lshl_add_u64 v[246:247], s[22:23], 0, v[144:145]
	s_addc_u32 s59, s23, 0
	s_add_i32 s17, s17, s18
	global_load_lds_dwordx4 v[246:247], off
	v_lshl_add_u64 v[248:249], s[58:59], 0, v[184:185]
	s_mov_b32 m0, s17
	v_lshl_add_u64 v[250:251], s[80:81], 0, v[144:145]
	global_load_lds_dwordx4 v[248:249], off
	v_lshl_add_u64 v[248:249], s[58:59], 0, v[144:145]
	s_add_i32 m0, s17, 0x2000
	s_nop 0
	global_load_lds_dwordx4 v[248:249], off
	v_lshl_add_u64 v[248:249], s[80:81], 0, v[184:185]
	s_mov_b32 m0, s48
	s_nop 0
	global_load_lds_dwordx4 v[248:249], off
	s_mov_b32 m0, s50
	s_nop 0
	global_load_lds_dwordx4 v[250:251], off
	s_waitcnt vmcnt(8)
	s_waitcnt lgkmcnt(0)
	s_barrier
; #define PG8_STAGE(bufoff, gbase) PG8_STAGEV(bufoff, gbase, voff)
; #define PG8_LDA(dst, b, h) do { _Pragma("unroll") for (int m = 0; m < 4; ++m) _Pragma("unroll") for (int k = 0; k < 2; ++k) dst[m][k] = *(const LAS bf16x8*)(lds + PG8_SA(b, h) + aoff + m * 2048 + k * 1024); } while (0)
; #define PG8_LDB(dst, b, h) do { _Pragma("unroll") for (int n = 0; n < 2; ++n) _Pragma("unroll") for (int k = 0; k < 2; ++k) dst[n][k] = *(const LAS bf16x8*)(lds + PG8_SB(b, h) + boff + n * 2048 + k * 1024); } while (0)
; #define PG8_MMA(ai, bj, At, Bt) do { __builtin_amdgcn_s_setprio(1); _Pragma("unroll") for (int m = 0; m < 4; ++m) _Pragma("unroll") for (int n = 0; n < 2; ++n) _Pragma("unroll") for (int k = 0; k < 2; ++k) \
;         acc[ai][bj][m][n] = __builtin_amdgcn_mfma_f32_16x16x32_bf16(Bt[n][k], At[m][k], acc[ai][bj][m][n], 0, 0, 0); __builtin_amdgcn_s_setprio(0); } while (0)
; #define PG8_WAIT_V(n) asm volatile("s_waitcnt vmcnt(" #n ")" ::: "memory")
; #define PG8_WAIT_L(n) asm volatile("s_waitcnt lgkmcnt(" #n ")" ::: "memory")
; #define PG8_BAR __builtin_amdgcn_s_barrier()
; #define PG8_SCHED __builtin_amdgcn_sched_barrier(0)
; template <bool PERM, class Epi, class Sched>
; __device__ __forceinline__ void gemm_phase(LAS unsigned char* lds, const int K, const Sched& S, const Epi& E, const int wid0) {
;     ...
;             PG8_WAIT_V(8); PG8_WAIT_L(0); PG8_BAR; PG8_MMA(1, 0, At, B0); PG8_MMA(1, 1, At, B1); PG8_BAR; PG8_SCHED;
;             PG8_LDB(B0, 1, 0); PG8_LDB(B1, 1, 1); PG8_SCHED; PG8_LDA(At, 1, 0); PG8_STAGE(PG8_SA(0, 1), a2 + hstep);
;             PG8_WAIT_V(8); PG8_WAIT_L(0); PG8_BAR; PG8_MMA(0, 0, At, B0); PG8_MMA(0, 1, At, B1); PG8_BAR; PG8_SCHED;
	s_waitcnt lgkmcnt(0)
	v_mfma_f32_16x16x32_bf16 v[64:67], v[56:59], v[190:193], v[64:67]
	v_mfma_f32_16x16x32_bf16 v[60:63], v[112:115], v[190:193], v[60:63]
	v_mfma_f32_16x16x32_bf16 v[44:47], v[56:59], v[222:225], v[44:47]
	v_mfma_f32_16x16x32_bf16 v[40:43], v[112:115], v[222:225], v[40:43]
	v_mfma_f32_16x16x32_bf16 v[28:31], v[56:59], v[230:233], v[28:31]
	v_mfma_f32_16x16x32_bf16 v[24:27], v[112:115], v[230:233], v[24:27]
	v_mfma_f32_16x16x32_bf16 v[12:15], v[56:59], v[238:241], v[12:15]
	v_mfma_f32_16x16x32_bf16 v[8:11], v[112:115], v[238:241], v[8:11]
	v_mfma_f32_16x16x32_bf16 v[64:67], v[108:111], v[194:197], v[64:67]
	v_mfma_f32_16x16x32_bf16 v[60:63], v[120:123], v[194:197], v[60:63]
	v_mfma_f32_16x16x32_bf16 v[44:47], v[108:111], v[226:229], v[44:47]
	v_mfma_f32_16x16x32_bf16 v[40:43], v[120:123], v[226:229], v[40:43]
	v_mfma_f32_16x16x32_bf16 v[28:31], v[108:111], v[234:237], v[28:31]
	v_mfma_f32_16x16x32_bf16 v[24:27], v[120:123], v[234:237], v[24:27]
	v_mfma_f32_16x16x32_bf16 v[12:15], v[108:111], v[242:245], v[12:15]
	v_mfma_f32_16x16x32_bf16 v[8:11], v[120:123], v[242:245], v[8:11]
	v_mfma_f32_16x16x32_bf16 v[52:55], v[172:175], v[190:193], v[52:55]
	v_mfma_f32_16x16x32_bf16 v[48:51], v[180:183], v[190:193], v[48:51]
	v_mfma_f32_16x16x32_bf16 v[36:39], v[172:175], v[222:225], v[36:39]
	v_mfma_f32_16x16x32_bf16 v[32:35], v[180:183], v[222:225], v[32:35]
	v_mfma_f32_16x16x32_bf16 v[20:23], v[172:175], v[230:233], v[20:23]
	v_mfma_f32_16x16x32_bf16 v[16:19], v[180:183], v[230:233], v[16:19]
	v_mfma_f32_16x16x32_bf16 v[4:7], v[172:175], v[238:241], v[4:7]
	v_mfma_f32_16x16x32_bf16 v[0:3], v[180:183], v[238:241], v[0:3]
	v_mfma_f32_16x16x32_bf16 v[52:55], v[176:179], v[194:197], v[52:55]
	v_mfma_f32_16x16x32_bf16 v[48:51], v[186:189], v[194:197], v[48:51]
	v_mfma_f32_16x16x32_bf16 v[36:39], v[176:179], v[226:229], v[36:39]
	v_mfma_f32_16x16x32_bf16 v[32:35], v[186:189], v[226:229], v[32:35]
	v_mfma_f32_16x16x32_bf16 v[20:23], v[176:179], v[234:237], v[20:23]
	v_mfma_f32_16x16x32_bf16 v[16:19], v[186:189], v[234:237], v[16:19]
	v_mfma_f32_16x16x32_bf16 v[4:7], v[176:179], v[242:245], v[4:7]
	v_mfma_f32_16x16x32_bf16 v[0:3], v[186:189], v[242:245], v[0:3]
	s_barrier
	s_add_i32 s17, 0, 0x18000
	s_add_i32 s60, 0, 0x1c000
	v_add_u32_e32 v120, s17, v168
	v_add_u32_e32 v171, s60, v168
	ds_read_b128 v[56:59], v120
	ds_read_b128 v[108:111], v120 offset:1024
	ds_read_b128 v[112:115], v120 offset:2048
	ds_read_b128 v[120:123], v120 offset:3072
	ds_read_b128 v[172:175], v171
	ds_read_b128 v[176:179], v171 offset:1024
	ds_read_b128 v[180:183], v171 offset:2048
	ds_read_b128 v[186:189], v171 offset:3072
	s_add_u32 s58, s80, 0x200000
	s_addc_u32 s59, s81, 0
	s_mov_b32 m0, s53
	v_lshl_add_u64 v[218:219], s[58:59], 0, v[184:185]
	ds_read_b128 v[190:193], v170 offset:32768
	ds_read_b128 v[194:197], v170 offset:33792
	ds_read_b128 v[222:225], v170 offset:34816
	ds_read_b128 v[226:229], v170 offset:35840
	ds_read_b128 v[230:233], v170 offset:36864
	ds_read_b128 v[234:237], v170 offset:37888
	ds_read_b128 v[238:241], v170 offset:38912
	ds_read_b128 v[242:245], v170 offset:39936
	global_load_lds_dwordx4 v[218:219], off
	v_lshl_add_u64 v[218:219], s[58:59], 0, v[144:145]
	s_mov_b32 m0, s54
	s_nop 0
	global_load_lds_dwordx4 v[218:219], off
	s_waitcnt vmcnt(8)
	s_waitcnt lgkmcnt(0)
	s_barrier
	s_waitcnt lgkmcnt(0)
	v_mfma_f32_16x16x32_bf16 v[140:143], v[56:59], v[190:193], v[140:143]
	v_mfma_f32_16x16x32_bf16 v[136:139], v[112:115], v[190:193], v[136:139]
	v_mfma_f32_16x16x32_bf16 v[128:131], v[56:59], v[222:225], v[128:131]
	v_mfma_f32_16x16x32_bf16 v[116:119], v[112:115], v[222:225], v[116:119]
	v_mfma_f32_16x16x32_bf16 v[100:103], v[56:59], v[230:233], v[100:103]
	v_mfma_f32_16x16x32_bf16 v[92:95], v[112:115], v[230:233], v[92:95]
	v_mfma_f32_16x16x32_bf16 v[84:87], v[56:59], v[238:241], v[84:87]
	v_mfma_f32_16x16x32_bf16 v[76:79], v[112:115], v[238:241], v[76:79]
	v_mfma_f32_16x16x32_bf16 v[140:143], v[108:111], v[194:197], v[140:143]
	v_mfma_f32_16x16x32_bf16 v[136:139], v[120:123], v[194:197], v[136:139]
	v_mfma_f32_16x16x32_bf16 v[128:131], v[108:111], v[226:229], v[128:131]
	v_mfma_f32_16x16x32_bf16 v[116:119], v[120:123], v[226:229], v[116:119]
	v_mfma_f32_16x16x32_bf16 v[100:103], v[108:111], v[234:237], v[100:103]
	v_mfma_f32_16x16x32_bf16 v[92:95], v[120:123], v[234:237], v[92:95]
	v_mfma_f32_16x16x32_bf16 v[84:87], v[108:111], v[242:245], v[84:87]
	v_mfma_f32_16x16x32_bf16 v[76:79], v[120:123], v[242:245], v[76:79]
	v_mfma_f32_16x16x32_bf16 v[132:135], v[172:175], v[190:193], v[132:135]
	v_mfma_f32_16x16x32_bf16 v[124:127], v[180:183], v[190:193], v[124:127]
	v_mfma_f32_16x16x32_bf16 v[104:107], v[172:175], v[222:225], v[104:107]
	v_mfma_f32_16x16x32_bf16 v[96:99], v[180:183], v[222:225], v[96:99]
	v_mfma_f32_16x16x32_bf16 v[88:91], v[172:175], v[230:233], v[88:91]
	v_mfma_f32_16x16x32_bf16 v[80:83], v[180:183], v[230:233], v[80:83]
	v_mfma_f32_16x16x32_bf16 v[72:75], v[172:175], v[238:241], v[72:75]
	v_mfma_f32_16x16x32_bf16 v[68:71], v[180:183], v[238:241], v[68:71]
	v_mfma_f32_16x16x32_bf16 v[132:135], v[176:179], v[194:197], v[132:135]
	v_mfma_f32_16x16x32_bf16 v[124:127], v[186:189], v[194:197], v[124:127]
	v_mfma_f32_16x16x32_bf16 v[104:107], v[176:179], v[226:229], v[104:107]
	v_mfma_f32_16x16x32_bf16 v[96:99], v[186:189], v[226:229], v[96:99]
	v_mfma_f32_16x16x32_bf16 v[88:91], v[176:179], v[234:237], v[88:91]
	v_mfma_f32_16x16x32_bf16 v[80:83], v[186:189], v[234:237], v[80:83]
	v_mfma_f32_16x16x32_bf16 v[72:75], v[176:179], v[242:245], v[72:75]
	v_mfma_f32_16x16x32_bf16 v[68:71], v[186:189], v[242:245], v[68:71]
	s_barrier
; #define PG8_STAGE(bufoff, gbase) PG8_STAGEV(bufoff, gbase, voff)
; #define PG8_STAGEB(bufoff, gbase) PG8_STAGEV(bufoff, gbase, voffB)
; #define PG8_LDA(dst, b, h) do { _Pragma("unroll") for (int m = 0; m < 4; ++m) _Pragma("unroll") for (int k = 0; k < 2; ++k) dst[m][k] = *(const LAS bf16x8*)(lds + PG8_SA(b, h) + aoff + m * 2048 + k * 1024); } while (0)
; #define PG8_MMA(ai, bj, At, Bt) do { __builtin_amdgcn_s_setprio(1); _Pragma("unroll") for (int m = 0; m < 4; ++m) _Pragma("unroll") for (int n = 0; n < 2; ++n) _Pragma("unroll") for (int k = 0; k < 2; ++k) \
;         acc[ai][bj][m][n] = __builtin_amdgcn_mfma_f32_16x16x32_bf16(Bt[n][k], At[m][k], acc[ai][bj][m][n], 0, 0, 0); __builtin_amdgcn_s_setprio(0); } while (0)
; #define PG8_WAIT_V(n) asm volatile("s_waitcnt vmcnt(" #n ")" ::: "memory")
; #define PG8_WAIT_L(n) asm volatile("s_waitcnt lgkmcnt(" #n ")" ::: "memory")
; #define PG8_BAR __builtin_amdgcn_s_barrier()
; #define PG8_SCHED __builtin_amdgcn_sched_barrier(0)
; template <bool PERM, class Epi, class Sched>
; __device__ __forceinline__ void gemm_phase(LAS unsigned char* lds, const int K, const Sched& S, const Epi& E, const int wid0) {
;     ...
;             PG8_LDA(At, 1, 1); PG8_STAGEB(PG8_SB(1, 0), b3); PG8_STAGEB(PG8_SB(1, 1), b3 + hstep); PG8_STAGE(PG8_SA(1, 0), a3);
;             PG8_WAIT_V(8); PG8_WAIT_L(0); PG8_BAR; PG8_MMA(1, 0, At, B0); PG8_MMA(1, 1, At, B1); PG8_BAR; PG8_SCHED;
;         }
	s_add_i32 s17, s17, s18
	v_lshl_add_u64 v[166:167], v[166:167], 0, s[42:43]
	s_mov_b32 m0, s17
	ds_read_b128 v[190:193], v170 offset:49152
	ds_read_b128 v[194:197], v170 offset:50176
	ds_read_b128 v[222:225], v170 offset:51200
	ds_read_b128 v[226:229], v170 offset:52224
	ds_read_b128 v[230:233], v170 offset:53248
	ds_read_b128 v[234:237], v170 offset:54272
	ds_read_b128 v[238:241], v170 offset:55296
	ds_read_b128 v[242:245], v170 offset:56320
	global_load_lds_dwordx4 v[166:167], off
	s_add_i32 m0, s17, 0x2000
	s_add_u32 s22, s22, 0x200080
	v_lshl_add_u64 v[166:167], v[246:247], 0, s[42:43]
	s_addc_u32 s23, s23, 0
	s_add_i32 s17, s60, s18
	global_load_lds_dwordx4 v[166:167], off
	v_lshl_add_u64 v[166:167], s[22:23], 0, v[184:185]
	s_mov_b32 m0, s17
	s_nop 0
	global_load_lds_dwordx4 v[166:167], off
	v_lshl_add_u64 v[166:167], s[22:23], 0, v[144:145]
	s_add_i32 m0, s17, 0x2000
	s_nop 0
	global_load_lds_dwordx4 v[166:167], off
	v_lshl_add_u64 v[166:167], v[248:249], 0, s[42:43]
	s_mov_b32 m0, s66
	s_nop 0
	global_load_lds_dwordx4 v[166:167], off
	v_lshl_add_u64 v[166:167], v[250:251], 0, s[42:43]
	s_mov_b32 m0, s67
	s_nop 0
	global_load_lds_dwordx4 v[166:167], off
	s_waitcnt vmcnt(8)
	s_waitcnt lgkmcnt(0)
	s_barrier
	s_waitcnt lgkmcnt(0)
	v_mfma_f32_16x16x32_bf16 v[64:67], v[56:59], v[190:193], v[64:67]
	v_mfma_f32_16x16x32_bf16 v[60:63], v[112:115], v[190:193], v[60:63]
	v_mfma_f32_16x16x32_bf16 v[44:47], v[56:59], v[222:225], v[44:47]
	v_mfma_f32_16x16x32_bf16 v[40:43], v[112:115], v[222:225], v[40:43]
	v_mfma_f32_16x16x32_bf16 v[28:31], v[56:59], v[230:233], v[28:31]
	v_mfma_f32_16x16x32_bf16 v[24:27], v[112:115], v[230:233], v[24:27]
	v_mfma_f32_16x16x32_bf16 v[12:15], v[56:59], v[238:241], v[12:15]
	v_mfma_f32_16x16x32_bf16 v[8:11], v[112:115], v[238:241], v[8:11]
	v_mfma_f32_16x16x32_bf16 v[64:67], v[108:111], v[194:197], v[64:67]
	v_mfma_f32_16x16x32_bf16 v[60:63], v[120:123], v[194:197], v[60:63]
	v_mfma_f32_16x16x32_bf16 v[44:47], v[108:111], v[226:229], v[44:47]
	v_mfma_f32_16x16x32_bf16 v[40:43], v[120:123], v[226:229], v[40:43]
	v_mfma_f32_16x16x32_bf16 v[28:31], v[108:111], v[234:237], v[28:31]
	v_mfma_f32_16x16x32_bf16 v[24:27], v[120:123], v[234:237], v[24:27]
	v_mfma_f32_16x16x32_bf16 v[12:15], v[108:111], v[242:245], v[12:15]
	v_mfma_f32_16x16x32_bf16 v[8:11], v[120:123], v[242:245], v[8:11]
	v_mfma_f32_16x16x32_bf16 v[52:55], v[172:175], v[190:193], v[52:55]
	v_mfma_f32_16x16x32_bf16 v[48:51], v[180:183], v[190:193], v[48:51]
	v_mfma_f32_16x16x32_bf16 v[36:39], v[172:175], v[222:225], v[36:39]
	v_mfma_f32_16x16x32_bf16 v[32:35], v[180:183], v[222:225], v[32:35]
	v_mfma_f32_16x16x32_bf16 v[20:23], v[172:175], v[230:233], v[20:23]
	v_mfma_f32_16x16x32_bf16 v[16:19], v[180:183], v[230:233], v[16:19]
	v_mfma_f32_16x16x32_bf16 v[4:7], v[172:175], v[238:241], v[4:7]
	v_mfma_f32_16x16x32_bf16 v[0:3], v[180:183], v[238:241], v[0:3]
	v_mfma_f32_16x16x32_bf16 v[52:55], v[176:179], v[194:197], v[52:55]
	v_mfma_f32_16x16x32_bf16 v[48:51], v[186:189], v[194:197], v[48:51]
	v_mfma_f32_16x16x32_bf16 v[36:39], v[176:179], v[226:229], v[36:39]
	v_mfma_f32_16x16x32_bf16 v[32:35], v[186:189], v[226:229], v[32:35]
	v_mfma_f32_16x16x32_bf16 v[20:23], v[176:179], v[234:237], v[20:23]
	v_mfma_f32_16x16x32_bf16 v[16:19], v[186:189], v[234:237], v[16:19]
	v_mfma_f32_16x16x32_bf16 v[4:7], v[176:179], v[242:245], v[4:7]
	v_mfma_f32_16x16x32_bf16 v[0:3], v[186:189], v[242:245], v[0:3]
	s_barrier
	s_add_i32 s16, s16, 2
	s_add_u32 s78, s78, 0x100
	s_addc_u32 s79, s79, 0
	s_add_u32 s83, s83, 0x100
	s_addc_u32 s92, s92, 0
	s_cmpk_gt_u32 s16, 0x7d
	s_cbranch_scc0 .LBB0_934
	s_and_b64 vcc, exec, s[8:9]
	s_cbranch_vccz .LBB0_937
	s_barrier
